# GEMM epilogue loads hoisted three (P5a) / two (P6) batches ahead instead of one
# speedup vs baseline: 1.0024x; 1.0024x over previous
; DEVINL float bflo(unsigned u) { return __uint_as_float(u << 16); }
; DEVINL float bfhi(unsigned u) { return __uint_as_float(u & 0xffff0000u); }
; DEVINL float sigm(float x) { return 1.f / (1.f + __expf(-x)); }
; template <int EPI, bool GATHER>
; DEVINL void gemm_tile(const Params& p, const u16* __restrict__ A, int lda, const int* __restrict__ rowidx,
;                       const u16* __restrict__ Bt, int ldb, int K, int brow, int bcol, int orow, int ocol) {
;     ...
;     for (int m = 0; m < 4; ++m) {
;       const int rA = row0 + ai * HALF + m * 16 + (odd ? 2 : 0);
;     ...
;             const unsigned row = (unsigned)(rA + k);
;             if (EPI == EPI_HID) {
;               *(unsigned*)(ws + O_HID + (row * 1024u + (unsigned)(colp + cc)) * 2u) = pk2(lo[k], hi[k]);
;             } else if (EPI == EPI_COLS) {
;               *(unsigned*)(ws + O_COLS + (row * (unsigned)NCP + (unsigned)(colp + cc)) * 2u) = pk2(lo[k], hi[k]);
;             } else if (EPI == EPI_MOE2) {
;               *(unsigned*)(ws + O_EO + (row * 2048u + (unsigned)(colp + cc)) * 2u) = pk2(gate[k] * lo[k], gate[k] * hi[k]);
;             } else if (EPI == EPI_M1) {
;               const unsigned g2 = *(const unsigned*)(ws + O_COLS + (row * (unsigned)NCP + (unsigned)(C_GG + colp + cc)) * 2u);
;               *(unsigned*)(ws + O_M1 + (row * 2048u + (unsigned)(colp + cc)) * 2u) = pk2(sigm(bflo(g2)) * lo[k], sigm(bfhi(g2)) * hi[k]);
.LBB0_609:
	s_or_b64 exec, exec, s[6:7]
	v_and_b32_e32 v182, 1, v141
	v_or_b32_e32 v183, s0, v143
	v_sub_u32_e32 v183, v183, v182
	v_add_u32_e32 v184, s55, v145
	v_lshlrev_b32_e32 v185, 2, v144
	v_lshl_add_u32 v186, v142, 5, v183
	v_lshlrev_b32_e32 v183, 1, v182
	v_or3_b32 v183, v184, v183, v185
	v_add_u32_e32 v185, 0x1960, v186
	v_mul_lo_u32 v187, v183, s49
	v_add_lshl_u32 v184, v187, v185, 1
	global_load_dword v150, v184, s[8:9]
	v_add_u32_e32 v182, 0x2a00, v187
	v_add_lshl_u32 v188, v182, v185, 1
	global_load_dword v151, v188, s[8:9]
	v_add_u32_e32 v222, 0x1970, v186
	v_add_lshl_u32 v223, v187, v222, 1
	global_load_dword v152, v223, s[8:9]
	v_add_lshl_u32 v223, v182, v222, 1
	global_load_dword v153, v223, s[8:9]
	v_add_u32_e32 v224, 0x19e0, v186
	v_add_lshl_u32 v225, v187, v224, 1
	global_load_dword v154, v225, s[8:9]
	v_add_lshl_u32 v225, v182, v224, 1
	global_load_dword v155, v225, s[8:9]
	v_add_u32_e32 v226, 0x19f0, v186
	v_add_lshl_u32 v227, v187, v226, 1
	global_load_dword v156, v227, s[8:9]
	v_add_lshl_u32 v227, v182, v226, 1
	global_load_dword v157, v227, s[8:9]
	v_and_b32_e32 v182, 1, v141
	v_or_b32_e32 v183, s0, v143
	v_sub_u32_e32 v183, v183, v182
	v_add_u32_e32 v184, s55, v145
	v_lshlrev_b32_e32 v185, 2, v144
	v_lshl_add_u32 v186, v142, 5, v183
	v_lshlrev_b32_e32 v183, 1, v182
	v_or3_b32 v183, v184, v183, v185
	v_add_u32_e32 v185, 0x1960, v186
	v_add_u32_e32 v187, 0x1970, v186
	v_add_u32_e32 v188, 0x19e0, v186
	v_add_u32_e32 v222, 0x19f0, v186
	v_or_b32_e32 v223, 16, v183
	v_mul_lo_u32 v224, v223, s49
	v_add_lshl_u32 v225, v224, v185, 1
	global_load_dword v166, v225, s[8:9]
	v_add_u32_e32 v226, 0x2a00, v224
	v_add_lshl_u32 v227, v226, v185, 1
	global_load_dword v167, v227, s[8:9]
	v_add_lshl_u32 v228, v224, v187, 1
	global_load_dword v168, v228, s[8:9]
	v_add_lshl_u32 v228, v226, v187, 1
	global_load_dword v169, v228, s[8:9]
	v_add_lshl_u32 v229, v224, v188, 1
	global_load_dword v170, v229, s[8:9]
	v_add_lshl_u32 v229, v226, v188, 1
	global_load_dword v171, v229, s[8:9]
	v_add_lshl_u32 v230, v224, v222, 1
	global_load_dword v172, v230, s[8:9]
	v_add_lshl_u32 v230, v226, v222, 1
	global_load_dword v173, v230, s[8:9]
	v_and_b32_e32 v182, 1, v141
	v_or_b32_e32 v183, s0, v143
	v_sub_u32_e32 v183, v183, v182
	v_add_u32_e32 v184, s55, v145
	v_lshlrev_b32_e32 v185, 2, v144
	v_lshl_add_u32 v186, v142, 5, v183
	v_lshlrev_b32_e32 v183, 1, v182
	v_or3_b32 v183, v184, v183, v185
	v_add_u32_e32 v185, 0x1960, v186
	v_add_u32_e32 v187, 0x1970, v186
	v_add_u32_e32 v188, 0x19e0, v186
	v_add_u32_e32 v222, 0x19f0, v186
	v_or_b32_e32 v223, 16, v183
	v_mul_lo_u32 v224, v223, s49
	v_add_u32_e32 v225, 0x2a000, v224
	v_add_lshl_u32 v226, v225, v185, 1
	global_load_dword v190, v226, s[8:9]
	v_add_u32_e32 v227, 0x2ca00, v224
	v_add_lshl_u32 v228, v227, v185, 1
	global_load_dword v191, v228, s[8:9]
	v_add_lshl_u32 v229, v225, v187, 1
	global_load_dword v192, v229, s[8:9]
	v_add_lshl_u32 v230, v227, v187, 1
	global_load_dword v193, v230, s[8:9]
	v_add_lshl_u32 v231, v225, v188, 1
	global_load_dword v194, v231, s[8:9]
	v_add_lshl_u32 v232, v227, v188, 1
	global_load_dword v195, v232, s[8:9]
	v_add_lshl_u32 v233, v225, v222, 1
	global_load_dword v196, v233, s[8:9]
	v_add_lshl_u32 v234, v227, v222, 1
	global_load_dword v197, v234, s[8:9]
	v_and_b32_e32 v182, 1, v141
	v_or_b32_e32 v183, s0, v143
	v_sub_u32_e32 v183, v183, v182
	v_add_u32_e32 v184, s55, v145
	v_lshlrev_b32_e32 v185, 2, v144
	v_lshl_add_u32 v186, v142, 5, v183
	v_lshlrev_b32_e32 v183, 1, v182
	v_or3_b32 v183, v184, v183, v185
	v_add_u32_e32 v185, 0x1960, v186
	v_add_u32_e32 v187, 0x1970, v186
	v_add_u32_e32 v188, 0x19e0, v186
	v_add_u32_e32 v222, 0x19f0, v186
	v_or_b32_e32 v223, 16, v183
	v_mul_lo_u32 v224, v223, s49
	v_add_u32_e32 v225, 0x54000, v224
	v_add_lshl_u32 v226, v225, v185, 1
	global_load_dword v206, v226, s[8:9]
	v_add_u32_e32 v227, 0x56a00, v224
	v_add_lshl_u32 v228, v227, v185, 1
	global_load_dword v207, v228, s[8:9]
	v_add_lshl_u32 v229, v225, v187, 1
	global_load_dword v208, v229, s[8:9]
	v_add_lshl_u32 v230, v227, v187, 1
	global_load_dword v209, v230, s[8:9]
	v_add_lshl_u32 v231, v225, v188, 1
	global_load_dword v210, v231, s[8:9]
	v_add_lshl_u32 v232, v227, v188, 1
	global_load_dword v211, v232, s[8:9]
	v_add_lshl_u32 v233, v225, v222, 1
	global_load_dword v212, v233, s[8:9]
	v_add_lshl_u32 v234, v227, v222, 1
	global_load_dword v213, v234, s[8:9]
	v_and_b32_e32 v131, 1, v141
	v_or_b32_e32 v130, s0, v143
	v_sub_u32_e32 v130, v130, v131
	v_add_u32_e32 v128, s55, v145
	v_lshlrev_b32_e32 v129, 2, v144
	v_lshl_add_u32 v132, v142, 5, v130
	v_lshlrev_b32_e32 v130, 1, v131
	v_or3_b32 v130, v128, v130, v129
	v_add_u32_e32 v129, 0x1960, v132
	v_mul_lo_u32 v133, v130, s49
	v_add_lshl_u32 v128, v133, v129, 1
	s_nop 0
	v_cmp_eq_u32_e64 s[6:7], 0, v131
	s_waitcnt vmcnt(31)
; DEVINL float bflo(unsigned u) { return __uint_as_float(u << 16); }
; DEVINL float bfhi(unsigned u) { return __uint_as_float(u & 0xffff0000u); }
; DEVINL float sigm(float x) { return 1.f / (1.f + __expf(-x)); }
; template <int EPI, bool GATHER>
; DEVINL void gemm_tile(const Params& p, const u16* __restrict__ A, int lda, const int* __restrict__ rowidx,
;                       const u16* __restrict__ Bt, int ldb, int K, int brow, int bcol, int orow, int ocol) {
;     ...
;       const int rA = row0 + ai * HALF + m * 16 + (odd ? 2 : 0);
;       float gate[2] = {0.f, 0.f};
;       if (EPI == EPI_MOE2) { gate[0] = ((const float*)(ws + O_SELG))[rA]; gate[1] = ((const float*)(ws + O_SELG))[rA + 1]; }
; #pragma unroll
;       for (int bj = 0; bj < (EPI == EPI_HID ? 1 : 2); ++bj)
; #pragma unroll
;         for (int n = 0; n < 2; ++n) {
;           const int cc = bj * HALF + n * 16;
;           f32x4 v = acc[ai][bj][m][n];
;           if (EPI == EPI_HID) {
; #pragma unroll
;             for (int j = 0; j < 4; ++j) { const float a1 = acc[ai][0][m][n][j], a3 = acc[ai][1][m][n][j]; v[j] = a1 * sigm(a1) * a3; }
;           }
;           float lo[2], hi[2];
;           xchg_pairs(v, odd, lo, hi);
; #pragma unroll
;           for (int k = 0; k < 2; ++k) {
;             const unsigned row = (unsigned)(rA + k);
;             if (EPI == EPI_HID) {
;               *(unsigned*)(ws + O_HID + (row * 1024u + (unsigned)(colp + cc)) * 2u) = pk2(lo[k], hi[k]);
;             } else if (EPI == EPI_COLS) {
;               *(unsigned*)(ws + O_COLS + (row * (unsigned)NCP + (unsigned)(colp + cc)) * 2u) = pk2(lo[k], hi[k]);
;             } else if (EPI == EPI_MOE2) {
;               *(unsigned*)(ws + O_EO + (row * 2048u + (unsigned)(colp + cc)) * 2u) = pk2(gate[k] * lo[k], gate[k] * hi[k]);
;             } else if (EPI == EPI_M1) {
;               const unsigned g2 = *(const unsigned*)(ws + O_COLS + (row * (unsigned)NCP + (unsigned)(C_GG + colp + cc)) * 2u);
;               *(unsigned*)(ws + O_M1 + (row * 2048u + (unsigned)(colp + cc)) * 2u) = pk2(sigm(bflo(g2)) * lo[k], sigm(bfhi(g2)) * hi[k]);
	v_lshlrev_b32_e32 v131, 16, v150
	v_and_b32_e32 v134, 0xffff0000, v150
	v_mul_f32_e32 v131, 0xbfb8aa3b, v131
	v_mul_f32_e32 v134, 0xbfb8aa3b, v134
	v_exp_f32_e32 v137, v131
	v_exp_f32_e32 v134, v134
	v_cndmask_b32_e64 v128, v124, v126, s[6:7]
	v_add_u32_e32 v131, 0x2a00, v133
	v_add_f32_e32 v137, 1.0, v137
	v_add_f32_e32 v134, 1.0, v134
	v_div_scale_f32 v139, s[0:1], v137, v137, 1.0
	v_div_scale_f32 v142, s[0:1], v134, v134, 1.0
	v_rcp_f32_e32 v143, v139
	v_rcp_f32_e32 v144, v142
	v_div_scale_f32 v141, vcc, 1.0, v137, 1.0
	v_fma_f32 v146, -v139, v143, 1.0
	v_fma_f32 v147, -v142, v144, 1.0
	v_fmac_f32_e32 v143, v146, v143
	v_div_scale_f32 v145, s[0:1], 1.0, v134, 1.0
	v_fmac_f32_e32 v144, v147, v144
	v_mul_f32_e32 v146, v141, v143
	v_mul_f32_e32 v147, v145, v144
	v_fma_f32 v148, -v139, v146, v141
	v_fma_f32 v149, -v142, v147, v145
	v_fmac_f32_e32 v146, v148, v143
	v_fmac_f32_e32 v147, v149, v144
	v_fma_f32 v139, -v139, v146, v141
	v_fma_f32 v141, -v142, v147, v145
	v_div_fmas_f32 v139, v139, v143, v146
	s_mov_b64 vcc, s[0:1]
	v_mov_b32_dpp v128, v128 quad_perm:[1,0,3,2] row_mask:0xf bank_mask:0xf bound_ctrl:1
	v_div_fixup_f32 v137, v139, v137, 1.0
	v_div_fmas_f32 v139, v141, v144, v147
	v_cndmask_b32_e64 v135, v128, v124, s[6:7]
	v_cndmask_b32_e64 v126, v126, v128, s[6:7]
	v_div_fixup_f32 v134, v139, v134, 1.0
	v_lshlrev_b32_e32 v124, 1, v132
	v_lshlrev_b32_e32 v128, 12, v130
	v_mul_f32_e32 v135, v135, v137
	v_mul_f32_e32 v126, v126, v134
	v_add_u32_e32 v136, v128, v124
	v_cvt_pk_bf16_f32 v126, v135, v126
	v_add_lshl_u32 v138, v131, v129, 1
	global_store_dword v136, v126, s[10:11]
	s_nop 0
	v_cndmask_b32_e64 v126, v125, v127, s[6:7]
	s_nop 1
	v_mov_b32_dpp v135, v126 quad_perm:[1,0,3,2] row_mask:0xf bank_mask:0xf bound_ctrl:1
	v_cndmask_b32_e64 v136, v135, v125, s[6:7]
	v_cndmask_b32_e64 v127, v127, v135, s[6:7]
	v_or_b32_e32 v125, 0x1000, v128
	v_add_u32_e32 v126, 0x1970, v132
	v_add_u32_e32 v138, v125, v124
	v_add_lshl_u32 v137, v133, v126, 1
	s_waitcnt vmcnt(31)
	v_lshlrev_b32_e32 v135, 16, v151
	v_and_b32_e32 v134, 0xffff0000, v151
	v_mul_f32_e32 v135, 0xbfb8aa3b, v135
	v_mul_f32_e32 v134, 0xbfb8aa3b, v134
	v_exp_f32_e32 v135, v135
	v_exp_f32_e32 v134, v134
	v_add_f32_e32 v135, 1.0, v135
	v_add_f32_e32 v134, 1.0, v134
	v_div_scale_f32 v139, s[0:1], v135, v135, 1.0
	v_div_scale_f32 v142, s[0:1], v134, v134, 1.0
	v_rcp_f32_e32 v143, v139
	v_rcp_f32_e32 v144, v142
	v_div_scale_f32 v141, vcc, 1.0, v135, 1.0
	v_fma_f32 v146, -v139, v143, 1.0
	v_fma_f32 v147, -v142, v144, 1.0
	v_fmac_f32_e32 v143, v146, v143
	v_div_scale_f32 v145, s[0:1], 1.0, v134, 1.0
	v_fmac_f32_e32 v144, v147, v144
	v_mul_f32_e32 v146, v141, v143
	v_mul_f32_e32 v147, v145, v144
	v_fma_f32 v148, -v139, v146, v141
	v_fma_f32 v149, -v142, v147, v145
	v_fmac_f32_e32 v146, v148, v143
	v_fmac_f32_e32 v147, v149, v144
	v_fma_f32 v139, -v139, v146, v141
	v_fma_f32 v141, -v142, v147, v145
	v_div_fmas_f32 v139, v139, v143, v146
	s_mov_b64 vcc, s[0:1]
	v_div_fixup_f32 v135, v139, v135, 1.0
	v_div_fmas_f32 v139, v141, v144, v147
	v_div_fixup_f32 v134, v139, v134, 1.0
	v_mul_f32_e32 v135, v136, v135
	v_mul_f32_e32 v127, v127, v134
	v_cvt_pk_bf16_f32 v127, v135, v127
	global_store_dword v138, v127, s[10:11]
	s_nop 0
	v_cndmask_b32_e64 v134, v120, v122, s[6:7]
	v_add_lshl_u32 v137, v131, v126, 1
	s_nop 0
	v_mov_b32_dpp v134, v134 quad_perm:[1,0,3,2] row_mask:0xf bank_mask:0xf bound_ctrl:1
	v_cndmask_b32_e64 v135, v134, v120, s[6:7]
	v_cndmask_b32_e64 v122, v122, v134, s[6:7]
	v_add_u32_e32 v120, 32, v124
	v_add_u32_e32 v136, v128, v120
	s_waitcnt vmcnt(31)
	v_lshlrev_b32_e32 v134, 16, v152
	v_and_b32_e32 v127, 0xffff0000, v152
	v_mul_f32_e32 v134, 0xbfb8aa3b, v134
	v_mul_f32_e32 v127, 0xbfb8aa3b, v127
	v_exp_f32_e32 v134, v134
	v_exp_f32_e32 v127, v127
	v_add_f32_e32 v134, 1.0, v134
	v_add_f32_e32 v127, 1.0, v127
	v_div_scale_f32 v138, s[0:1], v134, v134, 1.0
	v_div_scale_f32 v141, s[0:1], v127, v127, 1.0
	v_rcp_f32_e32 v142, v138
	v_rcp_f32_e32 v143, v141
	v_div_scale_f32 v139, vcc, 1.0, v134, 1.0
	v_fma_f32 v145, -v138, v142, 1.0
	v_fma_f32 v146, -v141, v143, 1.0
	v_fmac_f32_e32 v142, v145, v142
	v_div_scale_f32 v144, s[0:1], 1.0, v127, 1.0
	v_fmac_f32_e32 v143, v146, v143
	v_mul_f32_e32 v145, v139, v142
	v_mul_f32_e32 v146, v144, v143
	v_fma_f32 v147, -v138, v145, v139
	v_fma_f32 v148, -v141, v146, v144
	v_fmac_f32_e32 v145, v147, v142
	v_fmac_f32_e32 v146, v148, v143
	v_fma_f32 v138, -v138, v145, v139
	v_fma_f32 v139, -v141, v146, v144
	v_div_fmas_f32 v138, v138, v142, v145
	s_mov_b64 vcc, s[0:1]
	v_div_fixup_f32 v134, v138, v134, 1.0
	v_div_fmas_f32 v138, v139, v143, v146
	v_div_fixup_f32 v127, v138, v127, 1.0
	v_mul_f32_e32 v134, v135, v134
	v_mul_f32_e32 v122, v122, v127
	v_cvt_pk_bf16_f32 v122, v134, v122
	global_store_dword v136, v122, s[10:11]
	s_nop 0
	v_cndmask_b32_e64 v122, v121, v123, s[6:7]
	v_add_u32_e32 v136, v125, v120
	s_nop 0
	v_mov_b32_dpp v134, v122 quad_perm:[1,0,3,2] row_mask:0xf bank_mask:0xf bound_ctrl:1
	v_cndmask_b32_e64 v121, v134, v121, s[6:7]
	v_cndmask_b32_e64 v123, v123, v134, s[6:7]
	v_add_u32_e32 v122, 0x19e0, v132
	v_add_lshl_u32 v135, v133, v122, 1
	s_waitcnt vmcnt(31)
; DEVINL float bflo(unsigned u) { return __uint_as_float(u << 16); }
; DEVINL float bfhi(unsigned u) { return __uint_as_float(u & 0xffff0000u); }
; DEVINL float sigm(float x) { return 1.f / (1.f + __expf(-x)); }
; template <int EPI, bool GATHER>
; DEVINL void gemm_tile(const Params& p, const u16* __restrict__ A, int lda, const int* __restrict__ rowidx,
;                       const u16* __restrict__ Bt, int ldb, int K, int brow, int bcol, int orow, int ocol) {
;     ...
;       const int rA = row0 + ai * HALF + m * 16 + (odd ? 2 : 0);
;       float gate[2] = {0.f, 0.f};
;       if (EPI == EPI_MOE2) { gate[0] = ((const float*)(ws + O_SELG))[rA]; gate[1] = ((const float*)(ws + O_SELG))[rA + 1]; }
; #pragma unroll
;       for (int bj = 0; bj < (EPI == EPI_HID ? 1 : 2); ++bj)
; #pragma unroll
;         for (int n = 0; n < 2; ++n) {
;           const int cc = bj * HALF + n * 16;
;           f32x4 v = acc[ai][bj][m][n];
;           if (EPI == EPI_HID) {
; #pragma unroll
;             for (int j = 0; j < 4; ++j) { const float a1 = acc[ai][0][m][n][j], a3 = acc[ai][1][m][n][j]; v[j] = a1 * sigm(a1) * a3; }
;           }
;           float lo[2], hi[2];
;           xchg_pairs(v, odd, lo, hi);
; #pragma unroll
;           for (int k = 0; k < 2; ++k) {
;             const unsigned row = (unsigned)(rA + k);
;             if (EPI == EPI_HID) {
;               *(unsigned*)(ws + O_HID + (row * 1024u + (unsigned)(colp + cc)) * 2u) = pk2(lo[k], hi[k]);
;             } else if (EPI == EPI_COLS) {
;               *(unsigned*)(ws + O_COLS + (row * (unsigned)NCP + (unsigned)(colp + cc)) * 2u) = pk2(lo[k], hi[k]);
;             } else if (EPI == EPI_MOE2) {
;               *(unsigned*)(ws + O_EO + (row * 2048u + (unsigned)(colp + cc)) * 2u) = pk2(gate[k] * lo[k], gate[k] * hi[k]);
;             } else if (EPI == EPI_M1) {
;               const unsigned g2 = *(const unsigned*)(ws + O_COLS + (row * (unsigned)NCP + (unsigned)(C_GG + colp + cc)) * 2u);
;               *(unsigned*)(ws + O_M1 + (row * 2048u + (unsigned)(colp + cc)) * 2u) = pk2(sigm(bflo(g2)) * lo[k], sigm(bfhi(g2)) * hi[k]);
	v_lshlrev_b32_e32 v134, 16, v153
	v_and_b32_e32 v127, 0xffff0000, v153
	v_mul_f32_e32 v134, 0xbfb8aa3b, v134
	v_mul_f32_e32 v127, 0xbfb8aa3b, v127
	v_exp_f32_e32 v134, v134
	v_exp_f32_e32 v127, v127
	v_add_f32_e32 v134, 1.0, v134
	v_add_f32_e32 v127, 1.0, v127
	v_div_scale_f32 v137, s[0:1], v134, v134, 1.0
	v_div_scale_f32 v139, s[0:1], v127, v127, 1.0
	v_rcp_f32_e32 v141, v137
	v_rcp_f32_e32 v142, v139
	v_div_scale_f32 v138, vcc, 1.0, v134, 1.0
	v_fma_f32 v144, -v137, v141, 1.0
	v_fma_f32 v145, -v139, v142, 1.0
	v_fmac_f32_e32 v141, v144, v141
	v_div_scale_f32 v143, s[0:1], 1.0, v127, 1.0
	v_fmac_f32_e32 v142, v145, v142
	v_mul_f32_e32 v144, v138, v141
	v_mul_f32_e32 v145, v143, v142
	v_fma_f32 v146, -v137, v144, v138
	v_fma_f32 v147, -v139, v145, v143
	v_fmac_f32_e32 v144, v146, v141
	v_fmac_f32_e32 v145, v147, v142
	v_fma_f32 v137, -v137, v144, v138
	v_fma_f32 v138, -v139, v145, v143
	v_div_fmas_f32 v137, v137, v141, v144
	s_mov_b64 vcc, s[0:1]
	v_div_fixup_f32 v134, v137, v134, 1.0
	v_div_fmas_f32 v137, v138, v142, v145
	v_div_fixup_f32 v127, v137, v127, 1.0
	v_mul_f32_e32 v121, v121, v134
	v_mul_f32_e32 v123, v123, v127
	v_cvt_pk_bf16_f32 v121, v121, v123
	global_store_dword v136, v121, s[10:11]
	s_nop 0
	v_cndmask_b32_e64 v123, v116, v118, s[6:7]
	v_add_lshl_u32 v135, v131, v122, 1
	s_waitcnt vmcnt(31)
	v_lshlrev_b32_e32 v127, 16, v154
	v_and_b32_e32 v121, 0xffff0000, v154
	v_mul_f32_e32 v127, 0xbfb8aa3b, v127
	v_mul_f32_e32 v121, 0xbfb8aa3b, v121
	v_exp_f32_e32 v127, v127
	v_exp_f32_e32 v121, v121
	v_mov_b32_dpp v123, v123 quad_perm:[1,0,3,2] row_mask:0xf bank_mask:0xf bound_ctrl:1
	v_cndmask_b32_e64 v116, v123, v116, s[6:7]
	v_add_f32_e32 v127, 1.0, v127
	v_add_f32_e32 v121, 1.0, v121
	v_div_scale_f32 v136, s[0:1], v127, v127, 1.0
	v_div_scale_f32 v138, s[0:1], v121, v121, 1.0
	v_rcp_f32_e32 v139, v136
	v_rcp_f32_e32 v141, v138
	v_div_scale_f32 v137, vcc, 1.0, v127, 1.0
	v_fma_f32 v143, -v136, v139, 1.0
	v_fma_f32 v144, -v138, v141, 1.0
	v_fmac_f32_e32 v139, v143, v139
	v_div_scale_f32 v142, s[0:1], 1.0, v121, 1.0
	v_fmac_f32_e32 v141, v144, v141
	v_mul_f32_e32 v143, v137, v139
	v_mul_f32_e32 v144, v142, v141
	v_fma_f32 v145, -v136, v143, v137
	v_fma_f32 v146, -v138, v144, v142
	v_fmac_f32_e32 v143, v145, v139
	v_fmac_f32_e32 v144, v146, v141
	v_fma_f32 v136, -v136, v143, v137
	v_fma_f32 v137, -v138, v144, v142
	v_div_fmas_f32 v136, v136, v139, v143
	s_mov_b64 vcc, s[0:1]
	v_div_fixup_f32 v127, v136, v127, 1.0
	v_div_fmas_f32 v136, v137, v141, v144
	v_cndmask_b32_e64 v123, v118, v123, s[6:7]
	v_div_fixup_f32 v121, v136, v121, 1.0
	v_add_u32_e32 v118, 0x100, v124
	v_mul_f32_e32 v116, v116, v127
	v_mul_f32_e32 v121, v123, v121
	v_add_u32_e32 v134, v128, v118
	v_cvt_pk_bf16_f32 v116, v116, v121
	global_store_dword v134, v116, s[10:11]
	s_nop 0
	v_cndmask_b32_e64 v123, v117, v119, s[6:7]
	v_add_u32_e32 v116, 0x19f0, v132
	v_add_lshl_u32 v127, v133, v116, 1
	v_mov_b32_dpp v123, v123 quad_perm:[1,0,3,2] row_mask:0xf bank_mask:0xf bound_ctrl:1
	v_cndmask_b32_e64 v117, v123, v117, s[6:7]
	v_cndmask_b32_e64 v119, v119, v123, s[6:7]
	v_add_u32_e32 v132, v125, v118
	s_waitcnt vmcnt(31)
	v_lshlrev_b32_e32 v123, 16, v155
	v_and_b32_e32 v121, 0xffff0000, v155
	v_mul_f32_e32 v123, 0xbfb8aa3b, v123
	v_mul_f32_e32 v121, 0xbfb8aa3b, v121
	v_exp_f32_e32 v123, v123
	v_exp_f32_e32 v121, v121
	v_add_f32_e32 v123, 1.0, v123
	v_add_f32_e32 v121, 1.0, v121
	v_div_scale_f32 v133, s[0:1], v123, v123, 1.0
	v_div_scale_f32 v135, s[0:1], v121, v121, 1.0
	v_rcp_f32_e32 v136, v133
	v_rcp_f32_e32 v137, v135
	v_div_scale_f32 v134, vcc, 1.0, v123, 1.0
	v_fma_f32 v139, -v133, v136, 1.0
	v_fma_f32 v141, -v135, v137, 1.0
	v_fmac_f32_e32 v136, v139, v136
	v_div_scale_f32 v138, s[0:1], 1.0, v121, 1.0
	v_fmac_f32_e32 v137, v141, v137
	v_mul_f32_e32 v139, v134, v136
	v_mul_f32_e32 v141, v138, v137
	v_fma_f32 v142, -v133, v139, v134
	v_fma_f32 v143, -v135, v141, v138
	v_fmac_f32_e32 v139, v142, v136
	v_fmac_f32_e32 v141, v143, v137
	v_fma_f32 v133, -v133, v139, v134
	v_fma_f32 v134, -v135, v141, v138
	v_div_fmas_f32 v133, v133, v136, v139
	s_mov_b64 vcc, s[0:1]
	v_div_fixup_f32 v123, v133, v123, 1.0
	v_div_fmas_f32 v133, v134, v137, v141
	v_div_fixup_f32 v121, v133, v121, 1.0
	v_mul_f32_e32 v117, v117, v123
	v_mul_f32_e32 v119, v119, v121
	v_cvt_pk_bf16_f32 v117, v117, v119
	global_store_dword v132, v117, s[10:11]
	s_nop 0
	v_cndmask_b32_e64 v119, v112, v114, s[6:7]
	v_add_lshl_u32 v127, v131, v116, 1
	s_nop 0
	v_mov_b32_dpp v119, v119 quad_perm:[1,0,3,2] row_mask:0xf bank_mask:0xf bound_ctrl:1
	v_cndmask_b32_e64 v121, v119, v112, s[6:7]
	v_cndmask_b32_e64 v114, v114, v119, s[6:7]
	v_add_u32_e32 v112, 0x120, v124
	v_add_u32_e32 v123, v128, v112
	s_waitcnt vmcnt(31)
	v_lshlrev_b32_e32 v119, 16, v156
	v_and_b32_e32 v117, 0xffff0000, v156
	v_mul_f32_e32 v119, 0xbfb8aa3b, v119
	v_mul_f32_e32 v117, 0xbfb8aa3b, v117
	v_exp_f32_e32 v119, v119
	v_exp_f32_e32 v117, v117
	v_add_f32_e32 v119, 1.0, v119
	v_add_f32_e32 v117, 1.0, v117
	v_div_scale_f32 v131, s[0:1], v119, v119, 1.0
	v_div_scale_f32 v133, s[0:1], v117, v117, 1.0
	v_rcp_f32_e32 v134, v131
	v_rcp_f32_e32 v135, v133
	v_div_scale_f32 v132, vcc, 1.0, v119, 1.0
	v_fma_f32 v137, -v131, v134, 1.0
	v_fma_f32 v138, -v133, v135, 1.0
	v_fmac_f32_e32 v134, v137, v134
	v_div_scale_f32 v136, s[0:1], 1.0, v117, 1.0
	v_fmac_f32_e32 v135, v138, v135
	v_mul_f32_e32 v137, v132, v134
	v_mul_f32_e32 v138, v136, v135
	v_fma_f32 v139, -v131, v137, v132
	v_fma_f32 v141, -v133, v138, v136
	v_fmac_f32_e32 v137, v139, v134
	v_fmac_f32_e32 v138, v141, v135
	v_fma_f32 v131, -v131, v137, v132
	v_fma_f32 v132, -v133, v138, v136
	v_div_fmas_f32 v131, v131, v134, v137
	s_mov_b64 vcc, s[0:1]
	v_div_fixup_f32 v119, v131, v119, 1.0
	v_div_fmas_f32 v131, v132, v135, v138
	v_div_fixup_f32 v117, v131, v117, 1.0
	v_mul_f32_e32 v119, v121, v119
	v_mul_f32_e32 v114, v114, v117
	v_cvt_pk_bf16_f32 v114, v119, v114
	global_store_dword v123, v114, s[10:11]
	s_nop 0
	v_cndmask_b32_e64 v117, v113, v115, s[6:7]
	s_waitcnt vmcnt(31)
; DEVINL float bflo(unsigned u) { return __uint_as_float(u << 16); }
; DEVINL float bfhi(unsigned u) { return __uint_as_float(u & 0xffff0000u); }
; DEVINL float sigm(float x) { return 1.f / (1.f + __expf(-x)); }
; template <int EPI, bool GATHER>
; DEVINL void gemm_tile(const Params& p, const u16* __restrict__ A, int lda, const int* __restrict__ rowidx,
;                       const u16* __restrict__ Bt, int ldb, int K, int brow, int bcol, int orow, int ocol) {
;     ...
;       const int rA = row0 + ai * HALF + m * 16 + (odd ? 2 : 0);
;       float gate[2] = {0.f, 0.f};
;       if (EPI == EPI_MOE2) { gate[0] = ((const float*)(ws + O_SELG))[rA]; gate[1] = ((const float*)(ws + O_SELG))[rA + 1]; }
; #pragma unroll
;       for (int bj = 0; bj < (EPI == EPI_HID ? 1 : 2); ++bj)
; #pragma unroll
;         for (int n = 0; n < 2; ++n) {
;           const int cc = bj * HALF + n * 16;
;           f32x4 v = acc[ai][bj][m][n];
;           if (EPI == EPI_HID) {
; #pragma unroll
;             for (int j = 0; j < 4; ++j) { const float a1 = acc[ai][0][m][n][j], a3 = acc[ai][1][m][n][j]; v[j] = a1 * sigm(a1) * a3; }
;           }
;           float lo[2], hi[2];
;           xchg_pairs(v, odd, lo, hi);
; #pragma unroll
;           for (int k = 0; k < 2; ++k) {
;             const unsigned row = (unsigned)(rA + k);
;             if (EPI == EPI_HID) {
;               *(unsigned*)(ws + O_HID + (row * 1024u + (unsigned)(colp + cc)) * 2u) = pk2(lo[k], hi[k]);
;             } else if (EPI == EPI_COLS) {
;               *(unsigned*)(ws + O_COLS + (row * (unsigned)NCP + (unsigned)(colp + cc)) * 2u) = pk2(lo[k], hi[k]);
;             } else if (EPI == EPI_MOE2) {
;               *(unsigned*)(ws + O_EO + (row * 2048u + (unsigned)(colp + cc)) * 2u) = pk2(gate[k] * lo[k], gate[k] * hi[k]);
;             } else if (EPI == EPI_M1) {
;               const unsigned g2 = *(const unsigned*)(ws + O_COLS + (row * (unsigned)NCP + (unsigned)(C_GG + colp + cc)) * 2u);
;               *(unsigned*)(ws + O_M1 + (row * 2048u + (unsigned)(colp + cc)) * 2u) = pk2(sigm(bflo(g2)) * lo[k], sigm(bfhi(g2)) * hi[k]);
	v_lshlrev_b32_e32 v119, 16, v157
	v_and_b32_e32 v114, 0xffff0000, v157
	v_mul_f32_e32 v119, 0xbfb8aa3b, v119
	v_mul_f32_e32 v114, 0xbfb8aa3b, v114
	v_exp_f32_e32 v119, v119
	v_exp_f32_e32 v114, v114
	v_mov_b32_dpp v117, v117 quad_perm:[1,0,3,2] row_mask:0xf bank_mask:0xf bound_ctrl:1
	v_cndmask_b32_e64 v113, v117, v113, s[6:7]
	v_cndmask_b32_e64 v115, v115, v117, s[6:7]
	v_add_f32_e32 v117, 1.0, v119
	v_add_f32_e32 v114, 1.0, v114
	v_div_scale_f32 v119, s[0:1], v117, v117, 1.0
	v_div_scale_f32 v123, s[0:1], v114, v114, 1.0
	v_rcp_f32_e32 v127, v119
	v_rcp_f32_e32 v131, v123
	v_div_scale_f32 v121, vcc, 1.0, v117, 1.0
	v_fma_f32 v133, -v119, v127, 1.0
	v_fma_f32 v134, -v123, v131, 1.0
	v_fmac_f32_e32 v127, v133, v127
	v_div_scale_f32 v132, s[0:1], 1.0, v114, 1.0
	v_fmac_f32_e32 v131, v134, v131
	v_mul_f32_e32 v133, v121, v127
	v_mul_f32_e32 v134, v132, v131
	v_fma_f32 v135, -v119, v133, v121
	v_fma_f32 v136, -v123, v134, v132
	v_fmac_f32_e32 v133, v135, v127
	v_fmac_f32_e32 v134, v136, v131
	v_fma_f32 v119, -v119, v133, v121
	v_fma_f32 v121, -v123, v134, v132
	v_div_fmas_f32 v119, v119, v127, v133
	s_mov_b64 vcc, s[0:1]
	v_div_fixup_f32 v117, v119, v117, 1.0
	v_div_fmas_f32 v119, v121, v131, v134
	v_div_fixup_f32 v114, v119, v114, 1.0
	v_mul_f32_e32 v113, v113, v117
	v_mul_f32_e32 v114, v115, v114
	v_cvt_pk_bf16_f32 v113, v113, v114
	v_add_u32_e32 v114, v125, v112
	global_store_dword v114, v113, s[10:11]
	v_or_b32_e32 v182, 16, v130
	v_mul_lo_u32 v183, v182, s49
	v_add_u32_e32 v184, 0x126000, v183
	v_add_lshl_u32 v185, v184, v129, 1
	global_load_dword v150, v185, s[8:9]
	v_add_u32_e32 v186, 0x128a00, v183
	v_add_lshl_u32 v187, v186, v129, 1
	global_load_dword v151, v187, s[8:9]
	v_add_lshl_u32 v188, v184, v126, 1
	global_load_dword v152, v188, s[8:9]
	v_add_lshl_u32 v222, v186, v126, 1
	global_load_dword v153, v222, s[8:9]
	v_add_lshl_u32 v223, v184, v122, 1
	global_load_dword v154, v223, s[8:9]
	v_add_lshl_u32 v224, v186, v122, 1
	global_load_dword v155, v224, s[8:9]
	v_add_lshl_u32 v225, v184, v116, 1
	global_load_dword v156, v225, s[8:9]
	v_add_lshl_u32 v226, v186, v116, 1
	global_load_dword v157, v226, s[8:9]
	v_or_b32_e32 v114, 16, v130
	v_mul_lo_u32 v113, v114, s49
	v_add_lshl_u32 v115, v113, v129, 1
	s_nop 0
	v_cndmask_b32_e64 v117, v108, v110, s[6:7]
	v_lshlrev_b32_e32 v114, 12, v114
	v_add_u32_e32 v119, v114, v124
	v_mov_b32_dpp v117, v117 quad_perm:[1,0,3,2] row_mask:0xf bank_mask:0xf bound_ctrl:1
	v_cndmask_b32_e64 v108, v117, v108, s[6:7]
	v_cndmask_b32_e64 v117, v110, v117, s[6:7]
	s_waitcnt vmcnt(39)
	v_lshlrev_b32_e32 v110, 16, v166
	v_and_b32_e32 v115, 0xffff0000, v166
	v_mul_f32_e32 v110, 0xbfb8aa3b, v110
	v_mul_f32_e32 v115, 0xbfb8aa3b, v115
	v_exp_f32_e32 v121, v110
	v_exp_f32_e32 v115, v115
	v_add_u32_e32 v110, 0x2a00, v113
	v_add_lshl_u32 v123, v110, v129, 1
	v_add_f32_e32 v121, 1.0, v121
	v_add_f32_e32 v115, 1.0, v115
	v_div_scale_f32 v125, s[0:1], v121, v121, 1.0
	v_div_scale_f32 v130, s[0:1], v115, v115, 1.0
	v_rcp_f32_e32 v131, v125
	v_rcp_f32_e32 v132, v130
	v_div_scale_f32 v127, vcc, 1.0, v121, 1.0
	v_fma_f32 v134, -v125, v131, 1.0
	v_fma_f32 v135, -v130, v132, 1.0
	v_fmac_f32_e32 v131, v134, v131
	v_div_scale_f32 v133, s[0:1], 1.0, v115, 1.0
	v_fmac_f32_e32 v132, v135, v132
	v_mul_f32_e32 v134, v127, v131
	v_mul_f32_e32 v135, v133, v132
	v_fma_f32 v136, -v125, v134, v127
	v_fma_f32 v137, -v130, v135, v133
	v_fmac_f32_e32 v134, v136, v131
	v_fmac_f32_e32 v135, v137, v132
	v_fma_f32 v125, -v125, v134, v127
	v_fma_f32 v127, -v130, v135, v133
	v_div_fmas_f32 v125, v125, v131, v134
	s_mov_b64 vcc, s[0:1]
	v_div_fixup_f32 v121, v125, v121, 1.0
	v_div_fmas_f32 v125, v127, v132, v135
	v_div_fixup_f32 v115, v125, v115, 1.0
	v_mul_f32_e32 v108, v108, v121
	v_mul_f32_e32 v115, v117, v115
	v_cvt_pk_bf16_f32 v108, v108, v115
	global_store_dword v119, v108, s[10:11]
	s_nop 0
	v_cndmask_b32_e64 v117, v109, v111, s[6:7]
	v_or_b32_e32 v108, 0x11000, v128
	v_add_u32_e32 v119, v108, v124
	v_mov_b32_dpp v117, v117 quad_perm:[1,0,3,2] row_mask:0xf bank_mask:0xf bound_ctrl:1
	v_cndmask_b32_e64 v109, v117, v109, s[6:7]
	v_cndmask_b32_e64 v111, v111, v117, s[6:7]
	v_add_lshl_u32 v117, v113, v126, 1
	s_waitcnt vmcnt(39)
	v_lshlrev_b32_e32 v121, 16, v167
	v_and_b32_e32 v115, 0xffff0000, v167
	v_mul_f32_e32 v121, 0xbfb8aa3b, v121
	v_mul_f32_e32 v115, 0xbfb8aa3b, v115
	v_exp_f32_e32 v121, v121
	v_exp_f32_e32 v115, v115
	v_add_f32_e32 v121, 1.0, v121
	v_add_f32_e32 v115, 1.0, v115
	v_div_scale_f32 v123, s[0:1], v121, v121, 1.0
	v_div_scale_f32 v127, s[0:1], v115, v115, 1.0
	v_rcp_f32_e32 v130, v123
	v_rcp_f32_e32 v131, v127
	v_div_scale_f32 v125, vcc, 1.0, v121, 1.0
	v_fma_f32 v133, -v123, v130, 1.0
	v_fma_f32 v134, -v127, v131, 1.0
	v_fmac_f32_e32 v130, v133, v130
	v_div_scale_f32 v132, s[0:1], 1.0, v115, 1.0
	v_fmac_f32_e32 v131, v134, v131
	v_mul_f32_e32 v133, v125, v130
	v_mul_f32_e32 v134, v132, v131
	v_fma_f32 v135, -v123, v133, v125
	v_fma_f32 v136, -v127, v134, v132
	v_fmac_f32_e32 v133, v135, v130
	v_fmac_f32_e32 v134, v136, v131
	v_fma_f32 v123, -v123, v133, v125
	v_fma_f32 v125, -v127, v134, v132
	v_div_fmas_f32 v123, v123, v130, v133
	s_mov_b64 vcc, s[0:1]
	v_div_fixup_f32 v121, v123, v121, 1.0
	v_div_fmas_f32 v123, v125, v131, v134
	v_div_fixup_f32 v115, v123, v115, 1.0
	v_mul_f32_e32 v109, v109, v121
	v_mul_f32_e32 v111, v111, v115
	v_cvt_pk_bf16_f32 v109, v109, v111
	global_store_dword v119, v109, s[10:11]
	s_nop 0
	v_cndmask_b32_e64 v111, v104, v106, s[6:7]
	v_add_u32_e32 v115, v114, v120
	v_add_lshl_u32 v117, v110, v126, 1
	v_mov_b32_dpp v111, v111 quad_perm:[1,0,3,2] row_mask:0xf bank_mask:0xf bound_ctrl:1
	v_cndmask_b32_e64 v104, v111, v104, s[6:7]
	v_cndmask_b32_e64 v106, v106, v111, s[6:7]
	s_waitcnt vmcnt(39)
; DEVINL float bflo(unsigned u) { return __uint_as_float(u << 16); }
; DEVINL float bfhi(unsigned u) { return __uint_as_float(u & 0xffff0000u); }
; DEVINL float sigm(float x) { return 1.f / (1.f + __expf(-x)); }
; template <int EPI, bool GATHER>
; DEVINL void gemm_tile(const Params& p, const u16* __restrict__ A, int lda, const int* __restrict__ rowidx,
;                       const u16* __restrict__ Bt, int ldb, int K, int brow, int bcol, int orow, int ocol) {
;     ...
;       const int rA = row0 + ai * HALF + m * 16 + (odd ? 2 : 0);
;       float gate[2] = {0.f, 0.f};
;       if (EPI == EPI_MOE2) { gate[0] = ((const float*)(ws + O_SELG))[rA]; gate[1] = ((const float*)(ws + O_SELG))[rA + 1]; }
; #pragma unroll
;       for (int bj = 0; bj < (EPI == EPI_HID ? 1 : 2); ++bj)
; #pragma unroll
;         for (int n = 0; n < 2; ++n) {
;           const int cc = bj * HALF + n * 16;
;           f32x4 v = acc[ai][bj][m][n];
;           if (EPI == EPI_HID) {
; #pragma unroll
;             for (int j = 0; j < 4; ++j) { const float a1 = acc[ai][0][m][n][j], a3 = acc[ai][1][m][n][j]; v[j] = a1 * sigm(a1) * a3; }
;           }
;           float lo[2], hi[2];
;           xchg_pairs(v, odd, lo, hi);
; #pragma unroll
;           for (int k = 0; k < 2; ++k) {
;             const unsigned row = (unsigned)(rA + k);
;             if (EPI == EPI_HID) {
;               *(unsigned*)(ws + O_HID + (row * 1024u + (unsigned)(colp + cc)) * 2u) = pk2(lo[k], hi[k]);
;             } else if (EPI == EPI_COLS) {
;               *(unsigned*)(ws + O_COLS + (row * (unsigned)NCP + (unsigned)(colp + cc)) * 2u) = pk2(lo[k], hi[k]);
;             } else if (EPI == EPI_MOE2) {
;               *(unsigned*)(ws + O_EO + (row * 2048u + (unsigned)(colp + cc)) * 2u) = pk2(gate[k] * lo[k], gate[k] * hi[k]);
;             } else if (EPI == EPI_M1) {
;               const unsigned g2 = *(const unsigned*)(ws + O_COLS + (row * (unsigned)NCP + (unsigned)(C_GG + colp + cc)) * 2u);
;               *(unsigned*)(ws + O_M1 + (row * 2048u + (unsigned)(colp + cc)) * 2u) = pk2(sigm(bflo(g2)) * lo[k], sigm(bfhi(g2)) * hi[k]);
	v_lshlrev_b32_e32 v111, 16, v168
	v_and_b32_e32 v109, 0xffff0000, v168
	v_mul_f32_e32 v111, 0xbfb8aa3b, v111
	v_mul_f32_e32 v109, 0xbfb8aa3b, v109
	v_exp_f32_e32 v111, v111
	v_exp_f32_e32 v109, v109
	v_add_f32_e32 v111, 1.0, v111
	v_add_f32_e32 v109, 1.0, v109
	v_div_scale_f32 v119, s[0:1], v111, v111, 1.0
	v_div_scale_f32 v123, s[0:1], v109, v109, 1.0
	v_rcp_f32_e32 v125, v119
	v_rcp_f32_e32 v127, v123
	v_div_scale_f32 v121, vcc, 1.0, v111, 1.0
	v_fma_f32 v131, -v119, v125, 1.0
	v_fma_f32 v132, -v123, v127, 1.0
	v_fmac_f32_e32 v125, v131, v125
	v_div_scale_f32 v130, s[0:1], 1.0, v109, 1.0
	v_fmac_f32_e32 v127, v132, v127
	v_mul_f32_e32 v131, v121, v125
	v_mul_f32_e32 v132, v130, v127
	v_fma_f32 v133, -v119, v131, v121
	v_fma_f32 v134, -v123, v132, v130
	v_fmac_f32_e32 v131, v133, v125
	v_fmac_f32_e32 v132, v134, v127
	v_fma_f32 v119, -v119, v131, v121
	v_fma_f32 v121, -v123, v132, v130
	v_div_fmas_f32 v119, v119, v125, v131
	s_mov_b64 vcc, s[0:1]
	v_div_fixup_f32 v111, v119, v111, 1.0
	v_div_fmas_f32 v119, v121, v127, v132
	v_div_fixup_f32 v109, v119, v109, 1.0
	v_mul_f32_e32 v104, v104, v111
	v_mul_f32_e32 v106, v106, v109
	v_cvt_pk_bf16_f32 v104, v104, v106
	global_store_dword v115, v104, s[10:11]
	s_nop 0
	v_cndmask_b32_e64 v106, v105, v107, s[6:7]
	v_add_u32_e32 v109, v108, v120
	s_waitcnt vmcnt(39)
	v_lshlrev_b32_e32 v111, 16, v169
	v_and_b32_e32 v104, 0xffff0000, v169
	v_mul_f32_e32 v111, 0xbfb8aa3b, v111
	v_mul_f32_e32 v104, 0xbfb8aa3b, v104
	v_exp_f32_e32 v111, v111
	v_exp_f32_e32 v104, v104
	v_mov_b32_dpp v106, v106 quad_perm:[1,0,3,2] row_mask:0xf bank_mask:0xf bound_ctrl:1
	v_cndmask_b32_e64 v105, v106, v105, s[6:7]
	v_add_f32_e32 v111, 1.0, v111
	v_add_f32_e32 v104, 1.0, v104
	v_div_scale_f32 v115, s[0:1], v111, v111, 1.0
	v_div_scale_f32 v119, s[0:1], v104, v104, 1.0
	v_rcp_f32_e32 v121, v115
	v_rcp_f32_e32 v123, v119
	v_div_scale_f32 v117, vcc, 1.0, v111, 1.0
	v_fma_f32 v127, -v115, v121, 1.0
	v_fma_f32 v130, -v119, v123, 1.0
	v_fmac_f32_e32 v121, v127, v121
	v_div_scale_f32 v125, s[0:1], 1.0, v104, 1.0
	v_fmac_f32_e32 v123, v130, v123
	v_mul_f32_e32 v127, v117, v121
	v_mul_f32_e32 v130, v125, v123
	v_fma_f32 v131, -v115, v127, v117
	v_fma_f32 v132, -v119, v130, v125
	v_fmac_f32_e32 v127, v131, v121
	v_fmac_f32_e32 v130, v132, v123
	v_fma_f32 v115, -v115, v127, v117
	v_fma_f32 v117, -v119, v130, v125
	v_div_fmas_f32 v115, v115, v121, v127
	s_mov_b64 vcc, s[0:1]
	v_div_fixup_f32 v111, v115, v111, 1.0
	v_div_fmas_f32 v115, v117, v123, v130
	v_cndmask_b32_e64 v106, v107, v106, s[6:7]
	v_div_fixup_f32 v104, v115, v104, 1.0
	v_mul_f32_e32 v105, v105, v111
	v_mul_f32_e32 v104, v106, v104
	v_cvt_pk_bf16_f32 v104, v105, v104
	v_add_lshl_u32 v107, v113, v122, 1
	global_store_dword v109, v104, s[10:11]
	s_nop 0
	v_cndmask_b32_e64 v105, v100, v102, s[6:7]
	v_add_u32_e32 v106, v114, v118
	v_add_lshl_u32 v107, v110, v122, 1
	v_mov_b32_dpp v105, v105 quad_perm:[1,0,3,2] row_mask:0xf bank_mask:0xf bound_ctrl:1
	v_cndmask_b32_e64 v100, v105, v100, s[6:7]
	v_cndmask_b32_e64 v102, v102, v105, s[6:7]
	s_waitcnt vmcnt(39)
	v_lshlrev_b32_e32 v105, 16, v170
	v_and_b32_e32 v104, 0xffff0000, v170
	v_mul_f32_e32 v105, 0xbfb8aa3b, v105
	v_mul_f32_e32 v104, 0xbfb8aa3b, v104
	v_exp_f32_e32 v105, v105
	v_exp_f32_e32 v104, v104
	v_add_f32_e32 v105, 1.0, v105
	v_add_f32_e32 v104, 1.0, v104
	v_div_scale_f32 v109, s[0:1], v105, v105, 1.0
	v_div_scale_f32 v115, s[0:1], v104, v104, 1.0
	v_rcp_f32_e32 v117, v109
	v_rcp_f32_e32 v119, v115
	v_div_scale_f32 v111, vcc, 1.0, v105, 1.0
	v_fma_f32 v123, -v109, v117, 1.0
	v_fma_f32 v125, -v115, v119, 1.0
	v_fmac_f32_e32 v117, v123, v117
	v_div_scale_f32 v121, s[0:1], 1.0, v104, 1.0
	v_fmac_f32_e32 v119, v125, v119
	v_mul_f32_e32 v123, v111, v117
	v_mul_f32_e32 v125, v121, v119
	v_fma_f32 v127, -v109, v123, v111
	v_fma_f32 v130, -v115, v125, v121
	v_fmac_f32_e32 v123, v127, v117
	v_fmac_f32_e32 v125, v130, v119
	v_fma_f32 v109, -v109, v123, v111
	v_fma_f32 v111, -v115, v125, v121
	v_div_fmas_f32 v109, v109, v117, v123
	s_mov_b64 vcc, s[0:1]
	v_div_fixup_f32 v105, v109, v105, 1.0
	v_div_fmas_f32 v109, v111, v119, v125
	v_div_fixup_f32 v104, v109, v104, 1.0
	v_mul_f32_e32 v100, v100, v105
	v_mul_f32_e32 v102, v102, v104
	v_cvt_pk_bf16_f32 v100, v100, v102
	global_store_dword v106, v100, s[10:11]
	s_nop 0
	v_cndmask_b32_e64 v102, v101, v103, s[6:7]
	v_add_u32_e32 v104, v108, v118
	s_waitcnt vmcnt(39)
	v_lshlrev_b32_e32 v105, 16, v171
	v_and_b32_e32 v100, 0xffff0000, v171
	v_mul_f32_e32 v105, 0xbfb8aa3b, v105
	v_mul_f32_e32 v100, 0xbfb8aa3b, v100
	v_exp_f32_e32 v105, v105
	v_exp_f32_e32 v100, v100
	v_mov_b32_dpp v102, v102 quad_perm:[1,0,3,2] row_mask:0xf bank_mask:0xf bound_ctrl:1
	v_cndmask_b32_e64 v101, v102, v101, s[6:7]
	v_add_f32_e32 v105, 1.0, v105
	v_add_f32_e32 v100, 1.0, v100
	v_div_scale_f32 v106, s[0:1], v105, v105, 1.0
	v_div_scale_f32 v109, s[0:1], v100, v100, 1.0
	v_rcp_f32_e32 v111, v106
	v_rcp_f32_e32 v115, v109
	v_div_scale_f32 v107, vcc, 1.0, v105, 1.0
	v_fma_f32 v119, -v106, v111, 1.0
	v_fma_f32 v121, -v109, v115, 1.0
	v_fmac_f32_e32 v111, v119, v111
	v_div_scale_f32 v117, s[0:1], 1.0, v100, 1.0
	v_fmac_f32_e32 v115, v121, v115
	v_mul_f32_e32 v119, v107, v111
	v_mul_f32_e32 v121, v117, v115
	v_fma_f32 v123, -v106, v119, v107
	v_fma_f32 v125, -v109, v121, v117
	v_fmac_f32_e32 v119, v123, v111
	v_fmac_f32_e32 v121, v125, v115
	v_fma_f32 v106, -v106, v119, v107
	v_fma_f32 v107, -v109, v121, v117
	v_div_fmas_f32 v106, v106, v111, v119
	s_mov_b64 vcc, s[0:1]
	v_div_fixup_f32 v105, v106, v105, 1.0
	v_div_fmas_f32 v106, v107, v115, v121
	v_cndmask_b32_e64 v102, v103, v102, s[6:7]
	v_div_fixup_f32 v100, v106, v100, 1.0
	v_mul_f32_e32 v101, v101, v105
	v_mul_f32_e32 v100, v102, v100
	v_cvt_pk_bf16_f32 v100, v101, v100
	v_add_lshl_u32 v103, v113, v116, 1
	global_store_dword v104, v100, s[10:11]
	s_nop 0
	v_cndmask_b32_e64 v101, v96, v98, s[6:7]
	v_add_u32_e32 v102, v114, v112
	v_add_lshl_u32 v103, v110, v116, 1
	v_mov_b32_dpp v101, v101 quad_perm:[1,0,3,2] row_mask:0xf bank_mask:0xf bound_ctrl:1
	v_cndmask_b32_e64 v96, v101, v96, s[6:7]
	v_cndmask_b32_e64 v98, v98, v101, s[6:7]
	s_waitcnt vmcnt(39)
; DEVINL float bflo(unsigned u) { return __uint_as_float(u << 16); }
; DEVINL float bfhi(unsigned u) { return __uint_as_float(u & 0xffff0000u); }
; DEVINL float sigm(float x) { return 1.f / (1.f + __expf(-x)); }
; template <int EPI, bool GATHER>
; DEVINL void gemm_tile(const Params& p, const u16* __restrict__ A, int lda, const int* __restrict__ rowidx,
;                       const u16* __restrict__ Bt, int ldb, int K, int brow, int bcol, int orow, int ocol) {
;     ...
;       const int rA = row0 + ai * HALF + m * 16 + (odd ? 2 : 0);
;       float gate[2] = {0.f, 0.f};
;       if (EPI == EPI_MOE2) { gate[0] = ((const float*)(ws + O_SELG))[rA]; gate[1] = ((const float*)(ws + O_SELG))[rA + 1]; }
; #pragma unroll
;       for (int bj = 0; bj < (EPI == EPI_HID ? 1 : 2); ++bj)
; #pragma unroll
;         for (int n = 0; n < 2; ++n) {
;           const int cc = bj * HALF + n * 16;
;           f32x4 v = acc[ai][bj][m][n];
;           if (EPI == EPI_HID) {
; #pragma unroll
;             for (int j = 0; j < 4; ++j) { const float a1 = acc[ai][0][m][n][j], a3 = acc[ai][1][m][n][j]; v[j] = a1 * sigm(a1) * a3; }
;           }
;           float lo[2], hi[2];
;           xchg_pairs(v, odd, lo, hi);
; #pragma unroll
;           for (int k = 0; k < 2; ++k) {
;             const unsigned row = (unsigned)(rA + k);
;             if (EPI == EPI_HID) {
;               *(unsigned*)(ws + O_HID + (row * 1024u + (unsigned)(colp + cc)) * 2u) = pk2(lo[k], hi[k]);
;             } else if (EPI == EPI_COLS) {
;               *(unsigned*)(ws + O_COLS + (row * (unsigned)NCP + (unsigned)(colp + cc)) * 2u) = pk2(lo[k], hi[k]);
;             } else if (EPI == EPI_MOE2) {
;               *(unsigned*)(ws + O_EO + (row * 2048u + (unsigned)(colp + cc)) * 2u) = pk2(gate[k] * lo[k], gate[k] * hi[k]);
;             } else if (EPI == EPI_M1) {
;               const unsigned g2 = *(const unsigned*)(ws + O_COLS + (row * (unsigned)NCP + (unsigned)(C_GG + colp + cc)) * 2u);
;               *(unsigned*)(ws + O_M1 + (row * 2048u + (unsigned)(colp + cc)) * 2u) = pk2(sigm(bflo(g2)) * lo[k], sigm(bfhi(g2)) * hi[k]);
	v_lshlrev_b32_e32 v101, 16, v172
	v_and_b32_e32 v100, 0xffff0000, v172
	v_mul_f32_e32 v101, 0xbfb8aa3b, v101
	v_mul_f32_e32 v100, 0xbfb8aa3b, v100
	v_exp_f32_e32 v101, v101
	v_exp_f32_e32 v100, v100
	v_add_f32_e32 v101, 1.0, v101
	v_add_f32_e32 v100, 1.0, v100
	v_div_scale_f32 v104, s[0:1], v101, v101, 1.0
	v_div_scale_f32 v106, s[0:1], v100, v100, 1.0
	v_rcp_f32_e32 v107, v104
	v_rcp_f32_e32 v109, v106
	v_div_scale_f32 v105, vcc, 1.0, v101, 1.0
	v_fma_f32 v111, -v104, v107, 1.0
	v_fma_f32 v114, -v106, v109, 1.0
	v_fmac_f32_e32 v107, v111, v107
	v_div_scale_f32 v110, s[0:1], 1.0, v100, 1.0
	v_fmac_f32_e32 v109, v114, v109
	v_mul_f32_e32 v111, v105, v107
	v_mul_f32_e32 v114, v110, v109
	v_fma_f32 v115, -v104, v111, v105
	v_fma_f32 v117, -v106, v114, v110
	v_fmac_f32_e32 v111, v115, v107
	v_fmac_f32_e32 v114, v117, v109
	v_fma_f32 v104, -v104, v111, v105
	v_fma_f32 v105, -v106, v114, v110
	v_div_fmas_f32 v104, v104, v107, v111
	s_mov_b64 vcc, s[0:1]
	v_div_fixup_f32 v101, v104, v101, 1.0
	v_div_fmas_f32 v104, v105, v109, v114
	v_div_fixup_f32 v100, v104, v100, 1.0
	v_mul_f32_e32 v96, v96, v101
	v_mul_f32_e32 v98, v98, v100
	v_cvt_pk_bf16_f32 v96, v96, v98
	global_store_dword v102, v96, s[10:11]
	s_nop 0
	v_cndmask_b32_e64 v98, v97, v99, s[6:7]
	s_waitcnt vmcnt(39)
	v_lshlrev_b32_e32 v100, 16, v173
	v_and_b32_e32 v96, 0xffff0000, v173
	v_mul_f32_e32 v100, 0xbfb8aa3b, v100
	v_mul_f32_e32 v96, 0xbfb8aa3b, v96
	v_exp_f32_e32 v100, v100
	v_exp_f32_e32 v96, v96
	v_mov_b32_dpp v98, v98 quad_perm:[1,0,3,2] row_mask:0xf bank_mask:0xf bound_ctrl:1
	v_cndmask_b32_e64 v97, v98, v97, s[6:7]
	v_cndmask_b32_e64 v98, v99, v98, s[6:7]
	v_add_f32_e32 v99, 1.0, v100
	v_add_f32_e32 v96, 1.0, v96
	v_div_scale_f32 v100, s[0:1], v99, v99, 1.0
	v_div_scale_f32 v102, s[0:1], v96, v96, 1.0
	v_rcp_f32_e32 v103, v100
	v_rcp_f32_e32 v104, v102
	v_div_scale_f32 v101, vcc, 1.0, v99, 1.0
	v_fma_f32 v106, -v100, v103, 1.0
	v_fma_f32 v107, -v102, v104, 1.0
	v_fmac_f32_e32 v103, v106, v103
	v_div_scale_f32 v105, s[0:1], 1.0, v96, 1.0
	v_fmac_f32_e32 v104, v107, v104
	v_mul_f32_e32 v106, v101, v103
	v_mul_f32_e32 v107, v105, v104
	v_fma_f32 v109, -v100, v106, v101
	v_fma_f32 v110, -v102, v107, v105
	v_fmac_f32_e32 v106, v109, v103
	v_fmac_f32_e32 v107, v110, v104
	v_fma_f32 v100, -v100, v106, v101
	v_fma_f32 v101, -v102, v107, v105
	v_div_fmas_f32 v100, v100, v103, v106
	s_mov_b64 vcc, s[0:1]
	v_div_fixup_f32 v99, v100, v99, 1.0
	v_div_fmas_f32 v100, v101, v104, v107
	v_div_fixup_f32 v96, v100, v96, 1.0
	v_mul_f32_e32 v97, v97, v99
	v_mul_f32_e32 v96, v98, v96
	v_cvt_pk_bf16_f32 v96, v97, v96
	v_add_u32_e32 v97, v108, v112
	global_store_dword v97, v96, s[10:11]
	v_add_u32_e32 v182, 0x150000, v113
	v_add_lshl_u32 v183, v182, v129, 1
	global_load_dword v166, v183, s[8:9]
	v_add_u32_e32 v184, 0x152a00, v113
	v_add_lshl_u32 v185, v184, v129, 1
	global_load_dword v167, v185, s[8:9]
	v_add_lshl_u32 v186, v182, v126, 1
	global_load_dword v168, v186, s[8:9]
	v_add_lshl_u32 v187, v184, v126, 1
	global_load_dword v169, v187, s[8:9]
	v_add_lshl_u32 v188, v182, v122, 1
	global_load_dword v170, v188, s[8:9]
	v_add_lshl_u32 v222, v184, v122, 1
	global_load_dword v171, v222, s[8:9]
	v_add_lshl_u32 v223, v182, v116, 1
	global_load_dword v172, v223, s[8:9]
	v_add_lshl_u32 v224, v184, v116, 1
	global_load_dword v173, v224, s[8:9]
	v_add_u32_e32 v98, 0x2a000, v113
	v_add_lshl_u32 v96, v98, v129, 1
	s_nop 0
	v_cndmask_b32_e64 v100, v92, v94, s[6:7]
	v_or_b32_e32 v96, 0x20000, v128
	v_add_u32_e32 v97, 0x2ca00, v113
	v_mov_b32_dpp v100, v100 quad_perm:[1,0,3,2] row_mask:0xf bank_mask:0xf bound_ctrl:1
	v_cndmask_b32_e64 v92, v100, v92, s[6:7]
	v_cndmask_b32_e64 v94, v94, v100, s[6:7]
	v_add_u32_e32 v101, v96, v124
	v_add_lshl_u32 v102, v97, v129, 1
	s_waitcnt vmcnt(47)
	v_lshlrev_b32_e32 v103, 16, v190
	v_and_b32_e32 v99, 0xffff0000, v190
	v_mul_f32_e32 v103, 0xbfb8aa3b, v103
	v_mul_f32_e32 v99, 0xbfb8aa3b, v99
	v_exp_f32_e32 v103, v103
	v_exp_f32_e32 v99, v99
	v_add_f32_e32 v100, 1.0, v103
	v_add_f32_e32 v99, 1.0, v99
	v_div_scale_f32 v103, s[0:1], v100, v100, 1.0
	v_div_scale_f32 v105, s[0:1], v99, v99, 1.0
	v_rcp_f32_e32 v106, v103
	v_rcp_f32_e32 v107, v105
	v_div_scale_f32 v104, vcc, 1.0, v100, 1.0
	v_fma_f32 v109, -v103, v106, 1.0
	v_fma_f32 v110, -v105, v107, 1.0
	v_fmac_f32_e32 v106, v109, v106
	v_div_scale_f32 v108, s[0:1], 1.0, v99, 1.0
	v_fmac_f32_e32 v107, v110, v107
	v_mul_f32_e32 v109, v104, v106
	v_mul_f32_e32 v110, v108, v107
	v_fma_f32 v111, -v103, v109, v104
	v_fma_f32 v114, -v105, v110, v108
	v_fmac_f32_e32 v109, v111, v106
	v_fmac_f32_e32 v110, v114, v107
	v_fma_f32 v103, -v103, v109, v104
	v_fma_f32 v104, -v105, v110, v108
	v_div_fmas_f32 v103, v103, v106, v109
	s_mov_b64 vcc, s[0:1]
	v_div_fixup_f32 v100, v103, v100, 1.0
	v_div_fmas_f32 v103, v104, v107, v110
	v_div_fixup_f32 v99, v103, v99, 1.0
	v_mul_f32_e32 v92, v92, v100
	v_mul_f32_e32 v94, v94, v99
	v_cvt_pk_bf16_f32 v92, v92, v94
	global_store_dword v101, v92, s[10:11]
	s_nop 0
	v_cndmask_b32_e64 v99, v93, v95, s[6:7]
	v_or_b32_e32 v92, 0x21000, v128
	v_add_u32_e32 v100, v92, v124
	v_mov_b32_dpp v99, v99 quad_perm:[1,0,3,2] row_mask:0xf bank_mask:0xf bound_ctrl:1
	v_cndmask_b32_e64 v93, v99, v93, s[6:7]
	v_cndmask_b32_e64 v95, v95, v99, s[6:7]
	v_add_lshl_u32 v101, v98, v126, 1
	s_waitcnt vmcnt(47)
; DEVINL float bflo(unsigned u) { return __uint_as_float(u << 16); }
; DEVINL float bfhi(unsigned u) { return __uint_as_float(u & 0xffff0000u); }
; DEVINL float sigm(float x) { return 1.f / (1.f + __expf(-x)); }
; template <int EPI, bool GATHER>
; DEVINL void gemm_tile(const Params& p, const u16* __restrict__ A, int lda, const int* __restrict__ rowidx,
;                       const u16* __restrict__ Bt, int ldb, int K, int brow, int bcol, int orow, int ocol) {
;     ...
;       const int rA = row0 + ai * HALF + m * 16 + (odd ? 2 : 0);
;       float gate[2] = {0.f, 0.f};
;       if (EPI == EPI_MOE2) { gate[0] = ((const float*)(ws + O_SELG))[rA]; gate[1] = ((const float*)(ws + O_SELG))[rA + 1]; }
; #pragma unroll
;       for (int bj = 0; bj < (EPI == EPI_HID ? 1 : 2); ++bj)
; #pragma unroll
;         for (int n = 0; n < 2; ++n) {
;           const int cc = bj * HALF + n * 16;
;           f32x4 v = acc[ai][bj][m][n];
;           if (EPI == EPI_HID) {
; #pragma unroll
;             for (int j = 0; j < 4; ++j) { const float a1 = acc[ai][0][m][n][j], a3 = acc[ai][1][m][n][j]; v[j] = a1 * sigm(a1) * a3; }
;           }
;           float lo[2], hi[2];
;           xchg_pairs(v, odd, lo, hi);
; #pragma unroll
;           for (int k = 0; k < 2; ++k) {
;             const unsigned row = (unsigned)(rA + k);
;             if (EPI == EPI_HID) {
;               *(unsigned*)(ws + O_HID + (row * 1024u + (unsigned)(colp + cc)) * 2u) = pk2(lo[k], hi[k]);
;             } else if (EPI == EPI_COLS) {
;               *(unsigned*)(ws + O_COLS + (row * (unsigned)NCP + (unsigned)(colp + cc)) * 2u) = pk2(lo[k], hi[k]);
;             } else if (EPI == EPI_MOE2) {
;               *(unsigned*)(ws + O_EO + (row * 2048u + (unsigned)(colp + cc)) * 2u) = pk2(gate[k] * lo[k], gate[k] * hi[k]);
;             } else if (EPI == EPI_M1) {
;               const unsigned g2 = *(const unsigned*)(ws + O_COLS + (row * (unsigned)NCP + (unsigned)(C_GG + colp + cc)) * 2u);
;               *(unsigned*)(ws + O_M1 + (row * 2048u + (unsigned)(colp + cc)) * 2u) = pk2(sigm(bflo(g2)) * lo[k], sigm(bfhi(g2)) * hi[k]);
	v_lshlrev_b32_e32 v102, 16, v191
	v_and_b32_e32 v94, 0xffff0000, v191
	v_mul_f32_e32 v102, 0xbfb8aa3b, v102
	v_mul_f32_e32 v94, 0xbfb8aa3b, v94
	v_exp_f32_e32 v102, v102
	v_exp_f32_e32 v94, v94
	v_add_f32_e32 v99, 1.0, v102
	v_add_f32_e32 v94, 1.0, v94
	v_div_scale_f32 v102, s[0:1], v99, v99, 1.0
	v_div_scale_f32 v104, s[0:1], v94, v94, 1.0
	v_rcp_f32_e32 v105, v102
	v_rcp_f32_e32 v106, v104
	v_div_scale_f32 v103, vcc, 1.0, v99, 1.0
	v_fma_f32 v108, -v102, v105, 1.0
	v_fma_f32 v109, -v104, v106, 1.0
	v_fmac_f32_e32 v105, v108, v105
	v_div_scale_f32 v107, s[0:1], 1.0, v94, 1.0
	v_fmac_f32_e32 v106, v109, v106
	v_mul_f32_e32 v108, v103, v105
	v_mul_f32_e32 v109, v107, v106
	v_fma_f32 v110, -v102, v108, v103
	v_fma_f32 v111, -v104, v109, v107
	v_fmac_f32_e32 v108, v110, v105
	v_fmac_f32_e32 v109, v111, v106
	v_fma_f32 v102, -v102, v108, v103
	v_fma_f32 v103, -v104, v109, v107
	v_div_fmas_f32 v102, v102, v105, v108
	s_mov_b64 vcc, s[0:1]
	v_div_fixup_f32 v99, v102, v99, 1.0
	v_div_fmas_f32 v102, v103, v106, v109
	v_div_fixup_f32 v94, v102, v94, 1.0
	v_mul_f32_e32 v93, v93, v99
	v_mul_f32_e32 v94, v95, v94
	v_cvt_pk_bf16_f32 v93, v93, v94
	global_store_dword v100, v93, s[10:11]
	s_nop 0
	v_cndmask_b32_e64 v94, v88, v90, s[6:7]
	v_add_u32_e32 v95, v96, v120
	v_add_lshl_u32 v99, v97, v126, 1
	v_mov_b32_dpp v94, v94 quad_perm:[1,0,3,2] row_mask:0xf bank_mask:0xf bound_ctrl:1
	v_cndmask_b32_e64 v88, v94, v88, s[6:7]
	v_cndmask_b32_e64 v90, v90, v94, s[6:7]
	s_waitcnt vmcnt(47)
	v_lshlrev_b32_e32 v100, 16, v192
	v_and_b32_e32 v93, 0xffff0000, v192
	v_mul_f32_e32 v100, 0xbfb8aa3b, v100
	v_mul_f32_e32 v93, 0xbfb8aa3b, v93
	v_exp_f32_e32 v100, v100
	v_exp_f32_e32 v93, v93
	v_add_f32_e32 v94, 1.0, v100
	v_add_f32_e32 v93, 1.0, v93
	v_div_scale_f32 v100, s[0:1], v94, v94, 1.0
	v_div_scale_f32 v102, s[0:1], v93, v93, 1.0
	v_rcp_f32_e32 v103, v100
	v_rcp_f32_e32 v104, v102
	v_div_scale_f32 v101, vcc, 1.0, v94, 1.0
	v_fma_f32 v106, -v100, v103, 1.0
	v_fma_f32 v107, -v102, v104, 1.0
	v_fmac_f32_e32 v103, v106, v103
	v_div_scale_f32 v105, s[0:1], 1.0, v93, 1.0
	v_fmac_f32_e32 v104, v107, v104
	v_mul_f32_e32 v106, v101, v103
	v_mul_f32_e32 v107, v105, v104
	v_fma_f32 v108, -v100, v106, v101
	v_fma_f32 v109, -v102, v107, v105
	v_fmac_f32_e32 v106, v108, v103
	v_fmac_f32_e32 v107, v109, v104
	v_fma_f32 v100, -v100, v106, v101
	v_fma_f32 v101, -v102, v107, v105
	v_div_fmas_f32 v100, v100, v103, v106
	s_mov_b64 vcc, s[0:1]
	v_div_fixup_f32 v94, v100, v94, 1.0
	v_div_fmas_f32 v100, v101, v104, v107
	v_div_fixup_f32 v93, v100, v93, 1.0
	v_mul_f32_e32 v88, v88, v94
	v_mul_f32_e32 v90, v90, v93
	v_cvt_pk_bf16_f32 v88, v88, v90
	global_store_dword v95, v88, s[10:11]
	s_nop 0
	v_cndmask_b32_e64 v90, v89, v91, s[6:7]
	v_add_u32_e32 v93, v92, v120
	v_add_lshl_u32 v94, v98, v122, 1
	v_mov_b32_dpp v90, v90 quad_perm:[1,0,3,2] row_mask:0xf bank_mask:0xf bound_ctrl:1
	v_cndmask_b32_e64 v89, v90, v89, s[6:7]
	v_cndmask_b32_e64 v90, v91, v90, s[6:7]
	s_waitcnt vmcnt(47)
	v_lshlrev_b32_e32 v95, 16, v193
	v_and_b32_e32 v88, 0xffff0000, v193
	v_mul_f32_e32 v95, 0xbfb8aa3b, v95
	v_mul_f32_e32 v88, 0xbfb8aa3b, v88
	v_exp_f32_e32 v95, v95
	v_exp_f32_e32 v88, v88
	v_add_f32_e32 v91, 1.0, v95
	v_add_f32_e32 v88, 1.0, v88
	v_div_scale_f32 v95, s[0:1], v91, v91, 1.0
	v_div_scale_f32 v100, s[0:1], v88, v88, 1.0
	v_rcp_f32_e32 v101, v95
	v_rcp_f32_e32 v102, v100
	v_div_scale_f32 v99, vcc, 1.0, v91, 1.0
	v_fma_f32 v104, -v95, v101, 1.0
	v_fma_f32 v105, -v100, v102, 1.0
	v_fmac_f32_e32 v101, v104, v101
	v_div_scale_f32 v103, s[0:1], 1.0, v88, 1.0
	v_fmac_f32_e32 v102, v105, v102
	v_mul_f32_e32 v104, v99, v101
	v_mul_f32_e32 v105, v103, v102
	v_fma_f32 v106, -v95, v104, v99
	v_fma_f32 v107, -v100, v105, v103
	v_fmac_f32_e32 v104, v106, v101
	v_fmac_f32_e32 v105, v107, v102
	v_fma_f32 v95, -v95, v104, v99
	v_fma_f32 v99, -v100, v105, v103
	v_div_fmas_f32 v95, v95, v101, v104
	s_mov_b64 vcc, s[0:1]
	v_div_fixup_f32 v91, v95, v91, 1.0
	v_div_fmas_f32 v95, v99, v102, v105
	v_div_fixup_f32 v88, v95, v88, 1.0
	v_mul_f32_e32 v89, v89, v91
	v_mul_f32_e32 v88, v90, v88
	v_cvt_pk_bf16_f32 v88, v89, v88
	global_store_dword v93, v88, s[10:11]
	s_nop 0
	v_cndmask_b32_e64 v89, v84, v86, s[6:7]
	v_add_u32_e32 v90, v96, v118
	v_add_lshl_u32 v91, v97, v122, 1
	v_mov_b32_dpp v89, v89 quad_perm:[1,0,3,2] row_mask:0xf bank_mask:0xf bound_ctrl:1
	v_cndmask_b32_e64 v84, v89, v84, s[6:7]
	v_cndmask_b32_e64 v86, v86, v89, s[6:7]
	s_waitcnt vmcnt(47)
	v_lshlrev_b32_e32 v93, 16, v194
	v_and_b32_e32 v88, 0xffff0000, v194
	v_mul_f32_e32 v93, 0xbfb8aa3b, v93
	v_mul_f32_e32 v88, 0xbfb8aa3b, v88
	v_exp_f32_e32 v93, v93
	v_exp_f32_e32 v88, v88
	v_add_f32_e32 v89, 1.0, v93
	v_add_f32_e32 v88, 1.0, v88
	v_div_scale_f32 v93, s[0:1], v89, v89, 1.0
	v_div_scale_f32 v95, s[0:1], v88, v88, 1.0
	v_rcp_f32_e32 v99, v93
	v_rcp_f32_e32 v100, v95
	v_div_scale_f32 v94, vcc, 1.0, v89, 1.0
	v_fma_f32 v102, -v93, v99, 1.0
	v_fma_f32 v103, -v95, v100, 1.0
	v_fmac_f32_e32 v99, v102, v99
	v_div_scale_f32 v101, s[0:1], 1.0, v88, 1.0
	v_fmac_f32_e32 v100, v103, v100
	v_mul_f32_e32 v102, v94, v99
	v_mul_f32_e32 v103, v101, v100
	v_fma_f32 v104, -v93, v102, v94
	v_fma_f32 v105, -v95, v103, v101
	v_fmac_f32_e32 v102, v104, v99
	v_fmac_f32_e32 v103, v105, v100
	v_fma_f32 v93, -v93, v102, v94
	v_fma_f32 v94, -v95, v103, v101
	v_div_fmas_f32 v93, v93, v99, v102
	s_mov_b64 vcc, s[0:1]
	v_div_fixup_f32 v89, v93, v89, 1.0
	v_div_fmas_f32 v93, v94, v100, v103
	v_div_fixup_f32 v88, v93, v88, 1.0
	v_mul_f32_e32 v84, v84, v89
	v_mul_f32_e32 v86, v86, v88
	v_cvt_pk_bf16_f32 v84, v84, v86
	global_store_dword v90, v84, s[10:11]
	s_nop 0
	v_cndmask_b32_e64 v86, v85, v87, s[6:7]
	v_add_lshl_u32 v89, v98, v116, 1
	v_add_u32_e32 v88, v92, v118
	v_mov_b32_dpp v86, v86 quad_perm:[1,0,3,2] row_mask:0xf bank_mask:0xf bound_ctrl:1
	v_cndmask_b32_e64 v85, v86, v85, s[6:7]
	v_cndmask_b32_e64 v86, v87, v86, s[6:7]
	s_waitcnt vmcnt(47)
; DEVINL float bflo(unsigned u) { return __uint_as_float(u << 16); }
; DEVINL float bfhi(unsigned u) { return __uint_as_float(u & 0xffff0000u); }
; DEVINL float sigm(float x) { return 1.f / (1.f + __expf(-x)); }
; template <int EPI, bool GATHER>
; DEVINL void gemm_tile(const Params& p, const u16* __restrict__ A, int lda, const int* __restrict__ rowidx,
;                       const u16* __restrict__ Bt, int ldb, int K, int brow, int bcol, int orow, int ocol) {
;     ...
;       const int rA = row0 + ai * HALF + m * 16 + (odd ? 2 : 0);
;       float gate[2] = {0.f, 0.f};
;       if (EPI == EPI_MOE2) { gate[0] = ((const float*)(ws + O_SELG))[rA]; gate[1] = ((const float*)(ws + O_SELG))[rA + 1]; }
; #pragma unroll
;       for (int bj = 0; bj < (EPI == EPI_HID ? 1 : 2); ++bj)
; #pragma unroll
;         for (int n = 0; n < 2; ++n) {
;           const int cc = bj * HALF + n * 16;
;           f32x4 v = acc[ai][bj][m][n];
;           if (EPI == EPI_HID) {
; #pragma unroll
;             for (int j = 0; j < 4; ++j) { const float a1 = acc[ai][0][m][n][j], a3 = acc[ai][1][m][n][j]; v[j] = a1 * sigm(a1) * a3; }
;           }
;           float lo[2], hi[2];
;           xchg_pairs(v, odd, lo, hi);
; #pragma unroll
;           for (int k = 0; k < 2; ++k) {
;             const unsigned row = (unsigned)(rA + k);
;             if (EPI == EPI_HID) {
;               *(unsigned*)(ws + O_HID + (row * 1024u + (unsigned)(colp + cc)) * 2u) = pk2(lo[k], hi[k]);
;             } else if (EPI == EPI_COLS) {
;               *(unsigned*)(ws + O_COLS + (row * (unsigned)NCP + (unsigned)(colp + cc)) * 2u) = pk2(lo[k], hi[k]);
;             } else if (EPI == EPI_MOE2) {
;               *(unsigned*)(ws + O_EO + (row * 2048u + (unsigned)(colp + cc)) * 2u) = pk2(gate[k] * lo[k], gate[k] * hi[k]);
;             } else if (EPI == EPI_M1) {
;               const unsigned g2 = *(const unsigned*)(ws + O_COLS + (row * (unsigned)NCP + (unsigned)(C_GG + colp + cc)) * 2u);
;               *(unsigned*)(ws + O_M1 + (row * 2048u + (unsigned)(colp + cc)) * 2u) = pk2(sigm(bflo(g2)) * lo[k], sigm(bfhi(g2)) * hi[k]);
	v_lshlrev_b32_e32 v90, 16, v195
	v_and_b32_e32 v84, 0xffff0000, v195
	v_mul_f32_e32 v90, 0xbfb8aa3b, v90
	v_mul_f32_e32 v84, 0xbfb8aa3b, v84
	v_exp_f32_e32 v90, v90
	v_exp_f32_e32 v84, v84
	v_add_f32_e32 v87, 1.0, v90
	v_add_f32_e32 v84, 1.0, v84
	v_div_scale_f32 v90, s[0:1], v87, v87, 1.0
	v_div_scale_f32 v93, s[0:1], v84, v84, 1.0
	v_rcp_f32_e32 v94, v90
	v_rcp_f32_e32 v95, v93
	v_div_scale_f32 v91, vcc, 1.0, v87, 1.0
	v_fma_f32 v99, -v90, v94, 1.0
	v_fma_f32 v100, -v93, v95, 1.0
	v_fmac_f32_e32 v94, v99, v94
	v_div_scale_f32 v98, s[0:1], 1.0, v84, 1.0
	v_fmac_f32_e32 v95, v100, v95
	v_mul_f32_e32 v99, v91, v94
	v_mul_f32_e32 v100, v98, v95
	v_fma_f32 v101, -v90, v99, v91
	v_fma_f32 v102, -v93, v100, v98
	v_fmac_f32_e32 v99, v101, v94
	v_fmac_f32_e32 v100, v102, v95
	v_fma_f32 v90, -v90, v99, v91
	v_fma_f32 v91, -v93, v100, v98
	v_div_fmas_f32 v90, v90, v94, v99
	s_mov_b64 vcc, s[0:1]
	v_div_fixup_f32 v87, v90, v87, 1.0
	v_div_fmas_f32 v90, v91, v95, v100
	v_div_fixup_f32 v84, v90, v84, 1.0
	v_mul_f32_e32 v85, v85, v87
	v_mul_f32_e32 v84, v86, v84
	v_cvt_pk_bf16_f32 v84, v85, v84
	global_store_dword v88, v84, s[10:11]
	s_nop 0
	v_cndmask_b32_e64 v85, v80, v82, s[6:7]
	v_add_u32_e32 v86, v96, v112
	v_add_lshl_u32 v87, v97, v116, 1
	v_mov_b32_dpp v85, v85 quad_perm:[1,0,3,2] row_mask:0xf bank_mask:0xf bound_ctrl:1
	v_cndmask_b32_e64 v80, v85, v80, s[6:7]
	v_cndmask_b32_e64 v82, v82, v85, s[6:7]
	s_waitcnt vmcnt(47)
	v_lshlrev_b32_e32 v88, 16, v196
	v_and_b32_e32 v84, 0xffff0000, v196
	v_mul_f32_e32 v88, 0xbfb8aa3b, v88
	v_mul_f32_e32 v84, 0xbfb8aa3b, v84
	v_exp_f32_e32 v88, v88
	v_exp_f32_e32 v84, v84
	v_add_f32_e32 v85, 1.0, v88
	v_add_f32_e32 v84, 1.0, v84
	v_div_scale_f32 v88, s[0:1], v85, v85, 1.0
	v_div_scale_f32 v90, s[0:1], v84, v84, 1.0
	v_rcp_f32_e32 v91, v88
	v_rcp_f32_e32 v93, v90
	v_div_scale_f32 v89, vcc, 1.0, v85, 1.0
	v_fma_f32 v95, -v88, v91, 1.0
	v_fma_f32 v96, -v90, v93, 1.0
	v_fmac_f32_e32 v91, v95, v91
	v_div_scale_f32 v94, s[0:1], 1.0, v84, 1.0
	v_fmac_f32_e32 v93, v96, v93
	v_mul_f32_e32 v95, v89, v91
	v_mul_f32_e32 v96, v94, v93
	v_fma_f32 v97, -v88, v95, v89
	v_fma_f32 v98, -v90, v96, v94
	v_fmac_f32_e32 v95, v97, v91
	v_fmac_f32_e32 v96, v98, v93
	v_fma_f32 v88, -v88, v95, v89
	v_fma_f32 v89, -v90, v96, v94
	v_div_fmas_f32 v88, v88, v91, v95
	s_mov_b64 vcc, s[0:1]
	v_div_fixup_f32 v85, v88, v85, 1.0
	v_div_fmas_f32 v88, v89, v93, v96
	v_div_fixup_f32 v84, v88, v84, 1.0
	v_mul_f32_e32 v80, v80, v85
	v_mul_f32_e32 v82, v82, v84
	v_cvt_pk_bf16_f32 v80, v80, v82
	global_store_dword v86, v80, s[10:11]
	s_nop 0
	v_cndmask_b32_e64 v82, v81, v83, s[6:7]
	s_waitcnt vmcnt(47)
	v_lshlrev_b32_e32 v84, 16, v197
	v_and_b32_e32 v80, 0xffff0000, v197
	v_mul_f32_e32 v84, 0xbfb8aa3b, v84
	v_mul_f32_e32 v80, 0xbfb8aa3b, v80
	v_exp_f32_e32 v84, v84
	v_exp_f32_e32 v80, v80
	v_mov_b32_dpp v82, v82 quad_perm:[1,0,3,2] row_mask:0xf bank_mask:0xf bound_ctrl:1
	v_cndmask_b32_e64 v81, v82, v81, s[6:7]
	v_cndmask_b32_e64 v82, v83, v82, s[6:7]
	v_add_f32_e32 v83, 1.0, v84
	v_add_f32_e32 v80, 1.0, v80
	v_div_scale_f32 v84, s[0:1], v83, v83, 1.0
	v_div_scale_f32 v86, s[0:1], v80, v80, 1.0
	v_rcp_f32_e32 v87, v84
	v_rcp_f32_e32 v88, v86
	v_div_scale_f32 v85, vcc, 1.0, v83, 1.0
	v_fma_f32 v90, -v84, v87, 1.0
	v_fma_f32 v91, -v86, v88, 1.0
	v_fmac_f32_e32 v87, v90, v87
	v_div_scale_f32 v89, s[0:1], 1.0, v80, 1.0
	v_fmac_f32_e32 v88, v91, v88
	v_mul_f32_e32 v90, v85, v87
	v_mul_f32_e32 v91, v89, v88
	v_fma_f32 v93, -v84, v90, v85
	v_fma_f32 v94, -v86, v91, v89
	v_fmac_f32_e32 v90, v93, v87
	v_fmac_f32_e32 v91, v94, v88
	v_fma_f32 v84, -v84, v90, v85
	v_fma_f32 v85, -v86, v91, v89
	v_div_fmas_f32 v84, v84, v87, v90
	s_mov_b64 vcc, s[0:1]
	v_div_fixup_f32 v83, v84, v83, 1.0
	v_div_fmas_f32 v84, v85, v88, v91
	v_div_fixup_f32 v80, v84, v80, 1.0
	v_mul_f32_e32 v81, v81, v83
	v_mul_f32_e32 v80, v82, v80
	v_cvt_pk_bf16_f32 v80, v81, v80
	v_add_u32_e32 v81, v92, v112
	global_store_dword v81, v80, s[10:11]
	v_add_u32_e32 v182, 0x17a000, v113
	v_add_lshl_u32 v183, v182, v129, 1
	global_load_dword v190, v183, s[8:9]
	v_add_u32_e32 v184, 0x17ca00, v113
	v_add_lshl_u32 v185, v184, v129, 1
	global_load_dword v191, v185, s[8:9]
	v_add_lshl_u32 v186, v182, v126, 1
	global_load_dword v192, v186, s[8:9]
	v_add_lshl_u32 v187, v184, v126, 1
	global_load_dword v193, v187, s[8:9]
	v_add_lshl_u32 v188, v182, v122, 1
	global_load_dword v194, v188, s[8:9]
	v_add_lshl_u32 v222, v184, v122, 1
	global_load_dword v195, v222, s[8:9]
	v_add_lshl_u32 v223, v182, v116, 1
	global_load_dword v196, v223, s[8:9]
	v_add_lshl_u32 v224, v184, v116, 1
	global_load_dword v197, v224, s[8:9]
	v_add_u32_e32 v82, 0x54000, v113
	v_add_lshl_u32 v80, v82, v129, 1
	s_nop 0
	v_cndmask_b32_e64 v84, v76, v78, s[6:7]
	v_or_b32_e32 v80, 0x30000, v128
	v_add_u32_e32 v81, 0x56a00, v113
	v_mov_b32_dpp v84, v84 quad_perm:[1,0,3,2] row_mask:0xf bank_mask:0xf bound_ctrl:1
	v_cndmask_b32_e64 v76, v84, v76, s[6:7]
	v_cndmask_b32_e64 v78, v78, v84, s[6:7]
	v_add_u32_e32 v85, v80, v124
	v_add_lshl_u32 v86, v81, v129, 1
	s_waitcnt vmcnt(55)
; DEVINL float bflo(unsigned u) { return __uint_as_float(u << 16); }
; DEVINL float bfhi(unsigned u) { return __uint_as_float(u & 0xffff0000u); }
; DEVINL float sigm(float x) { return 1.f / (1.f + __expf(-x)); }
; template <int EPI, bool GATHER>
; DEVINL void gemm_tile(const Params& p, const u16* __restrict__ A, int lda, const int* __restrict__ rowidx,
;                       const u16* __restrict__ Bt, int ldb, int K, int brow, int bcol, int orow, int ocol) {
;     ...
;       const int rA = row0 + ai * HALF + m * 16 + (odd ? 2 : 0);
;       float gate[2] = {0.f, 0.f};
;       if (EPI == EPI_MOE2) { gate[0] = ((const float*)(ws + O_SELG))[rA]; gate[1] = ((const float*)(ws + O_SELG))[rA + 1]; }
; #pragma unroll
;       for (int bj = 0; bj < (EPI == EPI_HID ? 1 : 2); ++bj)
; #pragma unroll
;         for (int n = 0; n < 2; ++n) {
;           const int cc = bj * HALF + n * 16;
;           f32x4 v = acc[ai][bj][m][n];
;           if (EPI == EPI_HID) {
; #pragma unroll
;             for (int j = 0; j < 4; ++j) { const float a1 = acc[ai][0][m][n][j], a3 = acc[ai][1][m][n][j]; v[j] = a1 * sigm(a1) * a3; }
;           }
;           float lo[2], hi[2];
;           xchg_pairs(v, odd, lo, hi);
; #pragma unroll
;           for (int k = 0; k < 2; ++k) {
;             const unsigned row = (unsigned)(rA + k);
;             if (EPI == EPI_HID) {
;               *(unsigned*)(ws + O_HID + (row * 1024u + (unsigned)(colp + cc)) * 2u) = pk2(lo[k], hi[k]);
;             } else if (EPI == EPI_COLS) {
;               *(unsigned*)(ws + O_COLS + (row * (unsigned)NCP + (unsigned)(colp + cc)) * 2u) = pk2(lo[k], hi[k]);
;             } else if (EPI == EPI_MOE2) {
;               *(unsigned*)(ws + O_EO + (row * 2048u + (unsigned)(colp + cc)) * 2u) = pk2(gate[k] * lo[k], gate[k] * hi[k]);
;             } else if (EPI == EPI_M1) {
;               const unsigned g2 = *(const unsigned*)(ws + O_COLS + (row * (unsigned)NCP + (unsigned)(C_GG + colp + cc)) * 2u);
;               *(unsigned*)(ws + O_M1 + (row * 2048u + (unsigned)(colp + cc)) * 2u) = pk2(sigm(bflo(g2)) * lo[k], sigm(bfhi(g2)) * hi[k]);
	v_lshlrev_b32_e32 v87, 16, v206
	v_and_b32_e32 v83, 0xffff0000, v206
	v_mul_f32_e32 v87, 0xbfb8aa3b, v87
	v_mul_f32_e32 v83, 0xbfb8aa3b, v83
	v_exp_f32_e32 v87, v87
	v_exp_f32_e32 v83, v83
	v_add_f32_e32 v84, 1.0, v87
	v_add_f32_e32 v83, 1.0, v83
	v_div_scale_f32 v87, s[0:1], v84, v84, 1.0
	v_div_scale_f32 v89, s[0:1], v83, v83, 1.0
	v_rcp_f32_e32 v90, v87
	v_rcp_f32_e32 v91, v89
	v_div_scale_f32 v88, vcc, 1.0, v84, 1.0
	v_fma_f32 v93, -v87, v90, 1.0
	v_fma_f32 v94, -v89, v91, 1.0
	v_fmac_f32_e32 v90, v93, v90
	v_div_scale_f32 v92, s[0:1], 1.0, v83, 1.0
	v_fmac_f32_e32 v91, v94, v91
	v_mul_f32_e32 v93, v88, v90
	v_mul_f32_e32 v94, v92, v91
	v_fma_f32 v95, -v87, v93, v88
	v_fma_f32 v96, -v89, v94, v92
	v_fmac_f32_e32 v93, v95, v90
	v_fmac_f32_e32 v94, v96, v91
	v_fma_f32 v87, -v87, v93, v88
	v_fma_f32 v88, -v89, v94, v92
	v_div_fmas_f32 v87, v87, v90, v93
	s_mov_b64 vcc, s[0:1]
	v_div_fixup_f32 v84, v87, v84, 1.0
	v_div_fmas_f32 v87, v88, v91, v94
	v_div_fixup_f32 v83, v87, v83, 1.0
	v_mul_f32_e32 v76, v76, v84
	v_mul_f32_e32 v78, v78, v83
	v_cvt_pk_bf16_f32 v76, v76, v78
	global_store_dword v85, v76, s[10:11]
	s_nop 0
	v_cndmask_b32_e64 v83, v77, v79, s[6:7]
	v_or_b32_e32 v76, 0x31000, v128
	v_add_u32_e32 v84, v76, v124
	v_mov_b32_dpp v83, v83 quad_perm:[1,0,3,2] row_mask:0xf bank_mask:0xf bound_ctrl:1
	v_cndmask_b32_e64 v77, v83, v77, s[6:7]
	v_cndmask_b32_e64 v79, v79, v83, s[6:7]
	v_add_lshl_u32 v85, v82, v126, 1
	s_waitcnt vmcnt(55)
	v_lshlrev_b32_e32 v86, 16, v207
	v_and_b32_e32 v78, 0xffff0000, v207
	v_mul_f32_e32 v86, 0xbfb8aa3b, v86
	v_mul_f32_e32 v78, 0xbfb8aa3b, v78
	v_exp_f32_e32 v86, v86
	v_exp_f32_e32 v78, v78
	v_add_f32_e32 v83, 1.0, v86
	v_add_f32_e32 v78, 1.0, v78
	v_div_scale_f32 v86, s[0:1], v83, v83, 1.0
	v_div_scale_f32 v88, s[0:1], v78, v78, 1.0
	v_rcp_f32_e32 v89, v86
	v_rcp_f32_e32 v90, v88
	v_div_scale_f32 v87, vcc, 1.0, v83, 1.0
	v_fma_f32 v92, -v86, v89, 1.0
	v_fma_f32 v93, -v88, v90, 1.0
	v_fmac_f32_e32 v89, v92, v89
	v_div_scale_f32 v91, s[0:1], 1.0, v78, 1.0
	v_fmac_f32_e32 v90, v93, v90
	v_mul_f32_e32 v92, v87, v89
	v_mul_f32_e32 v93, v91, v90
	v_fma_f32 v94, -v86, v92, v87
	v_fma_f32 v95, -v88, v93, v91
	v_fmac_f32_e32 v92, v94, v89
	v_fmac_f32_e32 v93, v95, v90
	v_fma_f32 v86, -v86, v92, v87
	v_fma_f32 v87, -v88, v93, v91
	v_div_fmas_f32 v86, v86, v89, v92
	s_mov_b64 vcc, s[0:1]
	v_div_fixup_f32 v83, v86, v83, 1.0
	v_div_fmas_f32 v86, v87, v90, v93
	v_div_fixup_f32 v78, v86, v78, 1.0
	v_mul_f32_e32 v77, v77, v83
	v_mul_f32_e32 v78, v79, v78
	v_cvt_pk_bf16_f32 v77, v77, v78
	global_store_dword v84, v77, s[10:11]
	s_nop 0
	v_cndmask_b32_e64 v78, v72, v74, s[6:7]
	v_add_u32_e32 v79, v80, v120
	v_add_lshl_u32 v83, v81, v126, 1
	v_mov_b32_dpp v78, v78 quad_perm:[1,0,3,2] row_mask:0xf bank_mask:0xf bound_ctrl:1
	v_cndmask_b32_e64 v72, v78, v72, s[6:7]
	v_cndmask_b32_e64 v74, v74, v78, s[6:7]
	s_waitcnt vmcnt(55)
	v_lshlrev_b32_e32 v84, 16, v208
	v_and_b32_e32 v77, 0xffff0000, v208
	v_mul_f32_e32 v84, 0xbfb8aa3b, v84
	v_mul_f32_e32 v77, 0xbfb8aa3b, v77
	v_exp_f32_e32 v84, v84
	v_exp_f32_e32 v77, v77
	v_add_f32_e32 v78, 1.0, v84
	v_add_f32_e32 v77, 1.0, v77
	v_div_scale_f32 v84, s[0:1], v78, v78, 1.0
	v_div_scale_f32 v86, s[0:1], v77, v77, 1.0
	v_rcp_f32_e32 v87, v84
	v_rcp_f32_e32 v88, v86
	v_div_scale_f32 v85, vcc, 1.0, v78, 1.0
	v_fma_f32 v90, -v84, v87, 1.0
	v_fma_f32 v91, -v86, v88, 1.0
	v_fmac_f32_e32 v87, v90, v87
	v_div_scale_f32 v89, s[0:1], 1.0, v77, 1.0
	v_fmac_f32_e32 v88, v91, v88
	v_mul_f32_e32 v90, v85, v87
	v_mul_f32_e32 v91, v89, v88
	v_fma_f32 v92, -v84, v90, v85
	v_fma_f32 v93, -v86, v91, v89
	v_fmac_f32_e32 v90, v92, v87
	v_fmac_f32_e32 v91, v93, v88
	v_fma_f32 v84, -v84, v90, v85
	v_fma_f32 v85, -v86, v91, v89
	v_div_fmas_f32 v84, v84, v87, v90
	s_mov_b64 vcc, s[0:1]
	v_div_fixup_f32 v78, v84, v78, 1.0
	v_div_fmas_f32 v84, v85, v88, v91
	v_div_fixup_f32 v77, v84, v77, 1.0
	v_mul_f32_e32 v72, v72, v78
	v_mul_f32_e32 v74, v74, v77
	v_cvt_pk_bf16_f32 v72, v72, v74
	global_store_dword v79, v72, s[10:11]
	s_nop 0
	v_cndmask_b32_e64 v74, v73, v75, s[6:7]
	v_add_u32_e32 v77, v76, v120
	v_add_lshl_u32 v78, v82, v122, 1
	v_mov_b32_dpp v74, v74 quad_perm:[1,0,3,2] row_mask:0xf bank_mask:0xf bound_ctrl:1
	v_cndmask_b32_e64 v73, v74, v73, s[6:7]
	v_cndmask_b32_e64 v74, v75, v74, s[6:7]
	s_waitcnt vmcnt(55)
	v_lshlrev_b32_e32 v79, 16, v209
	v_and_b32_e32 v72, 0xffff0000, v209
	v_mul_f32_e32 v79, 0xbfb8aa3b, v79
	v_mul_f32_e32 v72, 0xbfb8aa3b, v72
	v_exp_f32_e32 v79, v79
	v_exp_f32_e32 v72, v72
	v_add_f32_e32 v75, 1.0, v79
	v_add_f32_e32 v72, 1.0, v72
	v_div_scale_f32 v79, s[0:1], v75, v75, 1.0
	v_div_scale_f32 v84, s[0:1], v72, v72, 1.0
	v_rcp_f32_e32 v85, v79
	v_rcp_f32_e32 v86, v84
	v_div_scale_f32 v83, vcc, 1.0, v75, 1.0
	v_fma_f32 v88, -v79, v85, 1.0
	v_fma_f32 v89, -v84, v86, 1.0
	v_fmac_f32_e32 v85, v88, v85
	v_div_scale_f32 v87, s[0:1], 1.0, v72, 1.0
	v_fmac_f32_e32 v86, v89, v86
	v_mul_f32_e32 v88, v83, v85
	v_mul_f32_e32 v89, v87, v86
	v_fma_f32 v90, -v79, v88, v83
	v_fma_f32 v91, -v84, v89, v87
	v_fmac_f32_e32 v88, v90, v85
	v_fmac_f32_e32 v89, v91, v86
	v_fma_f32 v79, -v79, v88, v83
	v_fma_f32 v83, -v84, v89, v87
	v_div_fmas_f32 v79, v79, v85, v88
	s_mov_b64 vcc, s[0:1]
	v_div_fixup_f32 v75, v79, v75, 1.0
	v_div_fmas_f32 v79, v83, v86, v89
	v_div_fixup_f32 v72, v79, v72, 1.0
	v_mul_f32_e32 v73, v73, v75
	v_mul_f32_e32 v72, v74, v72
	v_cvt_pk_bf16_f32 v72, v73, v72
	global_store_dword v77, v72, s[10:11]
	s_nop 0
	v_cndmask_b32_e64 v73, v68, v70, s[6:7]
	v_add_u32_e32 v74, v80, v118
	v_add_lshl_u32 v75, v81, v122, 1
	v_mov_b32_dpp v73, v73 quad_perm:[1,0,3,2] row_mask:0xf bank_mask:0xf bound_ctrl:1
	v_cndmask_b32_e64 v68, v73, v68, s[6:7]
	v_cndmask_b32_e64 v70, v70, v73, s[6:7]
	s_waitcnt vmcnt(55)
; DEVINL float bflo(unsigned u) { return __uint_as_float(u << 16); }
; DEVINL float bfhi(unsigned u) { return __uint_as_float(u & 0xffff0000u); }
; DEVINL float sigm(float x) { return 1.f / (1.f + __expf(-x)); }
; template <int EPI, bool GATHER>
; DEVINL void gemm_tile(const Params& p, const u16* __restrict__ A, int lda, const int* __restrict__ rowidx,
;                       const u16* __restrict__ Bt, int ldb, int K, int brow, int bcol, int orow, int ocol) {
;     ...
;       const int rA = row0 + ai * HALF + m * 16 + (odd ? 2 : 0);
;       float gate[2] = {0.f, 0.f};
;       if (EPI == EPI_MOE2) { gate[0] = ((const float*)(ws + O_SELG))[rA]; gate[1] = ((const float*)(ws + O_SELG))[rA + 1]; }
; #pragma unroll
;       for (int bj = 0; bj < (EPI == EPI_HID ? 1 : 2); ++bj)
; #pragma unroll
;         for (int n = 0; n < 2; ++n) {
;           const int cc = bj * HALF + n * 16;
;           f32x4 v = acc[ai][bj][m][n];
;           if (EPI == EPI_HID) {
; #pragma unroll
;             for (int j = 0; j < 4; ++j) { const float a1 = acc[ai][0][m][n][j], a3 = acc[ai][1][m][n][j]; v[j] = a1 * sigm(a1) * a3; }
;           }
;           float lo[2], hi[2];
;           xchg_pairs(v, odd, lo, hi);
; #pragma unroll
;           for (int k = 0; k < 2; ++k) {
;             const unsigned row = (unsigned)(rA + k);
;             if (EPI == EPI_HID) {
;               *(unsigned*)(ws + O_HID + (row * 1024u + (unsigned)(colp + cc)) * 2u) = pk2(lo[k], hi[k]);
;             } else if (EPI == EPI_COLS) {
;               *(unsigned*)(ws + O_COLS + (row * (unsigned)NCP + (unsigned)(colp + cc)) * 2u) = pk2(lo[k], hi[k]);
;             } else if (EPI == EPI_MOE2) {
;               *(unsigned*)(ws + O_EO + (row * 2048u + (unsigned)(colp + cc)) * 2u) = pk2(gate[k] * lo[k], gate[k] * hi[k]);
;             } else if (EPI == EPI_M1) {
;               const unsigned g2 = *(const unsigned*)(ws + O_COLS + (row * (unsigned)NCP + (unsigned)(C_GG + colp + cc)) * 2u);
;               *(unsigned*)(ws + O_M1 + (row * 2048u + (unsigned)(colp + cc)) * 2u) = pk2(sigm(bflo(g2)) * lo[k], sigm(bfhi(g2)) * hi[k]);
	v_lshlrev_b32_e32 v77, 16, v210
	v_and_b32_e32 v72, 0xffff0000, v210
	v_mul_f32_e32 v77, 0xbfb8aa3b, v77
	v_mul_f32_e32 v72, 0xbfb8aa3b, v72
	v_exp_f32_e32 v77, v77
	v_exp_f32_e32 v72, v72
	v_add_f32_e32 v73, 1.0, v77
	v_add_f32_e32 v72, 1.0, v72
	v_div_scale_f32 v77, s[0:1], v73, v73, 1.0
	v_div_scale_f32 v79, s[0:1], v72, v72, 1.0
	v_rcp_f32_e32 v83, v77
	v_rcp_f32_e32 v84, v79
	v_div_scale_f32 v78, vcc, 1.0, v73, 1.0
	v_fma_f32 v86, -v77, v83, 1.0
	v_fma_f32 v87, -v79, v84, 1.0
	v_fmac_f32_e32 v83, v86, v83
	v_div_scale_f32 v85, s[0:1], 1.0, v72, 1.0
	v_fmac_f32_e32 v84, v87, v84
	v_mul_f32_e32 v86, v78, v83
	v_mul_f32_e32 v87, v85, v84
	v_fma_f32 v88, -v77, v86, v78
	v_fma_f32 v89, -v79, v87, v85
	v_fmac_f32_e32 v86, v88, v83
	v_fmac_f32_e32 v87, v89, v84
	v_fma_f32 v77, -v77, v86, v78
	v_fma_f32 v78, -v79, v87, v85
	v_div_fmas_f32 v77, v77, v83, v86
	s_mov_b64 vcc, s[0:1]
	v_div_fixup_f32 v73, v77, v73, 1.0
	v_div_fmas_f32 v77, v78, v84, v87
	v_div_fixup_f32 v72, v77, v72, 1.0
	v_mul_f32_e32 v68, v68, v73
	v_mul_f32_e32 v70, v70, v72
	v_cvt_pk_bf16_f32 v68, v68, v70
	global_store_dword v74, v68, s[10:11]
	s_nop 0
	v_cndmask_b32_e64 v70, v69, v71, s[6:7]
	v_add_lshl_u32 v73, v82, v116, 1
	v_add_u32_e32 v72, v76, v118
	v_mov_b32_dpp v70, v70 quad_perm:[1,0,3,2] row_mask:0xf bank_mask:0xf bound_ctrl:1
	v_cndmask_b32_e64 v69, v70, v69, s[6:7]
	v_cndmask_b32_e64 v70, v71, v70, s[6:7]
	s_waitcnt vmcnt(55)
	v_lshlrev_b32_e32 v74, 16, v211
	v_and_b32_e32 v68, 0xffff0000, v211
	v_mul_f32_e32 v74, 0xbfb8aa3b, v74
	v_mul_f32_e32 v68, 0xbfb8aa3b, v68
	v_exp_f32_e32 v74, v74
	v_exp_f32_e32 v68, v68
	v_add_f32_e32 v71, 1.0, v74
	v_add_f32_e32 v68, 1.0, v68
	v_div_scale_f32 v74, s[0:1], v71, v71, 1.0
	v_div_scale_f32 v77, s[0:1], v68, v68, 1.0
	v_rcp_f32_e32 v78, v74
	v_rcp_f32_e32 v79, v77
	v_div_scale_f32 v75, vcc, 1.0, v71, 1.0
	v_fma_f32 v83, -v74, v78, 1.0
	v_fma_f32 v84, -v77, v79, 1.0
	v_fmac_f32_e32 v78, v83, v78
	v_div_scale_f32 v82, s[0:1], 1.0, v68, 1.0
	v_fmac_f32_e32 v79, v84, v79
	v_mul_f32_e32 v83, v75, v78
	v_mul_f32_e32 v84, v82, v79
	v_fma_f32 v85, -v74, v83, v75
	v_fma_f32 v86, -v77, v84, v82
	v_fmac_f32_e32 v83, v85, v78
	v_fmac_f32_e32 v84, v86, v79
	v_fma_f32 v74, -v74, v83, v75
	v_fma_f32 v75, -v77, v84, v82
	v_div_fmas_f32 v74, v74, v78, v83
	s_mov_b64 vcc, s[0:1]
	v_div_fixup_f32 v71, v74, v71, 1.0
	v_div_fmas_f32 v74, v75, v79, v84
	v_div_fixup_f32 v68, v74, v68, 1.0
	v_mul_f32_e32 v69, v69, v71
	v_mul_f32_e32 v68, v70, v68
	v_cvt_pk_bf16_f32 v68, v69, v68
	global_store_dword v72, v68, s[10:11]
	s_nop 0
	v_cndmask_b32_e64 v69, v64, v66, s[6:7]
	v_add_u32_e32 v70, v80, v112
	v_add_lshl_u32 v71, v81, v116, 1
	v_mov_b32_dpp v69, v69 quad_perm:[1,0,3,2] row_mask:0xf bank_mask:0xf bound_ctrl:1
	v_cndmask_b32_e64 v64, v69, v64, s[6:7]
	v_cndmask_b32_e64 v66, v66, v69, s[6:7]
	s_waitcnt vmcnt(55)
	v_lshlrev_b32_e32 v72, 16, v212
	v_and_b32_e32 v68, 0xffff0000, v212
	v_mul_f32_e32 v72, 0xbfb8aa3b, v72
	v_mul_f32_e32 v68, 0xbfb8aa3b, v68
	v_exp_f32_e32 v72, v72
	v_exp_f32_e32 v68, v68
	v_add_f32_e32 v69, 1.0, v72
	v_add_f32_e32 v68, 1.0, v68
	v_div_scale_f32 v72, s[0:1], v69, v69, 1.0
	v_div_scale_f32 v74, s[0:1], v68, v68, 1.0
	v_rcp_f32_e32 v75, v72
	v_rcp_f32_e32 v77, v74
	v_div_scale_f32 v73, vcc, 1.0, v69, 1.0
	v_fma_f32 v79, -v72, v75, 1.0
	v_fma_f32 v80, -v74, v77, 1.0
	v_fmac_f32_e32 v75, v79, v75
	v_div_scale_f32 v78, s[0:1], 1.0, v68, 1.0
	v_fmac_f32_e32 v77, v80, v77
	v_mul_f32_e32 v79, v73, v75
	v_mul_f32_e32 v80, v78, v77
	v_fma_f32 v81, -v72, v79, v73
	v_fma_f32 v82, -v74, v80, v78
	v_fmac_f32_e32 v79, v81, v75
	v_fmac_f32_e32 v80, v82, v77
	v_fma_f32 v72, -v72, v79, v73
	v_fma_f32 v73, -v74, v80, v78
	v_div_fmas_f32 v72, v72, v75, v79
	s_mov_b64 vcc, s[0:1]
	v_div_fixup_f32 v69, v72, v69, 1.0
	v_div_fmas_f32 v72, v73, v77, v80
	v_div_fixup_f32 v68, v72, v68, 1.0
	v_mul_f32_e32 v64, v64, v69
	v_mul_f32_e32 v66, v66, v68
	v_cvt_pk_bf16_f32 v64, v64, v66
	global_store_dword v70, v64, s[10:11]
	s_nop 0
	v_cndmask_b32_e64 v66, v65, v67, s[6:7]
	s_waitcnt vmcnt(55)
	v_lshlrev_b32_e32 v68, 16, v213
	v_and_b32_e32 v64, 0xffff0000, v213
	v_mul_f32_e32 v68, 0xbfb8aa3b, v68
	v_mul_f32_e32 v64, 0xbfb8aa3b, v64
	v_exp_f32_e32 v68, v68
	v_exp_f32_e32 v64, v64
	v_mov_b32_dpp v66, v66 quad_perm:[1,0,3,2] row_mask:0xf bank_mask:0xf bound_ctrl:1
	v_cndmask_b32_e64 v65, v66, v65, s[6:7]
	v_cndmask_b32_e64 v66, v67, v66, s[6:7]
	v_add_f32_e32 v67, 1.0, v68
	v_add_f32_e32 v64, 1.0, v64
	v_div_scale_f32 v68, s[0:1], v67, v67, 1.0
	v_div_scale_f32 v70, s[0:1], v64, v64, 1.0
	v_rcp_f32_e32 v71, v68
	v_rcp_f32_e32 v72, v70
	v_div_scale_f32 v69, vcc, 1.0, v67, 1.0
	v_fma_f32 v74, -v68, v71, 1.0
	v_fma_f32 v75, -v70, v72, 1.0
	v_fmac_f32_e32 v71, v74, v71
	v_div_scale_f32 v73, s[0:1], 1.0, v64, 1.0
	v_fmac_f32_e32 v72, v75, v72
	v_mul_f32_e32 v74, v69, v71
	v_mul_f32_e32 v75, v73, v72
	v_fma_f32 v77, -v68, v74, v69
	v_fma_f32 v78, -v70, v75, v73
	v_fmac_f32_e32 v74, v77, v71
	v_fmac_f32_e32 v75, v78, v72
	v_fma_f32 v68, -v68, v74, v69
	v_fma_f32 v69, -v70, v75, v73
	v_div_fmas_f32 v68, v68, v71, v74
	s_mov_b64 vcc, s[0:1]
	v_div_fixup_f32 v67, v68, v67, 1.0
	v_div_fmas_f32 v68, v69, v72, v75
	v_div_fixup_f32 v64, v68, v64, 1.0
	v_mul_f32_e32 v65, v65, v67
	v_mul_f32_e32 v64, v66, v64
	v_cvt_pk_bf16_f32 v64, v65, v64
	v_add_u32_e32 v65, v76, v112
	global_store_dword v65, v64, s[10:11]
	v_add_u32_e32 v182, 0x1a4000, v113
	v_add_lshl_u32 v183, v182, v129, 1
	global_load_dword v206, v183, s[8:9]
	v_add_u32_e32 v184, 0x1a6a00, v113
	v_add_lshl_u32 v185, v184, v129, 1
	global_load_dword v207, v185, s[8:9]
	v_add_lshl_u32 v186, v182, v126, 1
	global_load_dword v208, v186, s[8:9]
	v_add_lshl_u32 v187, v184, v126, 1
	global_load_dword v209, v187, s[8:9]
	v_add_lshl_u32 v188, v182, v122, 1
	global_load_dword v210, v188, s[8:9]
	v_add_lshl_u32 v222, v184, v122, 1
	global_load_dword v211, v222, s[8:9]
	v_add_lshl_u32 v223, v182, v116, 1
	global_load_dword v212, v223, s[8:9]
	v_add_lshl_u32 v224, v184, v116, 1
	global_load_dword v213, v224, s[8:9]
	v_add_u32_e32 v66, 0x126000, v113
	v_add_lshl_u32 v64, v66, v129, 1
	s_nop 0
	v_cndmask_b32_e64 v68, v60, v62, s[6:7]
	v_add_u32_e32 v64, 0x80000, v128
	v_add_u32_e32 v65, 0x128a00, v113
	v_mov_b32_dpp v68, v68 quad_perm:[1,0,3,2] row_mask:0xf bank_mask:0xf bound_ctrl:1
	v_cndmask_b32_e64 v60, v68, v60, s[6:7]
	v_cndmask_b32_e64 v62, v62, v68, s[6:7]
	v_add_u32_e32 v69, v64, v124
	v_add_lshl_u32 v70, v65, v129, 1
	s_waitcnt vmcnt(55)
; DEVINL float bflo(unsigned u) { return __uint_as_float(u << 16); }
; DEVINL float bfhi(unsigned u) { return __uint_as_float(u & 0xffff0000u); }
; DEVINL float sigm(float x) { return 1.f / (1.f + __expf(-x)); }
; template <int EPI, bool GATHER>
; DEVINL void gemm_tile(const Params& p, const u16* __restrict__ A, int lda, const int* __restrict__ rowidx,
;                       const u16* __restrict__ Bt, int ldb, int K, int brow, int bcol, int orow, int ocol) {
;     ...
;       const int rA = row0 + ai * HALF + m * 16 + (odd ? 2 : 0);
;       float gate[2] = {0.f, 0.f};
;       if (EPI == EPI_MOE2) { gate[0] = ((const float*)(ws + O_SELG))[rA]; gate[1] = ((const float*)(ws + O_SELG))[rA + 1]; }
; #pragma unroll
;       for (int bj = 0; bj < (EPI == EPI_HID ? 1 : 2); ++bj)
; #pragma unroll
;         for (int n = 0; n < 2; ++n) {
;           const int cc = bj * HALF + n * 16;
;           f32x4 v = acc[ai][bj][m][n];
;           if (EPI == EPI_HID) {
; #pragma unroll
;             for (int j = 0; j < 4; ++j) { const float a1 = acc[ai][0][m][n][j], a3 = acc[ai][1][m][n][j]; v[j] = a1 * sigm(a1) * a3; }
;           }
;           float lo[2], hi[2];
;           xchg_pairs(v, odd, lo, hi);
; #pragma unroll
;           for (int k = 0; k < 2; ++k) {
;             const unsigned row = (unsigned)(rA + k);
;             if (EPI == EPI_HID) {
;               *(unsigned*)(ws + O_HID + (row * 1024u + (unsigned)(colp + cc)) * 2u) = pk2(lo[k], hi[k]);
;             } else if (EPI == EPI_COLS) {
;               *(unsigned*)(ws + O_COLS + (row * (unsigned)NCP + (unsigned)(colp + cc)) * 2u) = pk2(lo[k], hi[k]);
;             } else if (EPI == EPI_MOE2) {
;               *(unsigned*)(ws + O_EO + (row * 2048u + (unsigned)(colp + cc)) * 2u) = pk2(gate[k] * lo[k], gate[k] * hi[k]);
;             } else if (EPI == EPI_M1) {
;               const unsigned g2 = *(const unsigned*)(ws + O_COLS + (row * (unsigned)NCP + (unsigned)(C_GG + colp + cc)) * 2u);
;               *(unsigned*)(ws + O_M1 + (row * 2048u + (unsigned)(colp + cc)) * 2u) = pk2(sigm(bflo(g2)) * lo[k], sigm(bfhi(g2)) * hi[k]);
	v_lshlrev_b32_e32 v71, 16, v150
	v_and_b32_e32 v67, 0xffff0000, v150
	v_mul_f32_e32 v71, 0xbfb8aa3b, v71
	v_mul_f32_e32 v67, 0xbfb8aa3b, v67
	v_exp_f32_e32 v71, v71
	v_exp_f32_e32 v67, v67
	v_add_f32_e32 v68, 1.0, v71
	v_add_f32_e32 v67, 1.0, v67
	v_div_scale_f32 v71, s[0:1], v68, v68, 1.0
	v_div_scale_f32 v73, s[0:1], v67, v67, 1.0
	v_rcp_f32_e32 v74, v71
	v_rcp_f32_e32 v75, v73
	v_div_scale_f32 v72, vcc, 1.0, v68, 1.0
	v_fma_f32 v77, -v71, v74, 1.0
	v_fma_f32 v78, -v73, v75, 1.0
	v_fmac_f32_e32 v74, v77, v74
	v_div_scale_f32 v76, s[0:1], 1.0, v67, 1.0
	v_fmac_f32_e32 v75, v78, v75
	v_mul_f32_e32 v77, v72, v74
	v_mul_f32_e32 v78, v76, v75
	v_fma_f32 v79, -v71, v77, v72
	v_fma_f32 v80, -v73, v78, v76
	v_fmac_f32_e32 v77, v79, v74
	v_fmac_f32_e32 v78, v80, v75
	v_fma_f32 v71, -v71, v77, v72
	v_fma_f32 v72, -v73, v78, v76
	v_div_fmas_f32 v71, v71, v74, v77
	s_mov_b64 vcc, s[0:1]
	v_div_fixup_f32 v68, v71, v68, 1.0
	v_div_fmas_f32 v71, v72, v75, v78
	v_div_fixup_f32 v67, v71, v67, 1.0
	v_mul_f32_e32 v60, v60, v68
	v_mul_f32_e32 v62, v62, v67
	v_cvt_pk_bf16_f32 v60, v60, v62
	global_store_dword v69, v60, s[10:11]
	s_nop 0
	v_cndmask_b32_e64 v67, v61, v63, s[6:7]
	v_add_u32_e32 v60, 0x81000, v128
	v_add_u32_e32 v68, v60, v124
	v_mov_b32_dpp v67, v67 quad_perm:[1,0,3,2] row_mask:0xf bank_mask:0xf bound_ctrl:1
	v_cndmask_b32_e64 v61, v67, v61, s[6:7]
	v_cndmask_b32_e64 v63, v63, v67, s[6:7]
	v_add_lshl_u32 v69, v66, v126, 1
	s_waitcnt vmcnt(55)
	v_lshlrev_b32_e32 v70, 16, v151
	v_and_b32_e32 v62, 0xffff0000, v151
	v_mul_f32_e32 v70, 0xbfb8aa3b, v70
	v_mul_f32_e32 v62, 0xbfb8aa3b, v62
	v_exp_f32_e32 v70, v70
	v_exp_f32_e32 v62, v62
	v_add_f32_e32 v67, 1.0, v70
	v_add_f32_e32 v62, 1.0, v62
	v_div_scale_f32 v70, s[0:1], v67, v67, 1.0
	v_div_scale_f32 v72, s[0:1], v62, v62, 1.0
	v_rcp_f32_e32 v73, v70
	v_rcp_f32_e32 v74, v72
	v_div_scale_f32 v71, vcc, 1.0, v67, 1.0
	v_fma_f32 v76, -v70, v73, 1.0
	v_fma_f32 v77, -v72, v74, 1.0
	v_fmac_f32_e32 v73, v76, v73
	v_div_scale_f32 v75, s[0:1], 1.0, v62, 1.0
	v_fmac_f32_e32 v74, v77, v74
	v_mul_f32_e32 v76, v71, v73
	v_mul_f32_e32 v77, v75, v74
	v_fma_f32 v78, -v70, v76, v71
	v_fma_f32 v79, -v72, v77, v75
	v_fmac_f32_e32 v76, v78, v73
	v_fmac_f32_e32 v77, v79, v74
	v_fma_f32 v70, -v70, v76, v71
	v_fma_f32 v71, -v72, v77, v75
	v_div_fmas_f32 v70, v70, v73, v76
	s_mov_b64 vcc, s[0:1]
	v_div_fixup_f32 v67, v70, v67, 1.0
	v_div_fmas_f32 v70, v71, v74, v77
	v_div_fixup_f32 v62, v70, v62, 1.0
	v_mul_f32_e32 v61, v61, v67
	v_mul_f32_e32 v62, v63, v62
	v_cvt_pk_bf16_f32 v61, v61, v62
	global_store_dword v68, v61, s[10:11]
	s_nop 0
	v_cndmask_b32_e64 v62, v56, v58, s[6:7]
	v_add_u32_e32 v63, v64, v120
	v_add_lshl_u32 v67, v65, v126, 1
	v_mov_b32_dpp v62, v62 quad_perm:[1,0,3,2] row_mask:0xf bank_mask:0xf bound_ctrl:1
	v_cndmask_b32_e64 v56, v62, v56, s[6:7]
	v_cndmask_b32_e64 v58, v58, v62, s[6:7]
	s_waitcnt vmcnt(55)
	v_lshlrev_b32_e32 v68, 16, v152
	v_and_b32_e32 v61, 0xffff0000, v152
	v_mul_f32_e32 v68, 0xbfb8aa3b, v68
	v_mul_f32_e32 v61, 0xbfb8aa3b, v61
	v_exp_f32_e32 v68, v68
	v_exp_f32_e32 v61, v61
	v_add_f32_e32 v62, 1.0, v68
	v_add_f32_e32 v61, 1.0, v61
	v_div_scale_f32 v68, s[0:1], v62, v62, 1.0
	v_div_scale_f32 v70, s[0:1], v61, v61, 1.0
	v_rcp_f32_e32 v71, v68
	v_rcp_f32_e32 v72, v70
	v_div_scale_f32 v69, vcc, 1.0, v62, 1.0
	v_fma_f32 v74, -v68, v71, 1.0
	v_fma_f32 v75, -v70, v72, 1.0
	v_fmac_f32_e32 v71, v74, v71
	v_div_scale_f32 v73, s[0:1], 1.0, v61, 1.0
	v_fmac_f32_e32 v72, v75, v72
	v_mul_f32_e32 v74, v69, v71
	v_mul_f32_e32 v75, v73, v72
	v_fma_f32 v76, -v68, v74, v69
	v_fma_f32 v77, -v70, v75, v73
	v_fmac_f32_e32 v74, v76, v71
	v_fmac_f32_e32 v75, v77, v72
	v_fma_f32 v68, -v68, v74, v69
	v_fma_f32 v69, -v70, v75, v73
	v_div_fmas_f32 v68, v68, v71, v74
	s_mov_b64 vcc, s[0:1]
	v_div_fixup_f32 v62, v68, v62, 1.0
	v_div_fmas_f32 v68, v69, v72, v75
	v_div_fixup_f32 v61, v68, v61, 1.0
	v_mul_f32_e32 v56, v56, v62
	v_mul_f32_e32 v58, v58, v61
	v_cvt_pk_bf16_f32 v56, v56, v58
	global_store_dword v63, v56, s[10:11]
	s_nop 0
	v_cndmask_b32_e64 v58, v57, v59, s[6:7]
	v_add_u32_e32 v61, v60, v120
	v_add_lshl_u32 v62, v66, v122, 1
	v_mov_b32_dpp v58, v58 quad_perm:[1,0,3,2] row_mask:0xf bank_mask:0xf bound_ctrl:1
	v_cndmask_b32_e64 v57, v58, v57, s[6:7]
	v_cndmask_b32_e64 v58, v59, v58, s[6:7]
	s_waitcnt vmcnt(55)
	v_lshlrev_b32_e32 v63, 16, v153
	v_and_b32_e32 v56, 0xffff0000, v153
	v_mul_f32_e32 v63, 0xbfb8aa3b, v63
	v_mul_f32_e32 v56, 0xbfb8aa3b, v56
	v_exp_f32_e32 v63, v63
	v_exp_f32_e32 v56, v56
	v_add_f32_e32 v59, 1.0, v63
	v_add_f32_e32 v56, 1.0, v56
	v_div_scale_f32 v63, s[0:1], v59, v59, 1.0
	v_div_scale_f32 v68, s[0:1], v56, v56, 1.0
	v_rcp_f32_e32 v69, v63
	v_rcp_f32_e32 v70, v68
	v_div_scale_f32 v67, vcc, 1.0, v59, 1.0
	v_fma_f32 v72, -v63, v69, 1.0
	v_fma_f32 v73, -v68, v70, 1.0
	v_fmac_f32_e32 v69, v72, v69
	v_div_scale_f32 v71, s[0:1], 1.0, v56, 1.0
	v_fmac_f32_e32 v70, v73, v70
	v_mul_f32_e32 v72, v67, v69
	v_mul_f32_e32 v73, v71, v70
	v_fma_f32 v74, -v63, v72, v67
	v_fma_f32 v75, -v68, v73, v71
	v_fmac_f32_e32 v72, v74, v69
	v_fmac_f32_e32 v73, v75, v70
	v_fma_f32 v63, -v63, v72, v67
	v_fma_f32 v67, -v68, v73, v71
	v_div_fmas_f32 v63, v63, v69, v72
	s_mov_b64 vcc, s[0:1]
	v_div_fixup_f32 v59, v63, v59, 1.0
	v_div_fmas_f32 v63, v67, v70, v73
	v_div_fixup_f32 v56, v63, v56, 1.0
	v_mul_f32_e32 v57, v57, v59
	v_mul_f32_e32 v56, v58, v56
	v_cvt_pk_bf16_f32 v56, v57, v56
	global_store_dword v61, v56, s[10:11]
	s_nop 0
	v_cndmask_b32_e64 v57, v52, v54, s[6:7]
	v_add_u32_e32 v58, v64, v118
	v_add_lshl_u32 v59, v65, v122, 1
	v_mov_b32_dpp v57, v57 quad_perm:[1,0,3,2] row_mask:0xf bank_mask:0xf bound_ctrl:1
	v_cndmask_b32_e64 v52, v57, v52, s[6:7]
	v_cndmask_b32_e64 v54, v54, v57, s[6:7]
	s_waitcnt vmcnt(55)
; DEVINL float bflo(unsigned u) { return __uint_as_float(u << 16); }
; DEVINL float bfhi(unsigned u) { return __uint_as_float(u & 0xffff0000u); }
; DEVINL float sigm(float x) { return 1.f / (1.f + __expf(-x)); }
; template <int EPI, bool GATHER>
; DEVINL void gemm_tile(const Params& p, const u16* __restrict__ A, int lda, const int* __restrict__ rowidx,
;                       const u16* __restrict__ Bt, int ldb, int K, int brow, int bcol, int orow, int ocol) {
;     ...
;       const int rA = row0 + ai * HALF + m * 16 + (odd ? 2 : 0);
;       float gate[2] = {0.f, 0.f};
;       if (EPI == EPI_MOE2) { gate[0] = ((const float*)(ws + O_SELG))[rA]; gate[1] = ((const float*)(ws + O_SELG))[rA + 1]; }
; #pragma unroll
;       for (int bj = 0; bj < (EPI == EPI_HID ? 1 : 2); ++bj)
; #pragma unroll
;         for (int n = 0; n < 2; ++n) {
;           const int cc = bj * HALF + n * 16;
;           f32x4 v = acc[ai][bj][m][n];
;           if (EPI == EPI_HID) {
; #pragma unroll
;             for (int j = 0; j < 4; ++j) { const float a1 = acc[ai][0][m][n][j], a3 = acc[ai][1][m][n][j]; v[j] = a1 * sigm(a1) * a3; }
;           }
;           float lo[2], hi[2];
;           xchg_pairs(v, odd, lo, hi);
; #pragma unroll
;           for (int k = 0; k < 2; ++k) {
;             const unsigned row = (unsigned)(rA + k);
;             if (EPI == EPI_HID) {
;               *(unsigned*)(ws + O_HID + (row * 1024u + (unsigned)(colp + cc)) * 2u) = pk2(lo[k], hi[k]);
;             } else if (EPI == EPI_COLS) {
;               *(unsigned*)(ws + O_COLS + (row * (unsigned)NCP + (unsigned)(colp + cc)) * 2u) = pk2(lo[k], hi[k]);
;             } else if (EPI == EPI_MOE2) {
;               *(unsigned*)(ws + O_EO + (row * 2048u + (unsigned)(colp + cc)) * 2u) = pk2(gate[k] * lo[k], gate[k] * hi[k]);
;             } else if (EPI == EPI_M1) {
;               const unsigned g2 = *(const unsigned*)(ws + O_COLS + (row * (unsigned)NCP + (unsigned)(C_GG + colp + cc)) * 2u);
;               *(unsigned*)(ws + O_M1 + (row * 2048u + (unsigned)(colp + cc)) * 2u) = pk2(sigm(bflo(g2)) * lo[k], sigm(bfhi(g2)) * hi[k]);
	v_lshlrev_b32_e32 v61, 16, v154
	v_and_b32_e32 v56, 0xffff0000, v154
	v_mul_f32_e32 v61, 0xbfb8aa3b, v61
	v_mul_f32_e32 v56, 0xbfb8aa3b, v56
	v_exp_f32_e32 v61, v61
	v_exp_f32_e32 v56, v56
	v_add_f32_e32 v57, 1.0, v61
	v_add_f32_e32 v56, 1.0, v56
	v_div_scale_f32 v61, s[0:1], v57, v57, 1.0
	v_div_scale_f32 v63, s[0:1], v56, v56, 1.0
	v_rcp_f32_e32 v67, v61
	v_rcp_f32_e32 v68, v63
	v_div_scale_f32 v62, vcc, 1.0, v57, 1.0
	v_fma_f32 v70, -v61, v67, 1.0
	v_fma_f32 v71, -v63, v68, 1.0
	v_fmac_f32_e32 v67, v70, v67
	v_div_scale_f32 v69, s[0:1], 1.0, v56, 1.0
	v_fmac_f32_e32 v68, v71, v68
	v_mul_f32_e32 v70, v62, v67
	v_mul_f32_e32 v71, v69, v68
	v_fma_f32 v72, -v61, v70, v62
	v_fma_f32 v73, -v63, v71, v69
	v_fmac_f32_e32 v70, v72, v67
	v_fmac_f32_e32 v71, v73, v68
	v_fma_f32 v61, -v61, v70, v62
	v_fma_f32 v62, -v63, v71, v69
	v_div_fmas_f32 v61, v61, v67, v70
	s_mov_b64 vcc, s[0:1]
	v_div_fixup_f32 v57, v61, v57, 1.0
	v_div_fmas_f32 v61, v62, v68, v71
	v_div_fixup_f32 v56, v61, v56, 1.0
	v_mul_f32_e32 v52, v52, v57
	v_mul_f32_e32 v54, v54, v56
	v_cvt_pk_bf16_f32 v52, v52, v54
	global_store_dword v58, v52, s[10:11]
	s_nop 0
	v_cndmask_b32_e64 v54, v53, v55, s[6:7]
	v_add_lshl_u32 v57, v66, v116, 1
	v_add_u32_e32 v56, v60, v118
	v_mov_b32_dpp v54, v54 quad_perm:[1,0,3,2] row_mask:0xf bank_mask:0xf bound_ctrl:1
	v_cndmask_b32_e64 v53, v54, v53, s[6:7]
	v_cndmask_b32_e64 v54, v55, v54, s[6:7]
	s_waitcnt vmcnt(55)
	v_lshlrev_b32_e32 v58, 16, v155
	v_and_b32_e32 v52, 0xffff0000, v155
	v_mul_f32_e32 v58, 0xbfb8aa3b, v58
	v_mul_f32_e32 v52, 0xbfb8aa3b, v52
	v_exp_f32_e32 v58, v58
	v_exp_f32_e32 v52, v52
	v_add_f32_e32 v55, 1.0, v58
	v_add_f32_e32 v52, 1.0, v52
	v_div_scale_f32 v58, s[0:1], v55, v55, 1.0
	v_div_scale_f32 v61, s[0:1], v52, v52, 1.0
	v_rcp_f32_e32 v62, v58
	v_rcp_f32_e32 v63, v61
	v_div_scale_f32 v59, vcc, 1.0, v55, 1.0
	v_fma_f32 v67, -v58, v62, 1.0
	v_fma_f32 v68, -v61, v63, 1.0
	v_fmac_f32_e32 v62, v67, v62
	v_div_scale_f32 v66, s[0:1], 1.0, v52, 1.0
	v_fmac_f32_e32 v63, v68, v63
	v_mul_f32_e32 v67, v59, v62
	v_mul_f32_e32 v68, v66, v63
	v_fma_f32 v69, -v58, v67, v59
	v_fma_f32 v70, -v61, v68, v66
	v_fmac_f32_e32 v67, v69, v62
	v_fmac_f32_e32 v68, v70, v63
	v_fma_f32 v58, -v58, v67, v59
	v_fma_f32 v59, -v61, v68, v66
	v_div_fmas_f32 v58, v58, v62, v67
	s_mov_b64 vcc, s[0:1]
	v_div_fixup_f32 v55, v58, v55, 1.0
	v_div_fmas_f32 v58, v59, v63, v68
	v_div_fixup_f32 v52, v58, v52, 1.0
	v_mul_f32_e32 v53, v53, v55
	v_mul_f32_e32 v52, v54, v52
	v_cvt_pk_bf16_f32 v52, v53, v52
	global_store_dword v56, v52, s[10:11]
	s_nop 0
	v_cndmask_b32_e64 v53, v48, v50, s[6:7]
	v_add_u32_e32 v54, v64, v112
	v_add_lshl_u32 v55, v65, v116, 1
	v_mov_b32_dpp v53, v53 quad_perm:[1,0,3,2] row_mask:0xf bank_mask:0xf bound_ctrl:1
	v_cndmask_b32_e64 v48, v53, v48, s[6:7]
	v_cndmask_b32_e64 v50, v50, v53, s[6:7]
	s_waitcnt vmcnt(55)
	v_lshlrev_b32_e32 v56, 16, v156
	v_and_b32_e32 v52, 0xffff0000, v156
	v_mul_f32_e32 v56, 0xbfb8aa3b, v56
	v_mul_f32_e32 v52, 0xbfb8aa3b, v52
	v_exp_f32_e32 v56, v56
	v_exp_f32_e32 v52, v52
	v_add_f32_e32 v53, 1.0, v56
	v_add_f32_e32 v52, 1.0, v52
	v_div_scale_f32 v56, s[0:1], v53, v53, 1.0
	v_div_scale_f32 v58, s[0:1], v52, v52, 1.0
	v_rcp_f32_e32 v59, v56
	v_rcp_f32_e32 v61, v58
	v_div_scale_f32 v57, vcc, 1.0, v53, 1.0
	v_fma_f32 v63, -v56, v59, 1.0
	v_fma_f32 v64, -v58, v61, 1.0
	v_fmac_f32_e32 v59, v63, v59
	v_div_scale_f32 v62, s[0:1], 1.0, v52, 1.0
	v_fmac_f32_e32 v61, v64, v61
	v_mul_f32_e32 v63, v57, v59
	v_mul_f32_e32 v64, v62, v61
	v_fma_f32 v65, -v56, v63, v57
	v_fma_f32 v66, -v58, v64, v62
	v_fmac_f32_e32 v63, v65, v59
	v_fmac_f32_e32 v64, v66, v61
	v_fma_f32 v56, -v56, v63, v57
	v_fma_f32 v57, -v58, v64, v62
	v_div_fmas_f32 v56, v56, v59, v63
	s_mov_b64 vcc, s[0:1]
	v_div_fixup_f32 v53, v56, v53, 1.0
	v_div_fmas_f32 v56, v57, v61, v64
	v_div_fixup_f32 v52, v56, v52, 1.0
	v_mul_f32_e32 v48, v48, v53
	v_mul_f32_e32 v50, v50, v52
	v_cvt_pk_bf16_f32 v48, v48, v50
	global_store_dword v54, v48, s[10:11]
	s_nop 0
	v_cndmask_b32_e64 v50, v49, v51, s[6:7]
	s_waitcnt vmcnt(55)
	v_lshlrev_b32_e32 v52, 16, v157
	v_and_b32_e32 v48, 0xffff0000, v157
	v_mul_f32_e32 v52, 0xbfb8aa3b, v52
	v_mul_f32_e32 v48, 0xbfb8aa3b, v48
	v_exp_f32_e32 v52, v52
	v_exp_f32_e32 v48, v48
	v_mov_b32_dpp v50, v50 quad_perm:[1,0,3,2] row_mask:0xf bank_mask:0xf bound_ctrl:1
	v_cndmask_b32_e64 v49, v50, v49, s[6:7]
	v_cndmask_b32_e64 v50, v51, v50, s[6:7]
	v_add_f32_e32 v51, 1.0, v52
	v_add_f32_e32 v48, 1.0, v48
	v_div_scale_f32 v52, s[0:1], v51, v51, 1.0
	v_div_scale_f32 v54, s[0:1], v48, v48, 1.0
	v_rcp_f32_e32 v55, v52
	v_rcp_f32_e32 v56, v54
	v_div_scale_f32 v53, vcc, 1.0, v51, 1.0
	v_fma_f32 v58, -v52, v55, 1.0
	v_fma_f32 v59, -v54, v56, 1.0
	v_fmac_f32_e32 v55, v58, v55
	v_div_scale_f32 v57, s[0:1], 1.0, v48, 1.0
	v_fmac_f32_e32 v56, v59, v56
	v_mul_f32_e32 v58, v53, v55
	v_mul_f32_e32 v59, v57, v56
	v_fma_f32 v61, -v52, v58, v53
	v_fma_f32 v62, -v54, v59, v57
	v_fmac_f32_e32 v58, v61, v55
	v_fmac_f32_e32 v59, v62, v56
	v_fma_f32 v52, -v52, v58, v53
	v_fma_f32 v53, -v54, v59, v57
	v_div_fmas_f32 v52, v52, v55, v58
	s_mov_b64 vcc, s[0:1]
	v_div_fixup_f32 v51, v52, v51, 1.0
	v_div_fmas_f32 v52, v53, v56, v59
	v_div_fixup_f32 v48, v52, v48, 1.0
	v_mul_f32_e32 v49, v49, v51
	v_mul_f32_e32 v48, v50, v48
	v_cvt_pk_bf16_f32 v48, v49, v48
	v_add_u32_e32 v49, v60, v112
	global_store_dword v49, v48, s[10:11]
	v_add_u32_e32 v50, 0x150000, v113
	v_add_lshl_u32 v48, v50, v129, 1
	s_nop 0
	v_cndmask_b32_e64 v52, v44, v46, s[6:7]
	v_add_u32_e32 v48, 0x90000, v128
	v_add_u32_e32 v49, 0x152a00, v113
	v_mov_b32_dpp v52, v52 quad_perm:[1,0,3,2] row_mask:0xf bank_mask:0xf bound_ctrl:1
	v_cndmask_b32_e64 v44, v52, v44, s[6:7]
	v_cndmask_b32_e64 v46, v46, v52, s[6:7]
	v_add_u32_e32 v53, v48, v124
	v_add_lshl_u32 v54, v49, v129, 1
	s_waitcnt vmcnt(47)
; DEVINL float bflo(unsigned u) { return __uint_as_float(u << 16); }
; DEVINL float bfhi(unsigned u) { return __uint_as_float(u & 0xffff0000u); }
; DEVINL float sigm(float x) { return 1.f / (1.f + __expf(-x)); }
; template <int EPI, bool GATHER>
; DEVINL void gemm_tile(const Params& p, const u16* __restrict__ A, int lda, const int* __restrict__ rowidx,
;                       const u16* __restrict__ Bt, int ldb, int K, int brow, int bcol, int orow, int ocol) {
;     ...
;       const int rA = row0 + ai * HALF + m * 16 + (odd ? 2 : 0);
;       float gate[2] = {0.f, 0.f};
;       if (EPI == EPI_MOE2) { gate[0] = ((const float*)(ws + O_SELG))[rA]; gate[1] = ((const float*)(ws + O_SELG))[rA + 1]; }
; #pragma unroll
;       for (int bj = 0; bj < (EPI == EPI_HID ? 1 : 2); ++bj)
; #pragma unroll
;         for (int n = 0; n < 2; ++n) {
;           const int cc = bj * HALF + n * 16;
;           f32x4 v = acc[ai][bj][m][n];
;           if (EPI == EPI_HID) {
; #pragma unroll
;             for (int j = 0; j < 4; ++j) { const float a1 = acc[ai][0][m][n][j], a3 = acc[ai][1][m][n][j]; v[j] = a1 * sigm(a1) * a3; }
;           }
;           float lo[2], hi[2];
;           xchg_pairs(v, odd, lo, hi);
; #pragma unroll
;           for (int k = 0; k < 2; ++k) {
;             const unsigned row = (unsigned)(rA + k);
;             if (EPI == EPI_HID) {
;               *(unsigned*)(ws + O_HID + (row * 1024u + (unsigned)(colp + cc)) * 2u) = pk2(lo[k], hi[k]);
;             } else if (EPI == EPI_COLS) {
;               *(unsigned*)(ws + O_COLS + (row * (unsigned)NCP + (unsigned)(colp + cc)) * 2u) = pk2(lo[k], hi[k]);
;             } else if (EPI == EPI_MOE2) {
;               *(unsigned*)(ws + O_EO + (row * 2048u + (unsigned)(colp + cc)) * 2u) = pk2(gate[k] * lo[k], gate[k] * hi[k]);
;             } else if (EPI == EPI_M1) {
;               const unsigned g2 = *(const unsigned*)(ws + O_COLS + (row * (unsigned)NCP + (unsigned)(C_GG + colp + cc)) * 2u);
;               *(unsigned*)(ws + O_M1 + (row * 2048u + (unsigned)(colp + cc)) * 2u) = pk2(sigm(bflo(g2)) * lo[k], sigm(bfhi(g2)) * hi[k]);
	v_lshlrev_b32_e32 v55, 16, v166
	v_and_b32_e32 v51, 0xffff0000, v166
	v_mul_f32_e32 v55, 0xbfb8aa3b, v55
	v_mul_f32_e32 v51, 0xbfb8aa3b, v51
	v_exp_f32_e32 v55, v55
	v_exp_f32_e32 v51, v51
	v_add_f32_e32 v52, 1.0, v55
	v_add_f32_e32 v51, 1.0, v51
	v_div_scale_f32 v55, s[0:1], v52, v52, 1.0
	v_div_scale_f32 v57, s[0:1], v51, v51, 1.0
	v_rcp_f32_e32 v58, v55
	v_rcp_f32_e32 v59, v57
	v_div_scale_f32 v56, vcc, 1.0, v52, 1.0
	v_fma_f32 v61, -v55, v58, 1.0
	v_fma_f32 v62, -v57, v59, 1.0
	v_fmac_f32_e32 v58, v61, v58
	v_div_scale_f32 v60, s[0:1], 1.0, v51, 1.0
	v_fmac_f32_e32 v59, v62, v59
	v_mul_f32_e32 v61, v56, v58
	v_mul_f32_e32 v62, v60, v59
	v_fma_f32 v63, -v55, v61, v56
	v_fma_f32 v64, -v57, v62, v60
	v_fmac_f32_e32 v61, v63, v58
	v_fmac_f32_e32 v62, v64, v59
	v_fma_f32 v55, -v55, v61, v56
	v_fma_f32 v56, -v57, v62, v60
	v_div_fmas_f32 v55, v55, v58, v61
	s_mov_b64 vcc, s[0:1]
	v_div_fixup_f32 v52, v55, v52, 1.0
	v_div_fmas_f32 v55, v56, v59, v62
	v_div_fixup_f32 v51, v55, v51, 1.0
	v_mul_f32_e32 v44, v44, v52
	v_mul_f32_e32 v46, v46, v51
	v_cvt_pk_bf16_f32 v44, v44, v46
	global_store_dword v53, v44, s[10:11]
	s_nop 0
	v_cndmask_b32_e64 v51, v45, v47, s[6:7]
	v_add_u32_e32 v44, 0x91000, v128
	v_add_u32_e32 v52, v44, v124
	v_mov_b32_dpp v51, v51 quad_perm:[1,0,3,2] row_mask:0xf bank_mask:0xf bound_ctrl:1
	v_cndmask_b32_e64 v45, v51, v45, s[6:7]
	v_cndmask_b32_e64 v47, v47, v51, s[6:7]
	v_add_lshl_u32 v53, v50, v126, 1
	s_waitcnt vmcnt(47)
	v_lshlrev_b32_e32 v54, 16, v167
	v_and_b32_e32 v46, 0xffff0000, v167
	v_mul_f32_e32 v54, 0xbfb8aa3b, v54
	v_mul_f32_e32 v46, 0xbfb8aa3b, v46
	v_exp_f32_e32 v54, v54
	v_exp_f32_e32 v46, v46
	v_add_f32_e32 v51, 1.0, v54
	v_add_f32_e32 v46, 1.0, v46
	v_div_scale_f32 v54, s[0:1], v51, v51, 1.0
	v_div_scale_f32 v56, s[0:1], v46, v46, 1.0
	v_rcp_f32_e32 v57, v54
	v_rcp_f32_e32 v58, v56
	v_div_scale_f32 v55, vcc, 1.0, v51, 1.0
	v_fma_f32 v60, -v54, v57, 1.0
	v_fma_f32 v61, -v56, v58, 1.0
	v_fmac_f32_e32 v57, v60, v57
	v_div_scale_f32 v59, s[0:1], 1.0, v46, 1.0
	v_fmac_f32_e32 v58, v61, v58
	v_mul_f32_e32 v60, v55, v57
	v_mul_f32_e32 v61, v59, v58
	v_fma_f32 v62, -v54, v60, v55
	v_fma_f32 v63, -v56, v61, v59
	v_fmac_f32_e32 v60, v62, v57
	v_fmac_f32_e32 v61, v63, v58
	v_fma_f32 v54, -v54, v60, v55
	v_fma_f32 v55, -v56, v61, v59
	v_div_fmas_f32 v54, v54, v57, v60
	s_mov_b64 vcc, s[0:1]
	v_div_fixup_f32 v51, v54, v51, 1.0
	v_div_fmas_f32 v54, v55, v58, v61
	v_div_fixup_f32 v46, v54, v46, 1.0
	v_mul_f32_e32 v45, v45, v51
	v_mul_f32_e32 v46, v47, v46
	v_cvt_pk_bf16_f32 v45, v45, v46
	global_store_dword v52, v45, s[10:11]
	s_nop 0
	v_cndmask_b32_e64 v46, v40, v42, s[6:7]
	v_add_u32_e32 v47, v48, v120
	v_add_lshl_u32 v51, v49, v126, 1
	v_mov_b32_dpp v46, v46 quad_perm:[1,0,3,2] row_mask:0xf bank_mask:0xf bound_ctrl:1
	v_cndmask_b32_e64 v40, v46, v40, s[6:7]
	v_cndmask_b32_e64 v42, v42, v46, s[6:7]
	s_waitcnt vmcnt(47)
	v_lshlrev_b32_e32 v52, 16, v168
	v_and_b32_e32 v45, 0xffff0000, v168
	v_mul_f32_e32 v52, 0xbfb8aa3b, v52
	v_mul_f32_e32 v45, 0xbfb8aa3b, v45
	v_exp_f32_e32 v52, v52
	v_exp_f32_e32 v45, v45
	v_add_f32_e32 v46, 1.0, v52
	v_add_f32_e32 v45, 1.0, v45
	v_div_scale_f32 v52, s[0:1], v46, v46, 1.0
	v_div_scale_f32 v54, s[0:1], v45, v45, 1.0
	v_rcp_f32_e32 v55, v52
	v_rcp_f32_e32 v56, v54
	v_div_scale_f32 v53, vcc, 1.0, v46, 1.0
	v_fma_f32 v58, -v52, v55, 1.0
	v_fma_f32 v59, -v54, v56, 1.0
	v_fmac_f32_e32 v55, v58, v55
	v_div_scale_f32 v57, s[0:1], 1.0, v45, 1.0
	v_fmac_f32_e32 v56, v59, v56
	v_mul_f32_e32 v58, v53, v55
	v_mul_f32_e32 v59, v57, v56
	v_fma_f32 v60, -v52, v58, v53
	v_fma_f32 v61, -v54, v59, v57
	v_fmac_f32_e32 v58, v60, v55
	v_fmac_f32_e32 v59, v61, v56
	v_fma_f32 v52, -v52, v58, v53
	v_fma_f32 v53, -v54, v59, v57
	v_div_fmas_f32 v52, v52, v55, v58
	s_mov_b64 vcc, s[0:1]
	v_div_fixup_f32 v46, v52, v46, 1.0
	v_div_fmas_f32 v52, v53, v56, v59
	v_div_fixup_f32 v45, v52, v45, 1.0
	v_mul_f32_e32 v40, v40, v46
	v_mul_f32_e32 v42, v42, v45
	v_cvt_pk_bf16_f32 v40, v40, v42
	global_store_dword v47, v40, s[10:11]
	s_nop 0
	v_cndmask_b32_e64 v42, v41, v43, s[6:7]
	v_add_u32_e32 v45, v44, v120
	v_add_lshl_u32 v46, v50, v122, 1
	v_mov_b32_dpp v42, v42 quad_perm:[1,0,3,2] row_mask:0xf bank_mask:0xf bound_ctrl:1
	v_cndmask_b32_e64 v41, v42, v41, s[6:7]
	v_cndmask_b32_e64 v42, v43, v42, s[6:7]
	s_waitcnt vmcnt(47)
	v_lshlrev_b32_e32 v47, 16, v169
	v_and_b32_e32 v40, 0xffff0000, v169
	v_mul_f32_e32 v47, 0xbfb8aa3b, v47
	v_mul_f32_e32 v40, 0xbfb8aa3b, v40
	v_exp_f32_e32 v47, v47
	v_exp_f32_e32 v40, v40
	v_add_f32_e32 v43, 1.0, v47
	v_add_f32_e32 v40, 1.0, v40
	v_div_scale_f32 v47, s[0:1], v43, v43, 1.0
	v_div_scale_f32 v52, s[0:1], v40, v40, 1.0
	v_rcp_f32_e32 v53, v47
	v_rcp_f32_e32 v54, v52
	v_div_scale_f32 v51, vcc, 1.0, v43, 1.0
	v_fma_f32 v56, -v47, v53, 1.0
	v_fma_f32 v57, -v52, v54, 1.0
	v_fmac_f32_e32 v53, v56, v53
	v_div_scale_f32 v55, s[0:1], 1.0, v40, 1.0
	v_fmac_f32_e32 v54, v57, v54
	v_mul_f32_e32 v56, v51, v53
	v_mul_f32_e32 v57, v55, v54
	v_fma_f32 v58, -v47, v56, v51
	v_fma_f32 v59, -v52, v57, v55
	v_fmac_f32_e32 v56, v58, v53
	v_fmac_f32_e32 v57, v59, v54
	v_fma_f32 v47, -v47, v56, v51
	v_fma_f32 v51, -v52, v57, v55
	v_div_fmas_f32 v47, v47, v53, v56
	s_mov_b64 vcc, s[0:1]
	v_div_fixup_f32 v43, v47, v43, 1.0
	v_div_fmas_f32 v47, v51, v54, v57
	v_div_fixup_f32 v40, v47, v40, 1.0
	v_mul_f32_e32 v41, v41, v43
	v_mul_f32_e32 v40, v42, v40
	v_cvt_pk_bf16_f32 v40, v41, v40
	global_store_dword v45, v40, s[10:11]
	s_nop 0
	v_cndmask_b32_e64 v41, v36, v38, s[6:7]
	v_add_u32_e32 v42, v48, v118
	v_add_lshl_u32 v43, v49, v122, 1
	v_mov_b32_dpp v41, v41 quad_perm:[1,0,3,2] row_mask:0xf bank_mask:0xf bound_ctrl:1
	v_cndmask_b32_e64 v36, v41, v36, s[6:7]
	v_cndmask_b32_e64 v38, v38, v41, s[6:7]
	s_waitcnt vmcnt(47)
; DEVINL float bflo(unsigned u) { return __uint_as_float(u << 16); }
; DEVINL float bfhi(unsigned u) { return __uint_as_float(u & 0xffff0000u); }
; DEVINL float sigm(float x) { return 1.f / (1.f + __expf(-x)); }
; template <int EPI, bool GATHER>
; DEVINL void gemm_tile(const Params& p, const u16* __restrict__ A, int lda, const int* __restrict__ rowidx,
;                       const u16* __restrict__ Bt, int ldb, int K, int brow, int bcol, int orow, int ocol) {
;     ...
;       const int rA = row0 + ai * HALF + m * 16 + (odd ? 2 : 0);
;       float gate[2] = {0.f, 0.f};
;       if (EPI == EPI_MOE2) { gate[0] = ((const float*)(ws + O_SELG))[rA]; gate[1] = ((const float*)(ws + O_SELG))[rA + 1]; }
; #pragma unroll
;       for (int bj = 0; bj < (EPI == EPI_HID ? 1 : 2); ++bj)
; #pragma unroll
;         for (int n = 0; n < 2; ++n) {
;           const int cc = bj * HALF + n * 16;
;           f32x4 v = acc[ai][bj][m][n];
;           if (EPI == EPI_HID) {
; #pragma unroll
;             for (int j = 0; j < 4; ++j) { const float a1 = acc[ai][0][m][n][j], a3 = acc[ai][1][m][n][j]; v[j] = a1 * sigm(a1) * a3; }
;           }
;           float lo[2], hi[2];
;           xchg_pairs(v, odd, lo, hi);
; #pragma unroll
;           for (int k = 0; k < 2; ++k) {
;             const unsigned row = (unsigned)(rA + k);
;             if (EPI == EPI_HID) {
;               *(unsigned*)(ws + O_HID + (row * 1024u + (unsigned)(colp + cc)) * 2u) = pk2(lo[k], hi[k]);
;             } else if (EPI == EPI_COLS) {
;               *(unsigned*)(ws + O_COLS + (row * (unsigned)NCP + (unsigned)(colp + cc)) * 2u) = pk2(lo[k], hi[k]);
;             } else if (EPI == EPI_MOE2) {
;               *(unsigned*)(ws + O_EO + (row * 2048u + (unsigned)(colp + cc)) * 2u) = pk2(gate[k] * lo[k], gate[k] * hi[k]);
;             } else if (EPI == EPI_M1) {
;               const unsigned g2 = *(const unsigned*)(ws + O_COLS + (row * (unsigned)NCP + (unsigned)(C_GG + colp + cc)) * 2u);
;               *(unsigned*)(ws + O_M1 + (row * 2048u + (unsigned)(colp + cc)) * 2u) = pk2(sigm(bflo(g2)) * lo[k], sigm(bfhi(g2)) * hi[k]);
	v_lshlrev_b32_e32 v45, 16, v170
	v_and_b32_e32 v40, 0xffff0000, v170
	v_mul_f32_e32 v45, 0xbfb8aa3b, v45
	v_mul_f32_e32 v40, 0xbfb8aa3b, v40
	v_exp_f32_e32 v45, v45
	v_exp_f32_e32 v40, v40
	v_add_f32_e32 v41, 1.0, v45
	v_add_f32_e32 v40, 1.0, v40
	v_div_scale_f32 v45, s[0:1], v41, v41, 1.0
	v_div_scale_f32 v47, s[0:1], v40, v40, 1.0
	v_rcp_f32_e32 v51, v45
	v_rcp_f32_e32 v52, v47
	v_div_scale_f32 v46, vcc, 1.0, v41, 1.0
	v_fma_f32 v54, -v45, v51, 1.0
	v_fma_f32 v55, -v47, v52, 1.0
	v_fmac_f32_e32 v51, v54, v51
	v_div_scale_f32 v53, s[0:1], 1.0, v40, 1.0
	v_fmac_f32_e32 v52, v55, v52
	v_mul_f32_e32 v54, v46, v51
	v_mul_f32_e32 v55, v53, v52
	v_fma_f32 v56, -v45, v54, v46
	v_fma_f32 v57, -v47, v55, v53
	v_fmac_f32_e32 v54, v56, v51
	v_fmac_f32_e32 v55, v57, v52
	v_fma_f32 v45, -v45, v54, v46
	v_fma_f32 v46, -v47, v55, v53
	v_div_fmas_f32 v45, v45, v51, v54
	s_mov_b64 vcc, s[0:1]
	v_div_fixup_f32 v41, v45, v41, 1.0
	v_div_fmas_f32 v45, v46, v52, v55
	v_div_fixup_f32 v40, v45, v40, 1.0
	v_mul_f32_e32 v36, v36, v41
	v_mul_f32_e32 v38, v38, v40
	v_cvt_pk_bf16_f32 v36, v36, v38
	global_store_dword v42, v36, s[10:11]
	s_nop 0
	v_cndmask_b32_e64 v38, v37, v39, s[6:7]
	v_add_lshl_u32 v41, v50, v116, 1
	v_add_u32_e32 v40, v44, v118
	v_mov_b32_dpp v38, v38 quad_perm:[1,0,3,2] row_mask:0xf bank_mask:0xf bound_ctrl:1
	v_cndmask_b32_e64 v37, v38, v37, s[6:7]
	v_cndmask_b32_e64 v38, v39, v38, s[6:7]
	s_waitcnt vmcnt(47)
	v_lshlrev_b32_e32 v42, 16, v171
	v_and_b32_e32 v36, 0xffff0000, v171
	v_mul_f32_e32 v42, 0xbfb8aa3b, v42
	v_mul_f32_e32 v36, 0xbfb8aa3b, v36
	v_exp_f32_e32 v42, v42
	v_exp_f32_e32 v36, v36
	v_add_f32_e32 v39, 1.0, v42
	v_add_f32_e32 v36, 1.0, v36
	v_div_scale_f32 v42, s[0:1], v39, v39, 1.0
	v_div_scale_f32 v45, s[0:1], v36, v36, 1.0
	v_rcp_f32_e32 v46, v42
	v_rcp_f32_e32 v47, v45
	v_div_scale_f32 v43, vcc, 1.0, v39, 1.0
	v_fma_f32 v51, -v42, v46, 1.0
	v_fma_f32 v52, -v45, v47, 1.0
	v_fmac_f32_e32 v46, v51, v46
	v_div_scale_f32 v50, s[0:1], 1.0, v36, 1.0
	v_fmac_f32_e32 v47, v52, v47
	v_mul_f32_e32 v51, v43, v46
	v_mul_f32_e32 v52, v50, v47
	v_fma_f32 v53, -v42, v51, v43
	v_fma_f32 v54, -v45, v52, v50
	v_fmac_f32_e32 v51, v53, v46
	v_fmac_f32_e32 v52, v54, v47
	v_fma_f32 v42, -v42, v51, v43
	v_fma_f32 v43, -v45, v52, v50
	v_div_fmas_f32 v42, v42, v46, v51
	s_mov_b64 vcc, s[0:1]
	v_div_fixup_f32 v39, v42, v39, 1.0
	v_div_fmas_f32 v42, v43, v47, v52
	v_div_fixup_f32 v36, v42, v36, 1.0
	v_mul_f32_e32 v37, v37, v39
	v_mul_f32_e32 v36, v38, v36
	v_cvt_pk_bf16_f32 v36, v37, v36
	global_store_dword v40, v36, s[10:11]
	s_nop 0
	v_cndmask_b32_e64 v37, v32, v34, s[6:7]
	v_add_u32_e32 v38, v48, v112
	v_add_lshl_u32 v39, v49, v116, 1
	v_mov_b32_dpp v37, v37 quad_perm:[1,0,3,2] row_mask:0xf bank_mask:0xf bound_ctrl:1
	v_cndmask_b32_e64 v32, v37, v32, s[6:7]
	v_cndmask_b32_e64 v34, v34, v37, s[6:7]
	s_waitcnt vmcnt(47)
	v_lshlrev_b32_e32 v40, 16, v172
	v_and_b32_e32 v36, 0xffff0000, v172
	v_mul_f32_e32 v40, 0xbfb8aa3b, v40
	v_mul_f32_e32 v36, 0xbfb8aa3b, v36
	v_exp_f32_e32 v40, v40
	v_exp_f32_e32 v36, v36
	v_add_f32_e32 v37, 1.0, v40
	v_add_f32_e32 v36, 1.0, v36
	v_div_scale_f32 v40, s[0:1], v37, v37, 1.0
	v_div_scale_f32 v42, s[0:1], v36, v36, 1.0
	v_rcp_f32_e32 v43, v40
	v_rcp_f32_e32 v45, v42
	v_div_scale_f32 v41, vcc, 1.0, v37, 1.0
	v_fma_f32 v47, -v40, v43, 1.0
	v_fma_f32 v48, -v42, v45, 1.0
	v_fmac_f32_e32 v43, v47, v43
	v_div_scale_f32 v46, s[0:1], 1.0, v36, 1.0
	v_fmac_f32_e32 v45, v48, v45
	v_mul_f32_e32 v47, v41, v43
	v_mul_f32_e32 v48, v46, v45
	v_fma_f32 v49, -v40, v47, v41
	v_fma_f32 v50, -v42, v48, v46
	v_fmac_f32_e32 v47, v49, v43
	v_fmac_f32_e32 v48, v50, v45
	v_fma_f32 v40, -v40, v47, v41
	v_fma_f32 v41, -v42, v48, v46
	v_div_fmas_f32 v40, v40, v43, v47
	s_mov_b64 vcc, s[0:1]
	v_div_fixup_f32 v37, v40, v37, 1.0
	v_div_fmas_f32 v40, v41, v45, v48
	v_div_fixup_f32 v36, v40, v36, 1.0
	v_mul_f32_e32 v32, v32, v37
	v_mul_f32_e32 v34, v34, v36
	v_cvt_pk_bf16_f32 v32, v32, v34
	global_store_dword v38, v32, s[10:11]
	s_nop 0
	v_cndmask_b32_e64 v34, v33, v35, s[6:7]
	s_waitcnt vmcnt(47)
	v_lshlrev_b32_e32 v36, 16, v173
	v_and_b32_e32 v32, 0xffff0000, v173
	v_mul_f32_e32 v36, 0xbfb8aa3b, v36
	v_mul_f32_e32 v32, 0xbfb8aa3b, v32
	v_exp_f32_e32 v36, v36
	v_exp_f32_e32 v32, v32
	v_mov_b32_dpp v34, v34 quad_perm:[1,0,3,2] row_mask:0xf bank_mask:0xf bound_ctrl:1
	v_cndmask_b32_e64 v33, v34, v33, s[6:7]
	v_cndmask_b32_e64 v34, v35, v34, s[6:7]
	v_add_f32_e32 v35, 1.0, v36
	v_add_f32_e32 v32, 1.0, v32
	v_div_scale_f32 v36, s[0:1], v35, v35, 1.0
	v_div_scale_f32 v38, s[0:1], v32, v32, 1.0
	v_rcp_f32_e32 v39, v36
	v_rcp_f32_e32 v40, v38
	v_div_scale_f32 v37, vcc, 1.0, v35, 1.0
	v_fma_f32 v42, -v36, v39, 1.0
	v_fma_f32 v43, -v38, v40, 1.0
	v_fmac_f32_e32 v39, v42, v39
	v_div_scale_f32 v41, s[0:1], 1.0, v32, 1.0
	v_fmac_f32_e32 v40, v43, v40
	v_mul_f32_e32 v42, v37, v39
	v_mul_f32_e32 v43, v41, v40
	v_fma_f32 v45, -v36, v42, v37
	v_fma_f32 v46, -v38, v43, v41
	v_fmac_f32_e32 v42, v45, v39
	v_fmac_f32_e32 v43, v46, v40
	v_fma_f32 v36, -v36, v42, v37
	v_fma_f32 v37, -v38, v43, v41
	v_div_fmas_f32 v36, v36, v39, v42
	s_mov_b64 vcc, s[0:1]
	v_div_fixup_f32 v35, v36, v35, 1.0
	v_div_fmas_f32 v36, v37, v40, v43
	v_div_fixup_f32 v32, v36, v32, 1.0
	v_mul_f32_e32 v33, v33, v35
	v_mul_f32_e32 v32, v34, v32
	v_cvt_pk_bf16_f32 v32, v33, v32
	v_add_u32_e32 v33, v44, v112
	global_store_dword v33, v32, s[10:11]
	v_add_u32_e32 v34, 0x17a000, v113
	v_add_lshl_u32 v32, v34, v129, 1
	s_nop 0
	v_cndmask_b32_e64 v36, v28, v30, s[6:7]
	v_add_u32_e32 v32, 0xa0000, v128
	v_add_u32_e32 v33, 0x17ca00, v113
	v_mov_b32_dpp v36, v36 quad_perm:[1,0,3,2] row_mask:0xf bank_mask:0xf bound_ctrl:1
	v_cndmask_b32_e64 v28, v36, v28, s[6:7]
	v_cndmask_b32_e64 v30, v30, v36, s[6:7]
	v_add_u32_e32 v37, v32, v124
	v_add_lshl_u32 v38, v33, v129, 1
	s_waitcnt vmcnt(39)
; DEVINL float bflo(unsigned u) { return __uint_as_float(u << 16); }
; DEVINL float bfhi(unsigned u) { return __uint_as_float(u & 0xffff0000u); }
; DEVINL float sigm(float x) { return 1.f / (1.f + __expf(-x)); }
; template <int EPI, bool GATHER>
; DEVINL void gemm_tile(const Params& p, const u16* __restrict__ A, int lda, const int* __restrict__ rowidx,
;                       const u16* __restrict__ Bt, int ldb, int K, int brow, int bcol, int orow, int ocol) {
;     ...
;       const int rA = row0 + ai * HALF + m * 16 + (odd ? 2 : 0);
;       float gate[2] = {0.f, 0.f};
;       if (EPI == EPI_MOE2) { gate[0] = ((const float*)(ws + O_SELG))[rA]; gate[1] = ((const float*)(ws + O_SELG))[rA + 1]; }
; #pragma unroll
;       for (int bj = 0; bj < (EPI == EPI_HID ? 1 : 2); ++bj)
; #pragma unroll
;         for (int n = 0; n < 2; ++n) {
;           const int cc = bj * HALF + n * 16;
;           f32x4 v = acc[ai][bj][m][n];
;           if (EPI == EPI_HID) {
; #pragma unroll
;             for (int j = 0; j < 4; ++j) { const float a1 = acc[ai][0][m][n][j], a3 = acc[ai][1][m][n][j]; v[j] = a1 * sigm(a1) * a3; }
;           }
;           float lo[2], hi[2];
;           xchg_pairs(v, odd, lo, hi);
; #pragma unroll
;           for (int k = 0; k < 2; ++k) {
;             const unsigned row = (unsigned)(rA + k);
;             if (EPI == EPI_HID) {
;               *(unsigned*)(ws + O_HID + (row * 1024u + (unsigned)(colp + cc)) * 2u) = pk2(lo[k], hi[k]);
;             } else if (EPI == EPI_COLS) {
;               *(unsigned*)(ws + O_COLS + (row * (unsigned)NCP + (unsigned)(colp + cc)) * 2u) = pk2(lo[k], hi[k]);
;             } else if (EPI == EPI_MOE2) {
;               *(unsigned*)(ws + O_EO + (row * 2048u + (unsigned)(colp + cc)) * 2u) = pk2(gate[k] * lo[k], gate[k] * hi[k]);
;             } else if (EPI == EPI_M1) {
;               const unsigned g2 = *(const unsigned*)(ws + O_COLS + (row * (unsigned)NCP + (unsigned)(C_GG + colp + cc)) * 2u);
;               *(unsigned*)(ws + O_M1 + (row * 2048u + (unsigned)(colp + cc)) * 2u) = pk2(sigm(bflo(g2)) * lo[k], sigm(bfhi(g2)) * hi[k]);
	v_lshlrev_b32_e32 v39, 16, v190
	v_and_b32_e32 v35, 0xffff0000, v190
	v_mul_f32_e32 v39, 0xbfb8aa3b, v39
	v_mul_f32_e32 v35, 0xbfb8aa3b, v35
	v_exp_f32_e32 v39, v39
	v_exp_f32_e32 v35, v35
	v_add_f32_e32 v36, 1.0, v39
	v_add_f32_e32 v35, 1.0, v35
	v_div_scale_f32 v39, s[0:1], v36, v36, 1.0
	v_div_scale_f32 v41, s[0:1], v35, v35, 1.0
	v_rcp_f32_e32 v42, v39
	v_rcp_f32_e32 v43, v41
	v_div_scale_f32 v40, vcc, 1.0, v36, 1.0
	v_fma_f32 v45, -v39, v42, 1.0
	v_fma_f32 v46, -v41, v43, 1.0
	v_fmac_f32_e32 v42, v45, v42
	v_div_scale_f32 v44, s[0:1], 1.0, v35, 1.0
	v_fmac_f32_e32 v43, v46, v43
	v_mul_f32_e32 v45, v40, v42
	v_mul_f32_e32 v46, v44, v43
	v_fma_f32 v47, -v39, v45, v40
	v_fma_f32 v48, -v41, v46, v44
	v_fmac_f32_e32 v45, v47, v42
	v_fmac_f32_e32 v46, v48, v43
	v_fma_f32 v39, -v39, v45, v40
	v_fma_f32 v40, -v41, v46, v44
	v_div_fmas_f32 v39, v39, v42, v45
	s_mov_b64 vcc, s[0:1]
	v_div_fixup_f32 v36, v39, v36, 1.0
	v_div_fmas_f32 v39, v40, v43, v46
	v_div_fixup_f32 v35, v39, v35, 1.0
	v_mul_f32_e32 v28, v28, v36
	v_mul_f32_e32 v30, v30, v35
	v_cvt_pk_bf16_f32 v28, v28, v30
	global_store_dword v37, v28, s[10:11]
	s_nop 0
	v_cndmask_b32_e64 v35, v29, v31, s[6:7]
	v_add_u32_e32 v28, 0xa1000, v128
	v_add_u32_e32 v36, v28, v124
	v_mov_b32_dpp v35, v35 quad_perm:[1,0,3,2] row_mask:0xf bank_mask:0xf bound_ctrl:1
	v_cndmask_b32_e64 v29, v35, v29, s[6:7]
	v_cndmask_b32_e64 v31, v31, v35, s[6:7]
	v_add_lshl_u32 v37, v34, v126, 1
	s_waitcnt vmcnt(39)
	v_lshlrev_b32_e32 v38, 16, v191
	v_and_b32_e32 v30, 0xffff0000, v191
	v_mul_f32_e32 v38, 0xbfb8aa3b, v38
	v_mul_f32_e32 v30, 0xbfb8aa3b, v30
	v_exp_f32_e32 v38, v38
	v_exp_f32_e32 v30, v30
	v_add_f32_e32 v35, 1.0, v38
	v_add_f32_e32 v30, 1.0, v30
	v_div_scale_f32 v38, s[0:1], v35, v35, 1.0
	v_div_scale_f32 v40, s[0:1], v30, v30, 1.0
	v_rcp_f32_e32 v41, v38
	v_rcp_f32_e32 v42, v40
	v_div_scale_f32 v39, vcc, 1.0, v35, 1.0
	v_fma_f32 v44, -v38, v41, 1.0
	v_fma_f32 v45, -v40, v42, 1.0
	v_fmac_f32_e32 v41, v44, v41
	v_div_scale_f32 v43, s[0:1], 1.0, v30, 1.0
	v_fmac_f32_e32 v42, v45, v42
	v_mul_f32_e32 v44, v39, v41
	v_mul_f32_e32 v45, v43, v42
	v_fma_f32 v46, -v38, v44, v39
	v_fma_f32 v47, -v40, v45, v43
	v_fmac_f32_e32 v44, v46, v41
	v_fmac_f32_e32 v45, v47, v42
	v_fma_f32 v38, -v38, v44, v39
	v_fma_f32 v39, -v40, v45, v43
	v_div_fmas_f32 v38, v38, v41, v44
	s_mov_b64 vcc, s[0:1]
	v_div_fixup_f32 v35, v38, v35, 1.0
	v_div_fmas_f32 v38, v39, v42, v45
	v_div_fixup_f32 v30, v38, v30, 1.0
	v_mul_f32_e32 v29, v29, v35
	v_mul_f32_e32 v30, v31, v30
	v_cvt_pk_bf16_f32 v29, v29, v30
	global_store_dword v36, v29, s[10:11]
	s_nop 0
	v_cndmask_b32_e64 v30, v24, v26, s[6:7]
	v_add_u32_e32 v31, v32, v120
	v_add_lshl_u32 v35, v33, v126, 1
	v_mov_b32_dpp v30, v30 quad_perm:[1,0,3,2] row_mask:0xf bank_mask:0xf bound_ctrl:1
	v_cndmask_b32_e64 v24, v30, v24, s[6:7]
	v_cndmask_b32_e64 v26, v26, v30, s[6:7]
	s_waitcnt vmcnt(39)
	v_lshlrev_b32_e32 v36, 16, v192
	v_and_b32_e32 v29, 0xffff0000, v192
	v_mul_f32_e32 v36, 0xbfb8aa3b, v36
	v_mul_f32_e32 v29, 0xbfb8aa3b, v29
	v_exp_f32_e32 v36, v36
	v_exp_f32_e32 v29, v29
	v_add_f32_e32 v30, 1.0, v36
	v_add_f32_e32 v29, 1.0, v29
	v_div_scale_f32 v36, s[0:1], v30, v30, 1.0
	v_div_scale_f32 v38, s[0:1], v29, v29, 1.0
	v_rcp_f32_e32 v39, v36
	v_rcp_f32_e32 v40, v38
	v_div_scale_f32 v37, vcc, 1.0, v30, 1.0
	v_fma_f32 v42, -v36, v39, 1.0
	v_fma_f32 v43, -v38, v40, 1.0
	v_fmac_f32_e32 v39, v42, v39
	v_div_scale_f32 v41, s[0:1], 1.0, v29, 1.0
	v_fmac_f32_e32 v40, v43, v40
	v_mul_f32_e32 v42, v37, v39
	v_mul_f32_e32 v43, v41, v40
	v_fma_f32 v44, -v36, v42, v37
	v_fma_f32 v45, -v38, v43, v41
	v_fmac_f32_e32 v42, v44, v39
	v_fmac_f32_e32 v43, v45, v40
	v_fma_f32 v36, -v36, v42, v37
	v_fma_f32 v37, -v38, v43, v41
	v_div_fmas_f32 v36, v36, v39, v42
	s_mov_b64 vcc, s[0:1]
	v_div_fixup_f32 v30, v36, v30, 1.0
	v_div_fmas_f32 v36, v37, v40, v43
	v_div_fixup_f32 v29, v36, v29, 1.0
	v_mul_f32_e32 v24, v24, v30
	v_mul_f32_e32 v26, v26, v29
	v_cvt_pk_bf16_f32 v24, v24, v26
	global_store_dword v31, v24, s[10:11]
	s_nop 0
	v_cndmask_b32_e64 v26, v25, v27, s[6:7]
	v_add_u32_e32 v29, v28, v120
	v_add_lshl_u32 v30, v34, v122, 1
	v_mov_b32_dpp v26, v26 quad_perm:[1,0,3,2] row_mask:0xf bank_mask:0xf bound_ctrl:1
	v_cndmask_b32_e64 v25, v26, v25, s[6:7]
	v_cndmask_b32_e64 v26, v27, v26, s[6:7]
	s_waitcnt vmcnt(39)
	v_lshlrev_b32_e32 v31, 16, v193
	v_and_b32_e32 v24, 0xffff0000, v193
	v_mul_f32_e32 v31, 0xbfb8aa3b, v31
	v_mul_f32_e32 v24, 0xbfb8aa3b, v24
	v_exp_f32_e32 v31, v31
	v_exp_f32_e32 v24, v24
	v_add_f32_e32 v27, 1.0, v31
	v_add_f32_e32 v24, 1.0, v24
	v_div_scale_f32 v31, s[0:1], v27, v27, 1.0
	v_div_scale_f32 v36, s[0:1], v24, v24, 1.0
	v_rcp_f32_e32 v37, v31
	v_rcp_f32_e32 v38, v36
	v_div_scale_f32 v35, vcc, 1.0, v27, 1.0
	v_fma_f32 v40, -v31, v37, 1.0
	v_fma_f32 v41, -v36, v38, 1.0
	v_fmac_f32_e32 v37, v40, v37
	v_div_scale_f32 v39, s[0:1], 1.0, v24, 1.0
	v_fmac_f32_e32 v38, v41, v38
	v_mul_f32_e32 v40, v35, v37
	v_mul_f32_e32 v41, v39, v38
	v_fma_f32 v42, -v31, v40, v35
	v_fma_f32 v43, -v36, v41, v39
	v_fmac_f32_e32 v40, v42, v37
	v_fmac_f32_e32 v41, v43, v38
	v_fma_f32 v31, -v31, v40, v35
	v_fma_f32 v35, -v36, v41, v39
	v_div_fmas_f32 v31, v31, v37, v40
	s_mov_b64 vcc, s[0:1]
	v_div_fixup_f32 v27, v31, v27, 1.0
	v_div_fmas_f32 v31, v35, v38, v41
	v_div_fixup_f32 v24, v31, v24, 1.0
	v_mul_f32_e32 v25, v25, v27
	v_mul_f32_e32 v24, v26, v24
	v_cvt_pk_bf16_f32 v24, v25, v24
	global_store_dword v29, v24, s[10:11]
	s_nop 0
	v_cndmask_b32_e64 v25, v20, v22, s[6:7]
	v_add_u32_e32 v26, v32, v118
	v_add_lshl_u32 v27, v33, v122, 1
	v_mov_b32_dpp v25, v25 quad_perm:[1,0,3,2] row_mask:0xf bank_mask:0xf bound_ctrl:1
	v_cndmask_b32_e64 v20, v25, v20, s[6:7]
	v_cndmask_b32_e64 v22, v22, v25, s[6:7]
	s_waitcnt vmcnt(39)
; DEVINL float bflo(unsigned u) { return __uint_as_float(u << 16); }
; DEVINL float bfhi(unsigned u) { return __uint_as_float(u & 0xffff0000u); }
; DEVINL float sigm(float x) { return 1.f / (1.f + __expf(-x)); }
; template <int EPI, bool GATHER>
; DEVINL void gemm_tile(const Params& p, const u16* __restrict__ A, int lda, const int* __restrict__ rowidx,
;                       const u16* __restrict__ Bt, int ldb, int K, int brow, int bcol, int orow, int ocol) {
;     ...
;       const int rA = row0 + ai * HALF + m * 16 + (odd ? 2 : 0);
;       float gate[2] = {0.f, 0.f};
;       if (EPI == EPI_MOE2) { gate[0] = ((const float*)(ws + O_SELG))[rA]; gate[1] = ((const float*)(ws + O_SELG))[rA + 1]; }
; #pragma unroll
;       for (int bj = 0; bj < (EPI == EPI_HID ? 1 : 2); ++bj)
; #pragma unroll
;         for (int n = 0; n < 2; ++n) {
;           const int cc = bj * HALF + n * 16;
;           f32x4 v = acc[ai][bj][m][n];
;           if (EPI == EPI_HID) {
; #pragma unroll
;             for (int j = 0; j < 4; ++j) { const float a1 = acc[ai][0][m][n][j], a3 = acc[ai][1][m][n][j]; v[j] = a1 * sigm(a1) * a3; }
;           }
;           float lo[2], hi[2];
;           xchg_pairs(v, odd, lo, hi);
; #pragma unroll
;           for (int k = 0; k < 2; ++k) {
;             const unsigned row = (unsigned)(rA + k);
;             if (EPI == EPI_HID) {
;               *(unsigned*)(ws + O_HID + (row * 1024u + (unsigned)(colp + cc)) * 2u) = pk2(lo[k], hi[k]);
;             } else if (EPI == EPI_COLS) {
;               *(unsigned*)(ws + O_COLS + (row * (unsigned)NCP + (unsigned)(colp + cc)) * 2u) = pk2(lo[k], hi[k]);
;             } else if (EPI == EPI_MOE2) {
;               *(unsigned*)(ws + O_EO + (row * 2048u + (unsigned)(colp + cc)) * 2u) = pk2(gate[k] * lo[k], gate[k] * hi[k]);
;             } else if (EPI == EPI_M1) {
;               const unsigned g2 = *(const unsigned*)(ws + O_COLS + (row * (unsigned)NCP + (unsigned)(C_GG + colp + cc)) * 2u);
;               *(unsigned*)(ws + O_M1 + (row * 2048u + (unsigned)(colp + cc)) * 2u) = pk2(sigm(bflo(g2)) * lo[k], sigm(bfhi(g2)) * hi[k]);
	v_lshlrev_b32_e32 v29, 16, v194
	v_and_b32_e32 v24, 0xffff0000, v194
	v_mul_f32_e32 v29, 0xbfb8aa3b, v29
	v_mul_f32_e32 v24, 0xbfb8aa3b, v24
	v_exp_f32_e32 v29, v29
	v_exp_f32_e32 v24, v24
	v_add_f32_e32 v25, 1.0, v29
	v_add_f32_e32 v24, 1.0, v24
	v_div_scale_f32 v29, s[0:1], v25, v25, 1.0
	v_div_scale_f32 v31, s[0:1], v24, v24, 1.0
	v_rcp_f32_e32 v35, v29
	v_rcp_f32_e32 v36, v31
	v_div_scale_f32 v30, vcc, 1.0, v25, 1.0
	v_fma_f32 v38, -v29, v35, 1.0
	v_fma_f32 v39, -v31, v36, 1.0
	v_fmac_f32_e32 v35, v38, v35
	v_div_scale_f32 v37, s[0:1], 1.0, v24, 1.0
	v_fmac_f32_e32 v36, v39, v36
	v_mul_f32_e32 v38, v30, v35
	v_mul_f32_e32 v39, v37, v36
	v_fma_f32 v40, -v29, v38, v30
	v_fma_f32 v41, -v31, v39, v37
	v_fmac_f32_e32 v38, v40, v35
	v_fmac_f32_e32 v39, v41, v36
	v_fma_f32 v29, -v29, v38, v30
	v_fma_f32 v30, -v31, v39, v37
	v_div_fmas_f32 v29, v29, v35, v38
	s_mov_b64 vcc, s[0:1]
	v_div_fixup_f32 v25, v29, v25, 1.0
	v_div_fmas_f32 v29, v30, v36, v39
	v_div_fixup_f32 v24, v29, v24, 1.0
	v_mul_f32_e32 v20, v20, v25
	v_mul_f32_e32 v22, v22, v24
	v_cvt_pk_bf16_f32 v20, v20, v22
	global_store_dword v26, v20, s[10:11]
	s_nop 0
	v_cndmask_b32_e64 v22, v21, v23, s[6:7]
	v_add_lshl_u32 v25, v34, v116, 1
	v_add_u32_e32 v24, v28, v118
	v_mov_b32_dpp v22, v22 quad_perm:[1,0,3,2] row_mask:0xf bank_mask:0xf bound_ctrl:1
	v_cndmask_b32_e64 v21, v22, v21, s[6:7]
	v_cndmask_b32_e64 v22, v23, v22, s[6:7]
	s_waitcnt vmcnt(39)
	v_lshlrev_b32_e32 v26, 16, v195
	v_and_b32_e32 v20, 0xffff0000, v195
	v_mul_f32_e32 v26, 0xbfb8aa3b, v26
	v_mul_f32_e32 v20, 0xbfb8aa3b, v20
	v_exp_f32_e32 v26, v26
	v_exp_f32_e32 v20, v20
	v_add_f32_e32 v23, 1.0, v26
	v_add_f32_e32 v20, 1.0, v20
	v_div_scale_f32 v26, s[0:1], v23, v23, 1.0
	v_div_scale_f32 v29, s[0:1], v20, v20, 1.0
	v_rcp_f32_e32 v30, v26
	v_rcp_f32_e32 v31, v29
	v_div_scale_f32 v27, vcc, 1.0, v23, 1.0
	v_fma_f32 v35, -v26, v30, 1.0
	v_fma_f32 v36, -v29, v31, 1.0
	v_fmac_f32_e32 v30, v35, v30
	v_div_scale_f32 v34, s[0:1], 1.0, v20, 1.0
	v_fmac_f32_e32 v31, v36, v31
	v_mul_f32_e32 v35, v27, v30
	v_mul_f32_e32 v36, v34, v31
	v_fma_f32 v37, -v26, v35, v27
	v_fma_f32 v38, -v29, v36, v34
	v_fmac_f32_e32 v35, v37, v30
	v_fmac_f32_e32 v36, v38, v31
	v_fma_f32 v26, -v26, v35, v27
	v_fma_f32 v27, -v29, v36, v34
	v_div_fmas_f32 v26, v26, v30, v35
	s_mov_b64 vcc, s[0:1]
	v_div_fixup_f32 v23, v26, v23, 1.0
	v_div_fmas_f32 v26, v27, v31, v36
	v_div_fixup_f32 v20, v26, v20, 1.0
	v_mul_f32_e32 v21, v21, v23
	v_mul_f32_e32 v20, v22, v20
	v_cvt_pk_bf16_f32 v20, v21, v20
	global_store_dword v24, v20, s[10:11]
	s_nop 0
	v_cndmask_b32_e64 v21, v16, v18, s[6:7]
	v_add_u32_e32 v22, v32, v112
	v_add_lshl_u32 v23, v33, v116, 1
	v_mov_b32_dpp v21, v21 quad_perm:[1,0,3,2] row_mask:0xf bank_mask:0xf bound_ctrl:1
	v_cndmask_b32_e64 v16, v21, v16, s[6:7]
	v_cndmask_b32_e64 v18, v18, v21, s[6:7]
	s_waitcnt vmcnt(39)
	v_lshlrev_b32_e32 v24, 16, v196
	v_and_b32_e32 v20, 0xffff0000, v196
	v_mul_f32_e32 v24, 0xbfb8aa3b, v24
	v_mul_f32_e32 v20, 0xbfb8aa3b, v20
	v_exp_f32_e32 v24, v24
	v_exp_f32_e32 v20, v20
	v_add_f32_e32 v21, 1.0, v24
	v_add_f32_e32 v20, 1.0, v20
	v_div_scale_f32 v24, s[0:1], v21, v21, 1.0
	v_div_scale_f32 v26, s[0:1], v20, v20, 1.0
	v_rcp_f32_e32 v27, v24
	v_rcp_f32_e32 v29, v26
	v_div_scale_f32 v25, vcc, 1.0, v21, 1.0
	v_fma_f32 v31, -v24, v27, 1.0
	v_fma_f32 v32, -v26, v29, 1.0
	v_fmac_f32_e32 v27, v31, v27
	v_div_scale_f32 v30, s[0:1], 1.0, v20, 1.0
	v_fmac_f32_e32 v29, v32, v29
	v_mul_f32_e32 v31, v25, v27
	v_mul_f32_e32 v32, v30, v29
	v_fma_f32 v33, -v24, v31, v25
	v_fma_f32 v34, -v26, v32, v30
	v_fmac_f32_e32 v31, v33, v27
	v_fmac_f32_e32 v32, v34, v29
	v_fma_f32 v24, -v24, v31, v25
	v_fma_f32 v25, -v26, v32, v30
	v_div_fmas_f32 v24, v24, v27, v31
	s_mov_b64 vcc, s[0:1]
	v_div_fixup_f32 v21, v24, v21, 1.0
	v_div_fmas_f32 v24, v25, v29, v32
	v_div_fixup_f32 v20, v24, v20, 1.0
	v_mul_f32_e32 v16, v16, v21
	v_mul_f32_e32 v18, v18, v20
	v_cvt_pk_bf16_f32 v16, v16, v18
	global_store_dword v22, v16, s[10:11]
	s_nop 0
	v_cndmask_b32_e64 v18, v17, v19, s[6:7]
	s_waitcnt vmcnt(39)
	v_lshlrev_b32_e32 v20, 16, v197
	v_and_b32_e32 v16, 0xffff0000, v197
	v_mul_f32_e32 v20, 0xbfb8aa3b, v20
	v_mul_f32_e32 v16, 0xbfb8aa3b, v16
	v_exp_f32_e32 v20, v20
	v_exp_f32_e32 v16, v16
	v_mov_b32_dpp v18, v18 quad_perm:[1,0,3,2] row_mask:0xf bank_mask:0xf bound_ctrl:1
	v_cndmask_b32_e64 v17, v18, v17, s[6:7]
	v_cndmask_b32_e64 v18, v19, v18, s[6:7]
	v_add_f32_e32 v19, 1.0, v20
	v_add_f32_e32 v16, 1.0, v16
	v_div_scale_f32 v20, s[0:1], v19, v19, 1.0
	v_div_scale_f32 v22, s[0:1], v16, v16, 1.0
	v_rcp_f32_e32 v23, v20
	v_rcp_f32_e32 v24, v22
	v_div_scale_f32 v21, vcc, 1.0, v19, 1.0
	v_fma_f32 v26, -v20, v23, 1.0
	v_fma_f32 v27, -v22, v24, 1.0
	v_fmac_f32_e32 v23, v26, v23
	v_div_scale_f32 v25, s[0:1], 1.0, v16, 1.0
	v_fmac_f32_e32 v24, v27, v24
	v_mul_f32_e32 v26, v21, v23
	v_mul_f32_e32 v27, v25, v24
	v_fma_f32 v29, -v20, v26, v21
	v_fma_f32 v30, -v22, v27, v25
	v_fmac_f32_e32 v26, v29, v23
	v_fmac_f32_e32 v27, v30, v24
	v_fma_f32 v20, -v20, v26, v21
	v_fma_f32 v21, -v22, v27, v25
	v_div_fmas_f32 v20, v20, v23, v26
	s_mov_b64 vcc, s[0:1]
	v_div_fixup_f32 v19, v20, v19, 1.0
	v_div_fmas_f32 v20, v21, v24, v27
	v_div_fixup_f32 v16, v20, v16, 1.0
	v_mul_f32_e32 v17, v17, v19
	v_mul_f32_e32 v16, v18, v16
	v_cvt_pk_bf16_f32 v16, v17, v16
	v_add_u32_e32 v17, v28, v112
	global_store_dword v17, v16, s[10:11]
	v_add_u32_e32 v18, 0x1a4000, v113
	v_add_lshl_u32 v16, v18, v129, 1
	s_nop 0
	v_cndmask_b32_e64 v20, v12, v14, s[6:7]
	v_add_u32_e32 v16, 0xb0000, v128
	v_add_u32_e32 v17, 0x1a6a00, v113
	v_mov_b32_dpp v20, v20 quad_perm:[1,0,3,2] row_mask:0xf bank_mask:0xf bound_ctrl:1
	v_cndmask_b32_e64 v12, v20, v12, s[6:7]
	v_cndmask_b32_e64 v14, v14, v20, s[6:7]
	v_add_u32_e32 v21, v16, v124
	v_add_lshl_u32 v22, v17, v129, 1
	s_waitcnt vmcnt(31)
; DEVINL float bflo(unsigned u) { return __uint_as_float(u << 16); }
; DEVINL float bfhi(unsigned u) { return __uint_as_float(u & 0xffff0000u); }
; DEVINL float sigm(float x) { return 1.f / (1.f + __expf(-x)); }
; template <int EPI, bool GATHER>
; DEVINL void gemm_tile(const Params& p, const u16* __restrict__ A, int lda, const int* __restrict__ rowidx,
;                       const u16* __restrict__ Bt, int ldb, int K, int brow, int bcol, int orow, int ocol) {
;     ...
;       const int rA = row0 + ai * HALF + m * 16 + (odd ? 2 : 0);
;       float gate[2] = {0.f, 0.f};
;       if (EPI == EPI_MOE2) { gate[0] = ((const float*)(ws + O_SELG))[rA]; gate[1] = ((const float*)(ws + O_SELG))[rA + 1]; }
; #pragma unroll
;       for (int bj = 0; bj < (EPI == EPI_HID ? 1 : 2); ++bj)
; #pragma unroll
;         for (int n = 0; n < 2; ++n) {
;           const int cc = bj * HALF + n * 16;
;           f32x4 v = acc[ai][bj][m][n];
;           if (EPI == EPI_HID) {
; #pragma unroll
;             for (int j = 0; j < 4; ++j) { const float a1 = acc[ai][0][m][n][j], a3 = acc[ai][1][m][n][j]; v[j] = a1 * sigm(a1) * a3; }
;           }
;           float lo[2], hi[2];
;           xchg_pairs(v, odd, lo, hi);
; #pragma unroll
;           for (int k = 0; k < 2; ++k) {
;             const unsigned row = (unsigned)(rA + k);
;             if (EPI == EPI_HID) {
;               *(unsigned*)(ws + O_HID + (row * 1024u + (unsigned)(colp + cc)) * 2u) = pk2(lo[k], hi[k]);
;             } else if (EPI == EPI_COLS) {
;               *(unsigned*)(ws + O_COLS + (row * (unsigned)NCP + (unsigned)(colp + cc)) * 2u) = pk2(lo[k], hi[k]);
;             } else if (EPI == EPI_MOE2) {
;               *(unsigned*)(ws + O_EO + (row * 2048u + (unsigned)(colp + cc)) * 2u) = pk2(gate[k] * lo[k], gate[k] * hi[k]);
;             } else if (EPI == EPI_M1) {
;               const unsigned g2 = *(const unsigned*)(ws + O_COLS + (row * (unsigned)NCP + (unsigned)(C_GG + colp + cc)) * 2u);
;               *(unsigned*)(ws + O_M1 + (row * 2048u + (unsigned)(colp + cc)) * 2u) = pk2(sigm(bflo(g2)) * lo[k], sigm(bfhi(g2)) * hi[k]);
	v_lshlrev_b32_e32 v23, 16, v206
	v_and_b32_e32 v19, 0xffff0000, v206
	v_mul_f32_e32 v23, 0xbfb8aa3b, v23
	v_mul_f32_e32 v19, 0xbfb8aa3b, v19
	v_exp_f32_e32 v23, v23
	v_exp_f32_e32 v19, v19
	v_add_f32_e32 v20, 1.0, v23
	v_add_f32_e32 v19, 1.0, v19
	v_div_scale_f32 v23, s[0:1], v20, v20, 1.0
	v_div_scale_f32 v25, s[0:1], v19, v19, 1.0
	v_rcp_f32_e32 v26, v23
	v_rcp_f32_e32 v27, v25
	v_div_scale_f32 v24, vcc, 1.0, v20, 1.0
	v_fma_f32 v29, -v23, v26, 1.0
	v_fma_f32 v30, -v25, v27, 1.0
	v_fmac_f32_e32 v26, v29, v26
	v_div_scale_f32 v28, s[0:1], 1.0, v19, 1.0
	v_fmac_f32_e32 v27, v30, v27
	v_mul_f32_e32 v29, v24, v26
	v_mul_f32_e32 v30, v28, v27
	v_fma_f32 v31, -v23, v29, v24
	v_fma_f32 v32, -v25, v30, v28
	v_fmac_f32_e32 v29, v31, v26
	v_fmac_f32_e32 v30, v32, v27
	v_fma_f32 v23, -v23, v29, v24
	v_fma_f32 v24, -v25, v30, v28
	v_div_fmas_f32 v23, v23, v26, v29
	s_mov_b64 vcc, s[0:1]
	v_div_fixup_f32 v20, v23, v20, 1.0
	v_div_fmas_f32 v23, v24, v27, v30
	v_div_fixup_f32 v19, v23, v19, 1.0
	v_mul_f32_e32 v12, v12, v20
	v_mul_f32_e32 v14, v14, v19
	v_cvt_pk_bf16_f32 v12, v12, v14
	global_store_dword v21, v12, s[10:11]
	s_nop 0
	v_cndmask_b32_e64 v19, v13, v15, s[6:7]
	v_add_u32_e32 v12, 0xb1000, v128
	v_add_u32_e32 v20, v12, v124
	v_mov_b32_dpp v19, v19 quad_perm:[1,0,3,2] row_mask:0xf bank_mask:0xf bound_ctrl:1
	v_cndmask_b32_e64 v13, v19, v13, s[6:7]
	v_cndmask_b32_e64 v15, v15, v19, s[6:7]
	v_add_lshl_u32 v21, v18, v126, 1
	s_waitcnt vmcnt(31)
	v_lshlrev_b32_e32 v22, 16, v207
	v_and_b32_e32 v14, 0xffff0000, v207
	v_mul_f32_e32 v22, 0xbfb8aa3b, v22
	v_mul_f32_e32 v14, 0xbfb8aa3b, v14
	v_exp_f32_e32 v22, v22
	v_exp_f32_e32 v14, v14
	v_add_f32_e32 v19, 1.0, v22
	v_add_f32_e32 v14, 1.0, v14
	v_div_scale_f32 v22, s[0:1], v19, v19, 1.0
	v_div_scale_f32 v24, s[0:1], v14, v14, 1.0
	v_rcp_f32_e32 v25, v22
	v_rcp_f32_e32 v26, v24
	v_div_scale_f32 v23, vcc, 1.0, v19, 1.0
	v_fma_f32 v28, -v22, v25, 1.0
	v_fma_f32 v29, -v24, v26, 1.0
	v_fmac_f32_e32 v25, v28, v25
	v_div_scale_f32 v27, s[0:1], 1.0, v14, 1.0
	v_fmac_f32_e32 v26, v29, v26
	v_mul_f32_e32 v28, v23, v25
	v_mul_f32_e32 v29, v27, v26
	v_fma_f32 v30, -v22, v28, v23
	v_fma_f32 v31, -v24, v29, v27
	v_fmac_f32_e32 v28, v30, v25
	v_fmac_f32_e32 v29, v31, v26
	v_fma_f32 v22, -v22, v28, v23
	v_fma_f32 v23, -v24, v29, v27
	v_div_fmas_f32 v22, v22, v25, v28
	s_mov_b64 vcc, s[0:1]
	v_div_fixup_f32 v19, v22, v19, 1.0
	v_div_fmas_f32 v22, v23, v26, v29
	v_div_fixup_f32 v14, v22, v14, 1.0
	v_mul_f32_e32 v13, v13, v19
	v_mul_f32_e32 v14, v15, v14
	v_cvt_pk_bf16_f32 v13, v13, v14
	global_store_dword v20, v13, s[10:11]
	s_nop 0
	v_cndmask_b32_e64 v14, v8, v10, s[6:7]
	v_add_u32_e32 v15, v16, v120
	v_add_lshl_u32 v19, v17, v126, 1
	v_mov_b32_dpp v14, v14 quad_perm:[1,0,3,2] row_mask:0xf bank_mask:0xf bound_ctrl:1
	v_cndmask_b32_e64 v8, v14, v8, s[6:7]
	v_cndmask_b32_e64 v10, v10, v14, s[6:7]
	s_waitcnt vmcnt(31)
	v_lshlrev_b32_e32 v20, 16, v208
	v_and_b32_e32 v13, 0xffff0000, v208
	v_mul_f32_e32 v20, 0xbfb8aa3b, v20
	v_mul_f32_e32 v13, 0xbfb8aa3b, v13
	v_exp_f32_e32 v20, v20
	v_exp_f32_e32 v13, v13
	v_add_f32_e32 v14, 1.0, v20
	v_add_f32_e32 v13, 1.0, v13
	v_div_scale_f32 v20, s[0:1], v14, v14, 1.0
	v_div_scale_f32 v22, s[0:1], v13, v13, 1.0
	v_rcp_f32_e32 v23, v20
	v_rcp_f32_e32 v24, v22
	v_div_scale_f32 v21, vcc, 1.0, v14, 1.0
	v_fma_f32 v26, -v20, v23, 1.0
	v_fma_f32 v27, -v22, v24, 1.0
	v_fmac_f32_e32 v23, v26, v23
	v_div_scale_f32 v25, s[0:1], 1.0, v13, 1.0
	v_fmac_f32_e32 v24, v27, v24
	v_mul_f32_e32 v26, v21, v23
	v_mul_f32_e32 v27, v25, v24
	v_fma_f32 v28, -v20, v26, v21
	v_fma_f32 v29, -v22, v27, v25
	v_fmac_f32_e32 v26, v28, v23
	v_fmac_f32_e32 v27, v29, v24
	v_fma_f32 v20, -v20, v26, v21
	v_fma_f32 v21, -v22, v27, v25
	v_div_fmas_f32 v20, v20, v23, v26
	s_mov_b64 vcc, s[0:1]
	v_div_fixup_f32 v14, v20, v14, 1.0
	v_div_fmas_f32 v20, v21, v24, v27
	v_div_fixup_f32 v13, v20, v13, 1.0
	v_mul_f32_e32 v8, v8, v14
	v_mul_f32_e32 v10, v10, v13
	v_cvt_pk_bf16_f32 v8, v8, v10
	global_store_dword v15, v8, s[10:11]
	s_nop 0
	v_cndmask_b32_e64 v10, v9, v11, s[6:7]
	v_add_u32_e32 v13, v12, v120
	v_add_lshl_u32 v14, v18, v122, 1
	v_mov_b32_dpp v10, v10 quad_perm:[1,0,3,2] row_mask:0xf bank_mask:0xf bound_ctrl:1
	v_cndmask_b32_e64 v9, v10, v9, s[6:7]
	v_cndmask_b32_e64 v10, v11, v10, s[6:7]
	s_waitcnt vmcnt(31)
	v_lshlrev_b32_e32 v15, 16, v209
	v_and_b32_e32 v8, 0xffff0000, v209
	v_mul_f32_e32 v15, 0xbfb8aa3b, v15
	v_mul_f32_e32 v8, 0xbfb8aa3b, v8
	v_exp_f32_e32 v15, v15
	v_exp_f32_e32 v8, v8
	v_add_f32_e32 v11, 1.0, v15
	v_add_f32_e32 v8, 1.0, v8
	v_div_scale_f32 v15, s[0:1], v11, v11, 1.0
	v_div_scale_f32 v20, s[0:1], v8, v8, 1.0
	v_rcp_f32_e32 v21, v15
	v_rcp_f32_e32 v22, v20
	v_div_scale_f32 v19, vcc, 1.0, v11, 1.0
	v_fma_f32 v24, -v15, v21, 1.0
	v_fma_f32 v25, -v20, v22, 1.0
	v_fmac_f32_e32 v21, v24, v21
	v_div_scale_f32 v23, s[0:1], 1.0, v8, 1.0
	v_fmac_f32_e32 v22, v25, v22
	v_mul_f32_e32 v24, v19, v21
	v_mul_f32_e32 v25, v23, v22
	v_fma_f32 v26, -v15, v24, v19
	v_fma_f32 v27, -v20, v25, v23
	v_fmac_f32_e32 v24, v26, v21
	v_fmac_f32_e32 v25, v27, v22
	v_fma_f32 v15, -v15, v24, v19
	v_fma_f32 v19, -v20, v25, v23
	v_div_fmas_f32 v15, v15, v21, v24
	s_mov_b64 vcc, s[0:1]
	v_div_fixup_f32 v11, v15, v11, 1.0
	v_div_fmas_f32 v15, v19, v22, v25
	v_div_fixup_f32 v8, v15, v8, 1.0
	v_mul_f32_e32 v9, v9, v11
	v_mul_f32_e32 v8, v10, v8
	v_cvt_pk_bf16_f32 v8, v9, v8
	global_store_dword v13, v8, s[10:11]
	s_nop 0
	v_cndmask_b32_e64 v9, v4, v6, s[6:7]
	v_add_u32_e32 v10, v16, v118
	v_add_lshl_u32 v11, v17, v122, 1
	v_mov_b32_dpp v9, v9 quad_perm:[1,0,3,2] row_mask:0xf bank_mask:0xf bound_ctrl:1
	v_cndmask_b32_e64 v4, v9, v4, s[6:7]
	v_cndmask_b32_e64 v6, v6, v9, s[6:7]
	s_waitcnt vmcnt(31)
; DEVINL float bflo(unsigned u) { return __uint_as_float(u << 16); }
; DEVINL float bfhi(unsigned u) { return __uint_as_float(u & 0xffff0000u); }
; DEVINL float sigm(float x) { return 1.f / (1.f + __expf(-x)); }
; template <int EPI, bool GATHER>
; DEVINL void gemm_tile(const Params& p, const u16* __restrict__ A, int lda, const int* __restrict__ rowidx,
;                       const u16* __restrict__ Bt, int ldb, int K, int brow, int bcol, int orow, int ocol) {
;     ...
;       const int rA = row0 + ai * HALF + m * 16 + (odd ? 2 : 0);
;       float gate[2] = {0.f, 0.f};
;       if (EPI == EPI_MOE2) { gate[0] = ((const float*)(ws + O_SELG))[rA]; gate[1] = ((const float*)(ws + O_SELG))[rA + 1]; }
; #pragma unroll
;       for (int bj = 0; bj < (EPI == EPI_HID ? 1 : 2); ++bj)
; #pragma unroll
;         for (int n = 0; n < 2; ++n) {
;           const int cc = bj * HALF + n * 16;
;           f32x4 v = acc[ai][bj][m][n];
;           if (EPI == EPI_HID) {
; #pragma unroll
;             for (int j = 0; j < 4; ++j) { const float a1 = acc[ai][0][m][n][j], a3 = acc[ai][1][m][n][j]; v[j] = a1 * sigm(a1) * a3; }
;           }
;           float lo[2], hi[2];
;           xchg_pairs(v, odd, lo, hi);
; #pragma unroll
;           for (int k = 0; k < 2; ++k) {
;             const unsigned row = (unsigned)(rA + k);
;             if (EPI == EPI_HID) {
;               *(unsigned*)(ws + O_HID + (row * 1024u + (unsigned)(colp + cc)) * 2u) = pk2(lo[k], hi[k]);
;             } else if (EPI == EPI_COLS) {
;               *(unsigned*)(ws + O_COLS + (row * (unsigned)NCP + (unsigned)(colp + cc)) * 2u) = pk2(lo[k], hi[k]);
;             } else if (EPI == EPI_MOE2) {
;               *(unsigned*)(ws + O_EO + (row * 2048u + (unsigned)(colp + cc)) * 2u) = pk2(gate[k] * lo[k], gate[k] * hi[k]);
;             } else if (EPI == EPI_M1) {
;               const unsigned g2 = *(const unsigned*)(ws + O_COLS + (row * (unsigned)NCP + (unsigned)(C_GG + colp + cc)) * 2u);
;               *(unsigned*)(ws + O_M1 + (row * 2048u + (unsigned)(colp + cc)) * 2u) = pk2(sigm(bflo(g2)) * lo[k], sigm(bfhi(g2)) * hi[k]);
; DEVINL void phase5(const Params& p) {
;     ...
;   for (int t = blockIdx.x; t < 256; t += gridDim.x) {
;     int pm = t & 31, pn = t >> 5;
;     gemm_tile<EPI_M1, false>(p, A1, 1024, nullptr, B1, 1024, 1024, pm * 256, pn * 256, pm * 256, pn * 256);
;   }
	v_lshlrev_b32_e32 v13, 16, v210
	v_and_b32_e32 v8, 0xffff0000, v210
	v_mul_f32_e32 v13, 0xbfb8aa3b, v13
	v_mul_f32_e32 v8, 0xbfb8aa3b, v8
	v_exp_f32_e32 v13, v13
	v_exp_f32_e32 v8, v8
	v_add_f32_e32 v9, 1.0, v13
	v_add_f32_e32 v8, 1.0, v8
	v_div_scale_f32 v13, s[0:1], v9, v9, 1.0
	v_div_scale_f32 v15, s[0:1], v8, v8, 1.0
	v_rcp_f32_e32 v19, v13
	v_rcp_f32_e32 v20, v15
	v_div_scale_f32 v14, vcc, 1.0, v9, 1.0
	v_fma_f32 v22, -v13, v19, 1.0
	v_fma_f32 v23, -v15, v20, 1.0
	v_fmac_f32_e32 v19, v22, v19
	v_div_scale_f32 v21, s[0:1], 1.0, v8, 1.0
	v_fmac_f32_e32 v20, v23, v20
	v_mul_f32_e32 v22, v14, v19
	v_mul_f32_e32 v23, v21, v20
	v_fma_f32 v24, -v13, v22, v14
	v_fma_f32 v25, -v15, v23, v21
	v_fmac_f32_e32 v22, v24, v19
	v_fmac_f32_e32 v23, v25, v20
	v_fma_f32 v13, -v13, v22, v14
	v_fma_f32 v14, -v15, v23, v21
	v_div_fmas_f32 v13, v13, v19, v22
	s_mov_b64 vcc, s[0:1]
	v_div_fixup_f32 v9, v13, v9, 1.0
	v_div_fmas_f32 v13, v14, v20, v23
	v_div_fixup_f32 v8, v13, v8, 1.0
	v_mul_f32_e32 v4, v4, v9
	v_mul_f32_e32 v6, v6, v8
	v_cvt_pk_bf16_f32 v4, v4, v6
	global_store_dword v10, v4, s[10:11]
	s_nop 0
	v_cndmask_b32_e64 v6, v5, v7, s[6:7]
	v_add_lshl_u32 v9, v18, v116, 1
	v_add_u32_e32 v8, v12, v118
	v_mov_b32_dpp v6, v6 quad_perm:[1,0,3,2] row_mask:0xf bank_mask:0xf bound_ctrl:1
	v_cndmask_b32_e64 v5, v6, v5, s[6:7]
	v_cndmask_b32_e64 v6, v7, v6, s[6:7]
	s_waitcnt vmcnt(31)
	v_lshlrev_b32_e32 v10, 16, v211
	v_and_b32_e32 v4, 0xffff0000, v211
	v_mul_f32_e32 v10, 0xbfb8aa3b, v10
	v_mul_f32_e32 v4, 0xbfb8aa3b, v4
	v_exp_f32_e32 v10, v10
	v_exp_f32_e32 v4, v4
	v_add_f32_e32 v7, 1.0, v10
	v_add_f32_e32 v4, 1.0, v4
	v_div_scale_f32 v10, s[0:1], v7, v7, 1.0
	v_div_scale_f32 v13, s[0:1], v4, v4, 1.0
	v_rcp_f32_e32 v14, v10
	v_rcp_f32_e32 v15, v13
	v_div_scale_f32 v11, vcc, 1.0, v7, 1.0
	v_fma_f32 v19, -v10, v14, 1.0
	v_fma_f32 v20, -v13, v15, 1.0
	v_fmac_f32_e32 v14, v19, v14
	v_div_scale_f32 v18, s[0:1], 1.0, v4, 1.0
	v_fmac_f32_e32 v15, v20, v15
	v_mul_f32_e32 v19, v11, v14
	v_mul_f32_e32 v20, v18, v15
	v_fma_f32 v21, -v10, v19, v11
	v_fma_f32 v22, -v13, v20, v18
	v_fmac_f32_e32 v19, v21, v14
	v_fmac_f32_e32 v20, v22, v15
	v_fma_f32 v10, -v10, v19, v11
	v_fma_f32 v11, -v13, v20, v18
	v_div_fmas_f32 v10, v10, v14, v19
	s_mov_b64 vcc, s[0:1]
	v_div_fixup_f32 v7, v10, v7, 1.0
	v_div_fmas_f32 v10, v11, v15, v20
	v_div_fixup_f32 v4, v10, v4, 1.0
	v_mul_f32_e32 v5, v5, v7
	v_mul_f32_e32 v4, v6, v4
	v_cvt_pk_bf16_f32 v4, v5, v4
	global_store_dword v8, v4, s[10:11]
	s_nop 0
	v_cndmask_b32_e64 v5, v0, v2, s[6:7]
	v_add_u32_e32 v6, v16, v112
	v_add_lshl_u32 v7, v17, v116, 1
	v_mov_b32_dpp v5, v5 quad_perm:[1,0,3,2] row_mask:0xf bank_mask:0xf bound_ctrl:1
	v_cndmask_b32_e64 v0, v5, v0, s[6:7]
	v_cndmask_b32_e64 v2, v2, v5, s[6:7]
	s_waitcnt vmcnt(31)
	v_lshlrev_b32_e32 v8, 16, v212
	v_and_b32_e32 v4, 0xffff0000, v212
	v_mul_f32_e32 v8, 0xbfb8aa3b, v8
	v_mul_f32_e32 v4, 0xbfb8aa3b, v4
	v_exp_f32_e32 v8, v8
	v_exp_f32_e32 v4, v4
	v_add_f32_e32 v5, 1.0, v8
	v_add_f32_e32 v4, 1.0, v4
	v_div_scale_f32 v8, s[0:1], v5, v5, 1.0
	v_div_scale_f32 v10, s[0:1], v4, v4, 1.0
	v_rcp_f32_e32 v11, v8
	v_rcp_f32_e32 v13, v10
	v_div_scale_f32 v9, vcc, 1.0, v5, 1.0
	v_fma_f32 v15, -v8, v11, 1.0
	v_fma_f32 v16, -v10, v13, 1.0
	v_fmac_f32_e32 v11, v15, v11
	v_div_scale_f32 v14, s[0:1], 1.0, v4, 1.0
	v_fmac_f32_e32 v13, v16, v13
	v_mul_f32_e32 v15, v9, v11
	v_mul_f32_e32 v16, v14, v13
	v_fma_f32 v17, -v8, v15, v9
	v_fma_f32 v18, -v10, v16, v14
	v_fmac_f32_e32 v15, v17, v11
	v_fmac_f32_e32 v16, v18, v13
	v_fma_f32 v8, -v8, v15, v9
	v_fma_f32 v9, -v10, v16, v14
	v_div_fmas_f32 v8, v8, v11, v15
	s_mov_b64 vcc, s[0:1]
	v_div_fixup_f32 v5, v8, v5, 1.0
	v_div_fmas_f32 v8, v9, v13, v16
	v_div_fixup_f32 v4, v8, v4, 1.0
	v_mul_f32_e32 v0, v0, v5
	v_mul_f32_e32 v2, v2, v4
	v_cvt_pk_bf16_f32 v0, v0, v2
	global_store_dword v6, v0, s[10:11]
	s_nop 0
	v_cndmask_b32_e64 v2, v1, v3, s[6:7]
	s_waitcnt vmcnt(31)
	v_lshlrev_b32_e32 v4, 16, v213
	v_and_b32_e32 v0, 0xffff0000, v213
	v_mul_f32_e32 v4, 0xbfb8aa3b, v4
	v_mul_f32_e32 v0, 0xbfb8aa3b, v0
	v_exp_f32_e32 v4, v4
	v_exp_f32_e32 v0, v0
	v_mov_b32_dpp v2, v2 quad_perm:[1,0,3,2] row_mask:0xf bank_mask:0xf bound_ctrl:1
	v_cndmask_b32_e64 v1, v2, v1, s[6:7]
	v_cndmask_b32_e64 v2, v3, v2, s[6:7]
	v_add_f32_e32 v3, 1.0, v4
	v_add_f32_e32 v0, 1.0, v0
	v_div_scale_f32 v4, s[0:1], v3, v3, 1.0
	v_div_scale_f32 v6, s[0:1], v0, v0, 1.0
	v_rcp_f32_e32 v7, v4
	v_rcp_f32_e32 v8, v6
	v_div_scale_f32 v5, vcc, 1.0, v3, 1.0
	v_fma_f32 v10, -v4, v7, 1.0
	v_fma_f32 v11, -v6, v8, 1.0
	v_fmac_f32_e32 v7, v10, v7
	v_div_scale_f32 v9, s[0:1], 1.0, v0, 1.0
	v_fmac_f32_e32 v8, v11, v8
	v_mul_f32_e32 v10, v5, v7
	v_mul_f32_e32 v11, v9, v8
	v_fma_f32 v13, -v4, v10, v5
	v_fma_f32 v14, -v6, v11, v9
	v_fmac_f32_e32 v10, v13, v7
	v_fmac_f32_e32 v11, v14, v8
	v_fma_f32 v4, -v4, v10, v5
	v_fma_f32 v5, -v6, v11, v9
	v_div_fmas_f32 v4, v4, v7, v10
	s_mov_b64 vcc, s[0:1]
	v_div_fixup_f32 v3, v4, v3, 1.0
	v_div_fmas_f32 v4, v5, v8, v11
	v_div_fixup_f32 v0, v4, v0, 1.0
	v_mul_f32_e32 v1, v1, v3
	v_mul_f32_e32 v0, v2, v0
	v_cvt_pk_bf16_f32 v0, v1, v0
	v_add_u32_e32 v1, v12, v112
	global_store_dword v1, v0, s[10:11]
	s_add_i32 s53, s53, s94
	s_add_i32 s51, s51, s40
	s_add_i32 s50, s50, s60
	s_cmpk_lt_i32 s53, 0x100
	s_barrier
	s_cbranch_scc0 .LBB0_616

; template <int EPI, bool GATHER>
; DEVINL void gemm_tile(const Params& p, const u16* __restrict__ A, int lda, const int* __restrict__ rowidx,
;                       const u16* __restrict__ Bt, int ldb, int K, int brow, int bcol, int orow, int ocol) {
;     ...
;       const int rA = row0 + ai * HALF + m * 16 + (odd ? 2 : 0);
;       float gate[2] = {0.f, 0.f};
;       if (EPI == EPI_MOE2) { gate[0] = ((const float*)(ws + O_SELG))[rA]; gate[1] = ((const float*)(ws + O_SELG))[rA + 1]; }
; #pragma unroll
;       for (int bj = 0; bj < (EPI == EPI_HID ? 1 : 2); ++bj)
; #pragma unroll
;         for (int n = 0; n < 2; ++n) {
;           const int cc = bj * HALF + n * 16;
;           f32x4 v = acc[ai][bj][m][n];
;           if (EPI == EPI_HID) {
; #pragma unroll
;             for (int j = 0; j < 4; ++j) { const float a1 = acc[ai][0][m][n][j], a3 = acc[ai][1][m][n][j]; v[j] = a1 * sigm(a1) * a3; }
;           }
;           float lo[2], hi[2];
;           xchg_pairs(v, odd, lo, hi);
; #pragma unroll
;           for (int k = 0; k < 2; ++k) {
;             const unsigned row = (unsigned)(rA + k);
;             if (EPI == EPI_HID) {
;               *(unsigned*)(ws + O_HID + (row * 1024u + (unsigned)(colp + cc)) * 2u) = pk2(lo[k], hi[k]);
;             } else if (EPI == EPI_COLS) {
;               *(unsigned*)(ws + O_COLS + (row * (unsigned)NCP + (unsigned)(colp + cc)) * 2u) = pk2(lo[k], hi[k]);
;             } else if (EPI == EPI_MOE2) {
;               *(unsigned*)(ws + O_EO + (row * 2048u + (unsigned)(colp + cc)) * 2u) = pk2(gate[k] * lo[k], gate[k] * hi[k]);
;             } else if (EPI == EPI_M1) {
;               const unsigned g2 = *(const unsigned*)(ws + O_COLS + (row * (unsigned)NCP + (unsigned)(C_GG + colp + cc)) * 2u);
;               *(unsigned*)(ws + O_M1 + (row * 2048u + (unsigned)(colp + cc)) * 2u) = pk2(sigm(bflo(g2)) * lo[k], sigm(bfhi(g2)) * hi[k]);
;             } else if (EPI == EPI_MERGED) {
;               const unsigned g2 = *(const unsigned*)(ws + O_COLS + (row * (unsigned)NCP + (unsigned)(C_GR + colp + cc)) * 2u);
;               const unsigned m1 = *(const unsigned*)(ws + O_M1 + (row * 2048u + (unsigned)(colp + cc)) * 2u);
;               *(unsigned*)(ws + O_MERGED + (row * 2048u + (unsigned)(colp + cc)) * 2u) =
;                   pk2(bflo(m1) + sigm(bflo(g2)) * lo[k], bfhi(m1) + sigm(bfhi(g2)) * hi[k]);
;             } else if (EPI == EPI_R1) {
.LBB0_678:
	s_or_b64 exec, exec, s[24:25]
	v_and_b32_e32 v135, 1, v141
	v_or_b32_e32 v136, s22, v144
	v_sub_u32_e32 v137, v136, v135
	v_lshlrev_b32_e32 v136, 15, v143
	v_lshlrev_b32_e32 v138, 14, v135
	v_add_lshl_u32 v139, v145, s43, 13
	v_or3_b32 v136, v139, v138, v136
	v_lshlrev_b32_e32 v138, 7, v142
	v_lshl_add_u32 v137, v137, 2, v138
	v_add_u32_e32 v170, v136, v137
	global_load_dwordx2 v[146:147], v170, s[76:77]
	v_or_b32_e32 v135, 0x2000, v136
	v_add_u32_e32 v171, v135, v137
	global_load_dwordx2 v[148:149], v171, s[76:77]
	v_add_u32_e32 v172, 64, v137
	v_add_u32_e32 v170, v136, v172
	global_load_dwordx2 v[150:151], v170, s[76:77]
	v_add_u32_e32 v173, v135, v172
	global_load_dwordx2 v[152:153], v173, s[76:77]
	v_add_u32_e32 v174, 0x200, v137
	v_add_u32_e32 v138, v136, v174
	global_load_dwordx2 v[154:155], v138, s[76:77]
	v_add_u32_e32 v175, v135, v174
	global_load_dwordx2 v[156:157], v175, s[76:77]
	v_add_u32_e32 v176, 0x240, v137
	v_add_u32_e32 v173, v136, v176
	global_load_dwordx2 v[158:159], v173, s[76:77]
	v_add_u32_e32 v177, v135, v176
	global_load_dwordx2 v[160:161], v177, s[76:77]
	v_and_b32_e32 v135, 1, v141
	v_or_b32_e32 v136, s22, v144
	v_sub_u32_e32 v137, v136, v135
	v_lshlrev_b32_e32 v136, 15, v143
	v_lshlrev_b32_e32 v138, 14, v135
	v_add_lshl_u32 v139, v145, s43, 13
	v_or3_b32 v136, v139, v138, v136
	v_lshlrev_b32_e32 v138, 7, v142
	v_lshl_add_u32 v137, v137, 2, v138
	v_add_u32_e32 v170, 64, v137
	v_add_u32_e32 v171, 0x200, v137
	v_add_u32_e32 v172, 0x240, v137
	v_or_b32_e32 v173, 0x20000, v136
	v_add_u32_e32 v174, v173, v137
	global_load_dwordx2 v[190:191], v174, s[76:77]
	v_or_b32_e32 v175, 0x22000, v136
	v_add_u32_e32 v176, v175, v137
	global_load_dwordx2 v[192:193], v176, s[76:77]
	v_add_u32_e32 v177, v173, v170
	global_load_dwordx2 v[194:195], v177, s[76:77]
	v_add_u32_e32 v178, v175, v170
	global_load_dwordx2 v[196:197], v178, s[76:77]
	v_add_u32_e32 v179, v173, v171
	global_load_dwordx2 v[198:199], v179, s[76:77]
	v_add_u32_e32 v180, v175, v171
	global_load_dwordx2 v[200:201], v180, s[76:77]
	v_add_u32_e32 v181, v173, v172
	global_load_dwordx2 v[202:203], v181, s[76:77]
	v_add_u32_e32 v182, v175, v172
	global_load_dwordx2 v[204:205], v182, s[76:77]
	v_and_b32_e32 v135, 1, v141
	v_or_b32_e32 v136, s22, v144
	v_sub_u32_e32 v137, v136, v135
	v_lshlrev_b32_e32 v136, 15, v143
	v_lshlrev_b32_e32 v138, 14, v135
	v_add_lshl_u32 v139, v145, s43, 13
	v_or3_b32 v136, v139, v138, v136
	v_lshlrev_b32_e32 v138, 7, v142
	v_lshl_add_u32 v137, v137, 2, v138
	v_add_u32_e32 v170, 64, v137
	v_add_u32_e32 v171, 0x200, v137
	v_add_u32_e32 v172, 0x240, v137
	v_or_b32_e32 v173, 0x40000, v136
	v_add_u32_e32 v174, v173, v137
	global_load_dwordx2 v[214:215], v174, s[76:77]
	v_or_b32_e32 v175, 0x42000, v136
	v_add_u32_e32 v176, v175, v137
	global_load_dwordx2 v[216:217], v176, s[76:77]
	v_add_u32_e32 v177, v173, v170
	global_load_dwordx2 v[218:219], v177, s[76:77]
	v_add_u32_e32 v178, v175, v170
	global_load_dwordx2 v[220:221], v178, s[76:77]
	v_add_u32_e32 v179, v173, v171
	global_load_dwordx2 v[222:223], v179, s[76:77]
	v_add_u32_e32 v180, v175, v171
	global_load_dwordx2 v[224:225], v180, s[76:77]
	v_add_u32_e32 v181, v173, v172
	global_load_dwordx2 v[226:227], v181, s[76:77]
	v_add_u32_e32 v182, v175, v172
	global_load_dwordx2 v[228:229], v182, s[76:77]
	v_and_b32_e32 v132, 1, v141
	v_or_b32_e32 v128, s22, v144
	v_sub_u32_e32 v129, v128, v132
	v_lshlrev_b32_e32 v128, 15, v143
	v_lshlrev_b32_e32 v130, 14, v132
	v_add_lshl_u32 v131, v145, s43, 13
	v_or3_b32 v128, v131, v130, v128
	v_lshlrev_b32_e32 v130, 7, v142
	v_lshl_add_u32 v129, v129, 2, v130
	v_add_u32_e32 v133, v128, v129
	s_nop 0
	v_cmp_eq_u32_e32 vcc, 0, v132
	v_lshrrev_b32_e32 v133, 1, v133
	s_nop 0
	v_cndmask_b32_e32 v132, v124, v126, vcc
	s_nop 1
	v_mov_b32_dpp v132, v132 quad_perm:[1,0,3,2] row_mask:0xf bank_mask:0xf bound_ctrl:1
	v_cndmask_b32_e32 v124, v132, v124, vcc
	v_cndmask_b32_e32 v126, v126, v132, vcc
	v_or_b32_e32 v132, 0x2000, v128
	v_add_u32_e32 v134, v132, v129
	s_waitcnt vmcnt(23)
	v_fmac_f32_e32 v124, 0x3f9837f0, v146
	v_fmac_f32_e32 v126, 0x3f9837f0, v147
	v_cvt_pk_bf16_f32 v124, v124, v126
	global_store_dword v133, v124, s[92:93]
	s_nop 0
	v_cndmask_b32_e32 v124, v125, v127, vcc
	s_nop 1
	v_mov_b32_dpp v126, v124 quad_perm:[1,0,3,2] row_mask:0xf bank_mask:0xf bound_ctrl:1
	v_cndmask_b32_e32 v125, v126, v125, vcc
	v_cndmask_b32_e32 v126, v127, v126, vcc
	v_add_u32_e32 v124, 64, v129
	v_lshrrev_b32_e32 v127, 1, v134
	v_add_u32_e32 v133, v128, v124
	s_waitcnt vmcnt(23)
	v_fmac_f32_e32 v125, 0x3f9837f0, v148
	v_fmac_f32_e32 v126, 0x3f9837f0, v149
	v_cvt_pk_bf16_f32 v125, v125, v126
	global_store_dword v127, v125, s[92:93]
	s_nop 0
	v_cndmask_b32_e32 v125, v120, v122, vcc
	v_lshrrev_b32_e32 v130, 1, v133
	s_nop 0
	v_mov_b32_dpp v125, v125 quad_perm:[1,0,3,2] row_mask:0xf bank_mask:0xf bound_ctrl:1
	v_cndmask_b32_e32 v120, v125, v120, vcc
	v_cndmask_b32_e32 v122, v122, v125, vcc
	v_add_u32_e32 v125, v132, v124
	s_waitcnt vmcnt(23)
	v_fmac_f32_e32 v120, 0x3f9837f0, v150
	v_fmac_f32_e32 v122, 0x3f9837f0, v151
	v_cvt_pk_bf16_f32 v120, v120, v122
	global_store_dword v130, v120, s[92:93]
	s_nop 0
	v_cndmask_b32_e32 v120, v121, v123, vcc
	s_nop 1
	v_mov_b32_dpp v122, v120 quad_perm:[1,0,3,2] row_mask:0xf bank_mask:0xf bound_ctrl:1
	v_cndmask_b32_e32 v121, v122, v121, vcc
	v_cndmask_b32_e32 v122, v123, v122, vcc
	v_add_u32_e32 v120, 0x200, v129
	v_lshrrev_b32_e32 v123, 1, v125
	v_add_u32_e32 v130, v128, v120
	v_lshrrev_b32_e32 v125, 1, v130
	s_waitcnt vmcnt(23)
; template <int EPI, bool GATHER>
; DEVINL void gemm_tile(const Params& p, const u16* __restrict__ A, int lda, const int* __restrict__ rowidx,
;                       const u16* __restrict__ Bt, int ldb, int K, int brow, int bcol, int orow, int ocol) {
;     ...
;       const int rA = row0 + ai * HALF + m * 16 + (odd ? 2 : 0);
;       float gate[2] = {0.f, 0.f};
;       if (EPI == EPI_MOE2) { gate[0] = ((const float*)(ws + O_SELG))[rA]; gate[1] = ((const float*)(ws + O_SELG))[rA + 1]; }
; #pragma unroll
;       for (int bj = 0; bj < (EPI == EPI_HID ? 1 : 2); ++bj)
; #pragma unroll
;         for (int n = 0; n < 2; ++n) {
;           const int cc = bj * HALF + n * 16;
;           f32x4 v = acc[ai][bj][m][n];
;           if (EPI == EPI_HID) {
; #pragma unroll
;             for (int j = 0; j < 4; ++j) { const float a1 = acc[ai][0][m][n][j], a3 = acc[ai][1][m][n][j]; v[j] = a1 * sigm(a1) * a3; }
;           }
;           float lo[2], hi[2];
;           xchg_pairs(v, odd, lo, hi);
; #pragma unroll
;           for (int k = 0; k < 2; ++k) {
;             const unsigned row = (unsigned)(rA + k);
;             if (EPI == EPI_HID) {
;               *(unsigned*)(ws + O_HID + (row * 1024u + (unsigned)(colp + cc)) * 2u) = pk2(lo[k], hi[k]);
;             } else if (EPI == EPI_COLS) {
;               *(unsigned*)(ws + O_COLS + (row * (unsigned)NCP + (unsigned)(colp + cc)) * 2u) = pk2(lo[k], hi[k]);
;             } else if (EPI == EPI_MOE2) {
;               *(unsigned*)(ws + O_EO + (row * 2048u + (unsigned)(colp + cc)) * 2u) = pk2(gate[k] * lo[k], gate[k] * hi[k]);
;             } else if (EPI == EPI_M1) {
;               const unsigned g2 = *(const unsigned*)(ws + O_COLS + (row * (unsigned)NCP + (unsigned)(C_GG + colp + cc)) * 2u);
;               *(unsigned*)(ws + O_M1 + (row * 2048u + (unsigned)(colp + cc)) * 2u) = pk2(sigm(bflo(g2)) * lo[k], sigm(bfhi(g2)) * hi[k]);
;             } else if (EPI == EPI_MERGED) {
;               const unsigned g2 = *(const unsigned*)(ws + O_COLS + (row * (unsigned)NCP + (unsigned)(C_GR + colp + cc)) * 2u);
;               const unsigned m1 = *(const unsigned*)(ws + O_M1 + (row * 2048u + (unsigned)(colp + cc)) * 2u);
;               *(unsigned*)(ws + O_MERGED + (row * 2048u + (unsigned)(colp + cc)) * 2u) =
;                   pk2(bflo(m1) + sigm(bflo(g2)) * lo[k], bfhi(m1) + sigm(bfhi(g2)) * hi[k]);
;             } else if (EPI == EPI_R1) {
	v_fmac_f32_e32 v121, 0x3f9837f0, v152
	v_fmac_f32_e32 v122, 0x3f9837f0, v153
	v_cvt_pk_bf16_f32 v121, v121, v122
	global_store_dword v123, v121, s[92:93]
	s_nop 0
	v_cndmask_b32_e32 v121, v116, v118, vcc
	s_nop 1
	v_mov_b32_dpp v121, v121 quad_perm:[1,0,3,2] row_mask:0xf bank_mask:0xf bound_ctrl:1
	v_cndmask_b32_e32 v116, v121, v116, vcc
	v_cndmask_b32_e32 v118, v118, v121, vcc
	v_add_u32_e32 v121, v132, v120
	s_waitcnt vmcnt(23)
	v_fmac_f32_e32 v116, 0x3f9837f0, v154
	v_fmac_f32_e32 v118, 0x3f9837f0, v155
	v_cvt_pk_bf16_f32 v116, v116, v118
	global_store_dword v125, v116, s[92:93]
	s_nop 0
	v_cndmask_b32_e32 v116, v117, v119, vcc
	s_nop 1
	v_mov_b32_dpp v118, v116 quad_perm:[1,0,3,2] row_mask:0xf bank_mask:0xf bound_ctrl:1
	v_cndmask_b32_e32 v117, v118, v117, vcc
	v_cndmask_b32_e32 v118, v119, v118, vcc
	v_add_u32_e32 v116, 0x240, v129
	v_lshrrev_b32_e32 v119, 1, v121
	v_add_u32_e32 v125, v128, v116
	v_lshrrev_b32_e32 v121, 1, v125
	s_waitcnt vmcnt(23)
	v_fmac_f32_e32 v117, 0x3f9837f0, v156
	v_fmac_f32_e32 v118, 0x3f9837f0, v157
	v_cvt_pk_bf16_f32 v117, v117, v118
	global_store_dword v119, v117, s[92:93]
	s_nop 0
	v_cndmask_b32_e32 v117, v112, v114, vcc
	s_nop 1
	v_mov_b32_dpp v117, v117 quad_perm:[1,0,3,2] row_mask:0xf bank_mask:0xf bound_ctrl:1
	v_cndmask_b32_e32 v112, v117, v112, vcc
	v_cndmask_b32_e32 v114, v114, v117, vcc
	v_add_u32_e32 v117, v132, v116
	s_waitcnt vmcnt(23)
	v_fmac_f32_e32 v112, 0x3f9837f0, v158
	v_fmac_f32_e32 v114, 0x3f9837f0, v159
	v_cvt_pk_bf16_f32 v112, v112, v114
	global_store_dword v121, v112, s[92:93]
	s_nop 0
	v_cndmask_b32_e32 v112, v113, v115, vcc
	s_nop 1
	v_mov_b32_dpp v112, v112 quad_perm:[1,0,3,2] row_mask:0xf bank_mask:0xf bound_ctrl:1
	v_cndmask_b32_e32 v113, v112, v113, vcc
	v_cndmask_b32_e32 v112, v115, v112, vcc
	s_waitcnt vmcnt(23)
	v_fmac_f32_e32 v113, 0x3f9837f0, v160
	v_fmac_f32_e32 v112, 0x3f9837f0, v161
	v_cvt_pk_bf16_f32 v112, v113, v112
	v_lshrrev_b32_e32 v113, 1, v117
	global_store_dword v113, v112, s[92:93]
	v_or_b32_e32 v135, 0x60000, v128
	v_add_u32_e32 v136, v135, v129
	global_load_dwordx2 v[146:147], v136, s[76:77]
	v_or_b32_e32 v137, 0x62000, v128
	v_add_u32_e32 v138, v137, v129
	global_load_dwordx2 v[148:149], v138, s[76:77]
	v_add_u32_e32 v139, v135, v124
	global_load_dwordx2 v[150:151], v139, s[76:77]
	v_add_u32_e32 v170, v137, v124
	global_load_dwordx2 v[152:153], v170, s[76:77]
	v_add_u32_e32 v171, v135, v120
	global_load_dwordx2 v[154:155], v171, s[76:77]
	v_add_u32_e32 v172, v137, v120
	global_load_dwordx2 v[156:157], v172, s[76:77]
	v_add_u32_e32 v173, v135, v116
	global_load_dwordx2 v[158:159], v173, s[76:77]
	v_add_u32_e32 v174, v137, v116
	global_load_dwordx2 v[160:161], v174, s[76:77]
	v_or_b32_e32 v114, 0x20000, v128
	v_add_u32_e32 v115, v114, v129
	s_nop 0
	v_cndmask_b32_e32 v117, v108, v110, vcc
	v_or_b32_e32 v118, 0x22000, v128
	v_lshrrev_b32_e32 v115, 1, v115
	v_mov_b32_dpp v117, v117 quad_perm:[1,0,3,2] row_mask:0xf bank_mask:0xf bound_ctrl:1
	v_cndmask_b32_e32 v108, v117, v108, vcc
	v_cndmask_b32_e32 v110, v110, v117, vcc
	v_add_u32_e32 v119, v118, v129
	s_waitcnt vmcnt(31)
	v_fmac_f32_e32 v108, 0x3f9837f0, v190
	v_fmac_f32_e32 v110, 0x3f9837f0, v191
	v_cvt_pk_bf16_f32 v108, v108, v110
	global_store_dword v115, v108, s[92:93]
	s_nop 0
	v_cndmask_b32_e32 v108, v109, v111, vcc
	v_add_u32_e32 v110, v114, v124
	s_nop 0
	v_mov_b32_dpp v108, v108 quad_perm:[1,0,3,2] row_mask:0xf bank_mask:0xf bound_ctrl:1
	v_cndmask_b32_e32 v109, v108, v109, vcc
	v_cndmask_b32_e32 v108, v111, v108, vcc
	v_lshrrev_b32_e32 v111, 1, v119
	s_waitcnt vmcnt(31)
	v_fmac_f32_e32 v109, 0x3f9837f0, v192
	v_fmac_f32_e32 v108, 0x3f9837f0, v193
	v_cvt_pk_bf16_f32 v108, v109, v108
	global_store_dword v111, v108, s[92:93]
	s_nop 0
	v_cndmask_b32_e32 v111, v104, v106, vcc
	v_lshrrev_b32_e32 v110, 1, v110
	v_add_u32_e32 v112, v118, v124
	v_mov_b32_dpp v111, v111 quad_perm:[1,0,3,2] row_mask:0xf bank_mask:0xf bound_ctrl:1
	v_cndmask_b32_e32 v104, v111, v104, vcc
	v_cndmask_b32_e32 v106, v106, v111, vcc
	s_waitcnt vmcnt(31)
	v_fmac_f32_e32 v104, 0x3f9837f0, v194
	v_fmac_f32_e32 v106, 0x3f9837f0, v195
	v_cvt_pk_bf16_f32 v104, v104, v106
	global_store_dword v110, v104, s[92:93]
	s_nop 0
	v_cndmask_b32_e32 v104, v105, v107, vcc
	v_add_u32_e32 v106, v114, v120
	s_nop 0
	v_mov_b32_dpp v104, v104 quad_perm:[1,0,3,2] row_mask:0xf bank_mask:0xf bound_ctrl:1
	v_cndmask_b32_e32 v105, v104, v105, vcc
	v_cndmask_b32_e32 v104, v107, v104, vcc
	v_lshrrev_b32_e32 v107, 1, v112
	s_waitcnt vmcnt(31)
	v_fmac_f32_e32 v105, 0x3f9837f0, v196
	v_fmac_f32_e32 v104, 0x3f9837f0, v197
	v_cvt_pk_bf16_f32 v104, v105, v104
	global_store_dword v107, v104, s[92:93]
	s_nop 0
	v_cndmask_b32_e32 v107, v100, v102, vcc
	v_lshrrev_b32_e32 v106, 1, v106
	v_add_u32_e32 v108, v118, v120
	v_mov_b32_dpp v107, v107 quad_perm:[1,0,3,2] row_mask:0xf bank_mask:0xf bound_ctrl:1
	v_cndmask_b32_e32 v100, v107, v100, vcc
	v_cndmask_b32_e32 v102, v102, v107, vcc
	s_waitcnt vmcnt(31)
	v_fmac_f32_e32 v100, 0x3f9837f0, v198
	v_fmac_f32_e32 v102, 0x3f9837f0, v199
	v_cvt_pk_bf16_f32 v100, v100, v102
	global_store_dword v106, v100, s[92:93]
	s_nop 0
	v_cndmask_b32_e32 v100, v101, v103, vcc
	v_add_u32_e32 v102, v114, v116
	s_nop 0
	v_mov_b32_dpp v100, v100 quad_perm:[1,0,3,2] row_mask:0xf bank_mask:0xf bound_ctrl:1
	v_cndmask_b32_e32 v101, v100, v101, vcc
	v_cndmask_b32_e32 v100, v103, v100, vcc
	v_lshrrev_b32_e32 v103, 1, v108
	s_waitcnt vmcnt(31)
; template <int EPI, bool GATHER>
; DEVINL void gemm_tile(const Params& p, const u16* __restrict__ A, int lda, const int* __restrict__ rowidx,
;                       const u16* __restrict__ Bt, int ldb, int K, int brow, int bcol, int orow, int ocol) {
;     ...
;       const int rA = row0 + ai * HALF + m * 16 + (odd ? 2 : 0);
;       float gate[2] = {0.f, 0.f};
;       if (EPI == EPI_MOE2) { gate[0] = ((const float*)(ws + O_SELG))[rA]; gate[1] = ((const float*)(ws + O_SELG))[rA + 1]; }
; #pragma unroll
;       for (int bj = 0; bj < (EPI == EPI_HID ? 1 : 2); ++bj)
; #pragma unroll
;         for (int n = 0; n < 2; ++n) {
;           const int cc = bj * HALF + n * 16;
;           f32x4 v = acc[ai][bj][m][n];
;           if (EPI == EPI_HID) {
; #pragma unroll
;             for (int j = 0; j < 4; ++j) { const float a1 = acc[ai][0][m][n][j], a3 = acc[ai][1][m][n][j]; v[j] = a1 * sigm(a1) * a3; }
;           }
;           float lo[2], hi[2];
;           xchg_pairs(v, odd, lo, hi);
; #pragma unroll
;           for (int k = 0; k < 2; ++k) {
;             const unsigned row = (unsigned)(rA + k);
;             if (EPI == EPI_HID) {
;               *(unsigned*)(ws + O_HID + (row * 1024u + (unsigned)(colp + cc)) * 2u) = pk2(lo[k], hi[k]);
;             } else if (EPI == EPI_COLS) {
;               *(unsigned*)(ws + O_COLS + (row * (unsigned)NCP + (unsigned)(colp + cc)) * 2u) = pk2(lo[k], hi[k]);
;             } else if (EPI == EPI_MOE2) {
;               *(unsigned*)(ws + O_EO + (row * 2048u + (unsigned)(colp + cc)) * 2u) = pk2(gate[k] * lo[k], gate[k] * hi[k]);
;             } else if (EPI == EPI_M1) {
;               const unsigned g2 = *(const unsigned*)(ws + O_COLS + (row * (unsigned)NCP + (unsigned)(C_GG + colp + cc)) * 2u);
;               *(unsigned*)(ws + O_M1 + (row * 2048u + (unsigned)(colp + cc)) * 2u) = pk2(sigm(bflo(g2)) * lo[k], sigm(bfhi(g2)) * hi[k]);
;             } else if (EPI == EPI_MERGED) {
;               const unsigned g2 = *(const unsigned*)(ws + O_COLS + (row * (unsigned)NCP + (unsigned)(C_GR + colp + cc)) * 2u);
;               const unsigned m1 = *(const unsigned*)(ws + O_M1 + (row * 2048u + (unsigned)(colp + cc)) * 2u);
;               *(unsigned*)(ws + O_MERGED + (row * 2048u + (unsigned)(colp + cc)) * 2u) =
;                   pk2(bflo(m1) + sigm(bflo(g2)) * lo[k], bfhi(m1) + sigm(bfhi(g2)) * hi[k]);
;             } else if (EPI == EPI_R1) {
	v_fmac_f32_e32 v101, 0x3f9837f0, v200
	v_fmac_f32_e32 v100, 0x3f9837f0, v201
	v_cvt_pk_bf16_f32 v100, v101, v100
	global_store_dword v103, v100, s[92:93]
	s_nop 0
	v_cndmask_b32_e32 v103, v96, v98, vcc
	v_lshrrev_b32_e32 v102, 1, v102
	v_add_u32_e32 v104, v118, v116
	v_mov_b32_dpp v103, v103 quad_perm:[1,0,3,2] row_mask:0xf bank_mask:0xf bound_ctrl:1
	v_cndmask_b32_e32 v96, v103, v96, vcc
	v_cndmask_b32_e32 v98, v98, v103, vcc
	s_waitcnt vmcnt(31)
	v_fmac_f32_e32 v96, 0x3f9837f0, v202
	v_fmac_f32_e32 v98, 0x3f9837f0, v203
	v_cvt_pk_bf16_f32 v96, v96, v98
	global_store_dword v102, v96, s[92:93]
	s_nop 0
	v_cndmask_b32_e32 v96, v97, v99, vcc
	s_nop 1
	v_mov_b32_dpp v96, v96 quad_perm:[1,0,3,2] row_mask:0xf bank_mask:0xf bound_ctrl:1
	v_cndmask_b32_e32 v97, v96, v97, vcc
	v_cndmask_b32_e32 v96, v99, v96, vcc
	s_waitcnt vmcnt(31)
	v_fmac_f32_e32 v97, 0x3f9837f0, v204
	v_fmac_f32_e32 v96, 0x3f9837f0, v205
	v_cvt_pk_bf16_f32 v96, v97, v96
	v_lshrrev_b32_e32 v97, 1, v104
	global_store_dword v97, v96, s[92:93]
	v_add_u32_e32 v135, 0x100000, v128
	v_add_u32_e32 v136, v135, v129
	global_load_dwordx2 v[190:191], v136, s[76:77]
	v_add_u32_e32 v137, 0x102000, v128
	v_add_u32_e32 v138, v137, v129
	global_load_dwordx2 v[192:193], v138, s[76:77]
	v_add_u32_e32 v139, v135, v124
	global_load_dwordx2 v[194:195], v139, s[76:77]
	v_add_u32_e32 v170, v137, v124
	global_load_dwordx2 v[196:197], v170, s[76:77]
	v_add_u32_e32 v171, v135, v120
	global_load_dwordx2 v[198:199], v171, s[76:77]
	v_add_u32_e32 v172, v137, v120
	global_load_dwordx2 v[200:201], v172, s[76:77]
	v_add_u32_e32 v173, v135, v116
	global_load_dwordx2 v[202:203], v173, s[76:77]
	v_add_u32_e32 v174, v137, v116
	global_load_dwordx2 v[204:205], v174, s[76:77]
	v_or_b32_e32 v98, 0x40000, v128
	v_add_u32_e32 v99, v98, v129
	s_nop 0
	v_cndmask_b32_e32 v100, v92, v94, vcc
	v_or_b32_e32 v101, 0x42000, v128
	v_lshrrev_b32_e32 v99, 1, v99
	v_mov_b32_dpp v100, v100 quad_perm:[1,0,3,2] row_mask:0xf bank_mask:0xf bound_ctrl:1
	v_cndmask_b32_e32 v92, v100, v92, vcc
	v_cndmask_b32_e32 v94, v94, v100, vcc
	v_add_u32_e32 v102, v101, v129
	s_waitcnt vmcnt(39)
	v_fmac_f32_e32 v92, 0x3f9837f0, v214
	v_fmac_f32_e32 v94, 0x3f9837f0, v215
	v_cvt_pk_bf16_f32 v92, v92, v94
	global_store_dword v99, v92, s[92:93]
	s_nop 0
	v_cndmask_b32_e32 v92, v93, v95, vcc
	v_add_u32_e32 v94, v98, v124
	s_nop 0
	v_mov_b32_dpp v92, v92 quad_perm:[1,0,3,2] row_mask:0xf bank_mask:0xf bound_ctrl:1
	v_cndmask_b32_e32 v93, v92, v93, vcc
	v_cndmask_b32_e32 v92, v95, v92, vcc
	v_lshrrev_b32_e32 v95, 1, v102
	s_waitcnt vmcnt(39)
	v_fmac_f32_e32 v93, 0x3f9837f0, v216
	v_fmac_f32_e32 v92, 0x3f9837f0, v217
	v_cvt_pk_bf16_f32 v92, v93, v92
	global_store_dword v95, v92, s[92:93]
	s_nop 0
	v_cndmask_b32_e32 v95, v88, v90, vcc
	v_lshrrev_b32_e32 v94, 1, v94
	v_add_u32_e32 v96, v101, v124
	v_mov_b32_dpp v95, v95 quad_perm:[1,0,3,2] row_mask:0xf bank_mask:0xf bound_ctrl:1
	v_cndmask_b32_e32 v88, v95, v88, vcc
	v_cndmask_b32_e32 v90, v90, v95, vcc
	s_waitcnt vmcnt(39)
	v_fmac_f32_e32 v88, 0x3f9837f0, v218
	v_fmac_f32_e32 v90, 0x3f9837f0, v219
	v_cvt_pk_bf16_f32 v88, v88, v90
	global_store_dword v94, v88, s[92:93]
	s_nop 0
	v_cndmask_b32_e32 v88, v89, v91, vcc
	v_add_u32_e32 v90, v98, v120
	s_nop 0
	v_mov_b32_dpp v88, v88 quad_perm:[1,0,3,2] row_mask:0xf bank_mask:0xf bound_ctrl:1
	v_cndmask_b32_e32 v89, v88, v89, vcc
	v_cndmask_b32_e32 v88, v91, v88, vcc
	v_lshrrev_b32_e32 v91, 1, v96
	s_waitcnt vmcnt(39)
	v_fmac_f32_e32 v89, 0x3f9837f0, v220
	v_fmac_f32_e32 v88, 0x3f9837f0, v221
	v_cvt_pk_bf16_f32 v88, v89, v88
	global_store_dword v91, v88, s[92:93]
	s_nop 0
	v_cndmask_b32_e32 v91, v84, v86, vcc
	v_lshrrev_b32_e32 v90, 1, v90
	v_add_u32_e32 v92, v101, v120
	v_mov_b32_dpp v91, v91 quad_perm:[1,0,3,2] row_mask:0xf bank_mask:0xf bound_ctrl:1
	v_cndmask_b32_e32 v84, v91, v84, vcc
	v_cndmask_b32_e32 v86, v86, v91, vcc
	s_waitcnt vmcnt(39)
	v_fmac_f32_e32 v84, 0x3f9837f0, v222
	v_fmac_f32_e32 v86, 0x3f9837f0, v223
	v_cvt_pk_bf16_f32 v84, v84, v86
	global_store_dword v90, v84, s[92:93]
	s_nop 0
	v_cndmask_b32_e32 v84, v85, v87, vcc
	v_add_u32_e32 v86, v98, v116
	s_nop 0
	v_mov_b32_dpp v84, v84 quad_perm:[1,0,3,2] row_mask:0xf bank_mask:0xf bound_ctrl:1
	v_cndmask_b32_e32 v85, v84, v85, vcc
	v_cndmask_b32_e32 v84, v87, v84, vcc
	v_lshrrev_b32_e32 v87, 1, v92
	s_waitcnt vmcnt(39)
	v_fmac_f32_e32 v85, 0x3f9837f0, v224
	v_fmac_f32_e32 v84, 0x3f9837f0, v225
	v_cvt_pk_bf16_f32 v84, v85, v84
	global_store_dword v87, v84, s[92:93]
	s_nop 0
	v_cndmask_b32_e32 v87, v80, v82, vcc
	v_lshrrev_b32_e32 v86, 1, v86
	v_add_u32_e32 v88, v101, v116
	v_mov_b32_dpp v87, v87 quad_perm:[1,0,3,2] row_mask:0xf bank_mask:0xf bound_ctrl:1
	v_cndmask_b32_e32 v80, v87, v80, vcc
	v_cndmask_b32_e32 v82, v82, v87, vcc
	s_waitcnt vmcnt(39)
	v_fmac_f32_e32 v80, 0x3f9837f0, v226
	v_fmac_f32_e32 v82, 0x3f9837f0, v227
	v_cvt_pk_bf16_f32 v80, v80, v82
	global_store_dword v86, v80, s[92:93]
	s_nop 0
	v_cndmask_b32_e32 v80, v81, v83, vcc
	s_nop 1
	v_mov_b32_dpp v80, v80 quad_perm:[1,0,3,2] row_mask:0xf bank_mask:0xf bound_ctrl:1
	v_cndmask_b32_e32 v81, v80, v81, vcc
	v_cndmask_b32_e32 v80, v83, v80, vcc
	s_waitcnt vmcnt(39)
; DEVINL void xchg_pairs(f32x4 v, bool odd, float (&lo)[2], float (&hi)[2]) {
;   const float s0 = odd ? v[0] : v[2], s1 = odd ? v[1] : v[3];
;   const float r0 = dppf<0xB1>(s0), r1 = dppf<0xB1>(s1);
;   lo[0] = odd ? r0 : v[0]; hi[0] = odd ? v[2] : r0;
;   lo[1] = odd ? r1 : v[1]; hi[1] = odd ? v[3] : r1;
; }
; template <int EPI, bool GATHER>
; DEVINL void gemm_tile(const Params& p, const u16* __restrict__ A, int lda, const int* __restrict__ rowidx,
;                       const u16* __restrict__ Bt, int ldb, int K, int brow, int bcol, int orow, int ocol) {
;     ...
;             } else if (EPI == EPI_R1) {
;               const unsigned o4 = (row * 2048u + (unsigned)(colp + cc)) * 4u;
;               const float2 xv = *(const float2*)((const char*)p.x + o4);
;               *(unsigned*)(ws + O_R1 + (o4 >> 1)) = pk2(ALPHA * xv.x + lo[k], ALPHA * xv.y + hi[k]);
;             }
	v_fmac_f32_e32 v81, 0x3f9837f0, v228
	v_fmac_f32_e32 v80, 0x3f9837f0, v229
	v_cvt_pk_bf16_f32 v80, v81, v80
	v_lshrrev_b32_e32 v81, 1, v88
	global_store_dword v81, v80, s[92:93]
	v_add_u32_e32 v135, 0x120000, v128
	v_add_u32_e32 v136, v135, v129
	global_load_dwordx2 v[214:215], v136, s[76:77]
	v_add_u32_e32 v137, 0x122000, v128
	v_add_u32_e32 v138, v137, v129
	global_load_dwordx2 v[216:217], v138, s[76:77]
	v_add_u32_e32 v139, v135, v124
	global_load_dwordx2 v[218:219], v139, s[76:77]
	v_add_u32_e32 v170, v137, v124
	global_load_dwordx2 v[220:221], v170, s[76:77]
	v_add_u32_e32 v171, v135, v120
	global_load_dwordx2 v[222:223], v171, s[76:77]
	v_add_u32_e32 v172, v137, v120
	global_load_dwordx2 v[224:225], v172, s[76:77]
	v_add_u32_e32 v173, v135, v116
	global_load_dwordx2 v[226:227], v173, s[76:77]
	v_add_u32_e32 v174, v137, v116
	global_load_dwordx2 v[228:229], v174, s[76:77]
	v_or_b32_e32 v82, 0x60000, v128
	v_add_u32_e32 v83, v82, v129
	s_nop 0
	v_cndmask_b32_e32 v84, v76, v78, vcc
	v_or_b32_e32 v85, 0x62000, v128
	v_lshrrev_b32_e32 v83, 1, v83
	v_mov_b32_dpp v84, v84 quad_perm:[1,0,3,2] row_mask:0xf bank_mask:0xf bound_ctrl:1
	v_cndmask_b32_e32 v76, v84, v76, vcc
	v_cndmask_b32_e32 v78, v78, v84, vcc
	v_add_u32_e32 v86, v85, v129
	s_waitcnt vmcnt(39)
	v_fmac_f32_e32 v76, 0x3f9837f0, v146
	v_fmac_f32_e32 v78, 0x3f9837f0, v147
	v_cvt_pk_bf16_f32 v76, v76, v78
	global_store_dword v83, v76, s[92:93]
	s_nop 0
	v_cndmask_b32_e32 v76, v77, v79, vcc
	v_add_u32_e32 v78, v82, v124
	s_nop 0
	v_mov_b32_dpp v76, v76 quad_perm:[1,0,3,2] row_mask:0xf bank_mask:0xf bound_ctrl:1
	v_cndmask_b32_e32 v77, v76, v77, vcc
	v_cndmask_b32_e32 v76, v79, v76, vcc
	v_lshrrev_b32_e32 v79, 1, v86
	s_waitcnt vmcnt(39)
	v_fmac_f32_e32 v77, 0x3f9837f0, v148
	v_fmac_f32_e32 v76, 0x3f9837f0, v149
	v_cvt_pk_bf16_f32 v76, v77, v76
	global_store_dword v79, v76, s[92:93]
	s_nop 0
	v_cndmask_b32_e32 v79, v72, v74, vcc
	v_lshrrev_b32_e32 v78, 1, v78
	v_add_u32_e32 v80, v85, v124
	v_mov_b32_dpp v79, v79 quad_perm:[1,0,3,2] row_mask:0xf bank_mask:0xf bound_ctrl:1
	v_cndmask_b32_e32 v72, v79, v72, vcc
	v_cndmask_b32_e32 v74, v74, v79, vcc
	s_waitcnt vmcnt(39)
	v_fmac_f32_e32 v72, 0x3f9837f0, v150
	v_fmac_f32_e32 v74, 0x3f9837f0, v151
	v_cvt_pk_bf16_f32 v72, v72, v74
	global_store_dword v78, v72, s[92:93]
	s_nop 0
	v_cndmask_b32_e32 v72, v73, v75, vcc
	v_add_u32_e32 v74, v82, v120
	s_nop 0
	v_mov_b32_dpp v72, v72 quad_perm:[1,0,3,2] row_mask:0xf bank_mask:0xf bound_ctrl:1
	v_cndmask_b32_e32 v73, v72, v73, vcc
	v_cndmask_b32_e32 v72, v75, v72, vcc
	v_lshrrev_b32_e32 v75, 1, v80
	s_waitcnt vmcnt(39)
	v_fmac_f32_e32 v73, 0x3f9837f0, v152
	v_fmac_f32_e32 v72, 0x3f9837f0, v153
	v_cvt_pk_bf16_f32 v72, v73, v72
	global_store_dword v75, v72, s[92:93]
	s_nop 0
	v_cndmask_b32_e32 v75, v68, v70, vcc
	v_lshrrev_b32_e32 v74, 1, v74
	v_add_u32_e32 v76, v85, v120
	v_mov_b32_dpp v75, v75 quad_perm:[1,0,3,2] row_mask:0xf bank_mask:0xf bound_ctrl:1
	v_cndmask_b32_e32 v68, v75, v68, vcc
	v_cndmask_b32_e32 v70, v70, v75, vcc
	s_waitcnt vmcnt(39)
	v_fmac_f32_e32 v68, 0x3f9837f0, v154
	v_fmac_f32_e32 v70, 0x3f9837f0, v155
	v_cvt_pk_bf16_f32 v68, v68, v70
	global_store_dword v74, v68, s[92:93]
	s_nop 0
	v_cndmask_b32_e32 v68, v69, v71, vcc
	v_add_u32_e32 v70, v82, v116
	s_nop 0
	v_mov_b32_dpp v68, v68 quad_perm:[1,0,3,2] row_mask:0xf bank_mask:0xf bound_ctrl:1
	v_cndmask_b32_e32 v69, v68, v69, vcc
	v_cndmask_b32_e32 v68, v71, v68, vcc
	v_lshrrev_b32_e32 v71, 1, v76
	s_waitcnt vmcnt(39)
	v_fmac_f32_e32 v69, 0x3f9837f0, v156
	v_fmac_f32_e32 v68, 0x3f9837f0, v157
	v_cvt_pk_bf16_f32 v68, v69, v68
	global_store_dword v71, v68, s[92:93]
	s_nop 0
	v_cndmask_b32_e32 v71, v64, v66, vcc
	v_lshrrev_b32_e32 v70, 1, v70
	v_add_u32_e32 v72, v85, v116
	v_mov_b32_dpp v71, v71 quad_perm:[1,0,3,2] row_mask:0xf bank_mask:0xf bound_ctrl:1
	v_cndmask_b32_e32 v64, v71, v64, vcc
	v_cndmask_b32_e32 v66, v66, v71, vcc
	s_waitcnt vmcnt(39)
	v_fmac_f32_e32 v64, 0x3f9837f0, v158
	v_fmac_f32_e32 v66, 0x3f9837f0, v159
	v_cvt_pk_bf16_f32 v64, v64, v66
	global_store_dword v70, v64, s[92:93]
	s_nop 0
	v_cndmask_b32_e32 v64, v65, v67, vcc
	s_nop 1
	v_mov_b32_dpp v64, v64 quad_perm:[1,0,3,2] row_mask:0xf bank_mask:0xf bound_ctrl:1
	v_cndmask_b32_e32 v65, v64, v65, vcc
	v_cndmask_b32_e32 v64, v67, v64, vcc
	s_waitcnt vmcnt(39)
	v_fmac_f32_e32 v65, 0x3f9837f0, v160
	v_fmac_f32_e32 v64, 0x3f9837f0, v161
	v_cvt_pk_bf16_f32 v64, v65, v64
	v_lshrrev_b32_e32 v65, 1, v72
	global_store_dword v65, v64, s[92:93]
	v_add_u32_e32 v135, 0x140000, v128
	v_add_u32_e32 v136, v135, v129
	global_load_dwordx2 v[146:147], v136, s[76:77]
	v_add_u32_e32 v137, 0x142000, v128
	v_add_u32_e32 v138, v137, v129
	global_load_dwordx2 v[148:149], v138, s[76:77]
	v_add_u32_e32 v139, v135, v124
	global_load_dwordx2 v[150:151], v139, s[76:77]
	v_add_u32_e32 v170, v137, v124
	global_load_dwordx2 v[152:153], v170, s[76:77]
	v_add_u32_e32 v171, v135, v120
	global_load_dwordx2 v[154:155], v171, s[76:77]
	v_add_u32_e32 v172, v137, v120
	global_load_dwordx2 v[156:157], v172, s[76:77]
	v_add_u32_e32 v173, v135, v116
	global_load_dwordx2 v[158:159], v173, s[76:77]
	v_add_u32_e32 v174, v137, v116
	global_load_dwordx2 v[160:161], v174, s[76:77]
	v_add_u32_e32 v66, 0x100000, v128
	v_add_u32_e32 v67, v66, v129
	s_nop 0
	v_cndmask_b32_e32 v68, v60, v62, vcc
	v_add_u32_e32 v69, 0x102000, v128
	v_lshrrev_b32_e32 v67, 1, v67
	v_mov_b32_dpp v68, v68 quad_perm:[1,0,3,2] row_mask:0xf bank_mask:0xf bound_ctrl:1
	v_cndmask_b32_e32 v60, v68, v60, vcc
	v_cndmask_b32_e32 v62, v62, v68, vcc
	v_add_u32_e32 v70, v69, v129
	s_waitcnt vmcnt(39)
; DEVINL void xchg_pairs(f32x4 v, bool odd, float (&lo)[2], float (&hi)[2]) {
;   const float s0 = odd ? v[0] : v[2], s1 = odd ? v[1] : v[3];
;   const float r0 = dppf<0xB1>(s0), r1 = dppf<0xB1>(s1);
;   lo[0] = odd ? r0 : v[0]; hi[0] = odd ? v[2] : r0;
;   lo[1] = odd ? r1 : v[1]; hi[1] = odd ? v[3] : r1;
; }
; template <int EPI, bool GATHER>
; DEVINL void gemm_tile(const Params& p, const u16* __restrict__ A, int lda, const int* __restrict__ rowidx,
;                       const u16* __restrict__ Bt, int ldb, int K, int brow, int bcol, int orow, int ocol) {
;     ...
;             } else if (EPI == EPI_R1) {
;               const unsigned o4 = (row * 2048u + (unsigned)(colp + cc)) * 4u;
;               const float2 xv = *(const float2*)((const char*)p.x + o4);
;               *(unsigned*)(ws + O_R1 + (o4 >> 1)) = pk2(ALPHA * xv.x + lo[k], ALPHA * xv.y + hi[k]);
;             }
	v_fmac_f32_e32 v60, 0x3f9837f0, v190
	v_fmac_f32_e32 v62, 0x3f9837f0, v191
	v_cvt_pk_bf16_f32 v60, v60, v62
	global_store_dword v67, v60, s[92:93]
	s_nop 0
	v_cndmask_b32_e32 v60, v61, v63, vcc
	v_add_u32_e32 v62, v66, v124
	s_nop 0
	v_mov_b32_dpp v60, v60 quad_perm:[1,0,3,2] row_mask:0xf bank_mask:0xf bound_ctrl:1
	v_cndmask_b32_e32 v61, v60, v61, vcc
	v_cndmask_b32_e32 v60, v63, v60, vcc
	v_lshrrev_b32_e32 v63, 1, v70
	s_waitcnt vmcnt(39)
	v_fmac_f32_e32 v61, 0x3f9837f0, v192
	v_fmac_f32_e32 v60, 0x3f9837f0, v193
	v_cvt_pk_bf16_f32 v60, v61, v60
	global_store_dword v63, v60, s[92:93]
	s_nop 0
	v_cndmask_b32_e32 v63, v56, v58, vcc
	v_lshrrev_b32_e32 v62, 1, v62
	v_add_u32_e32 v64, v69, v124
	v_mov_b32_dpp v63, v63 quad_perm:[1,0,3,2] row_mask:0xf bank_mask:0xf bound_ctrl:1
	v_cndmask_b32_e32 v56, v63, v56, vcc
	v_cndmask_b32_e32 v58, v58, v63, vcc
	s_waitcnt vmcnt(39)
	v_fmac_f32_e32 v56, 0x3f9837f0, v194
	v_fmac_f32_e32 v58, 0x3f9837f0, v195
	v_cvt_pk_bf16_f32 v56, v56, v58
	global_store_dword v62, v56, s[92:93]
	s_nop 0
	v_cndmask_b32_e32 v56, v57, v59, vcc
	v_add_u32_e32 v58, v66, v120
	s_nop 0
	v_mov_b32_dpp v56, v56 quad_perm:[1,0,3,2] row_mask:0xf bank_mask:0xf bound_ctrl:1
	v_cndmask_b32_e32 v57, v56, v57, vcc
	v_cndmask_b32_e32 v56, v59, v56, vcc
	v_lshrrev_b32_e32 v59, 1, v64
	s_waitcnt vmcnt(39)
	v_fmac_f32_e32 v57, 0x3f9837f0, v196
	v_fmac_f32_e32 v56, 0x3f9837f0, v197
	v_cvt_pk_bf16_f32 v56, v57, v56
	global_store_dword v59, v56, s[92:93]
	s_nop 0
	v_cndmask_b32_e32 v59, v52, v54, vcc
	v_lshrrev_b32_e32 v58, 1, v58
	v_add_u32_e32 v60, v69, v120
	v_mov_b32_dpp v59, v59 quad_perm:[1,0,3,2] row_mask:0xf bank_mask:0xf bound_ctrl:1
	v_cndmask_b32_e32 v52, v59, v52, vcc
	v_cndmask_b32_e32 v54, v54, v59, vcc
	s_waitcnt vmcnt(39)
	v_fmac_f32_e32 v52, 0x3f9837f0, v198
	v_fmac_f32_e32 v54, 0x3f9837f0, v199
	v_cvt_pk_bf16_f32 v52, v52, v54
	global_store_dword v58, v52, s[92:93]
	s_nop 0
	v_cndmask_b32_e32 v52, v53, v55, vcc
	v_add_u32_e32 v54, v66, v116
	s_nop 0
	v_mov_b32_dpp v52, v52 quad_perm:[1,0,3,2] row_mask:0xf bank_mask:0xf bound_ctrl:1
	v_cndmask_b32_e32 v53, v52, v53, vcc
	v_cndmask_b32_e32 v52, v55, v52, vcc
	v_lshrrev_b32_e32 v55, 1, v60
	s_waitcnt vmcnt(39)
	v_fmac_f32_e32 v53, 0x3f9837f0, v200
	v_fmac_f32_e32 v52, 0x3f9837f0, v201
	v_cvt_pk_bf16_f32 v52, v53, v52
	global_store_dword v55, v52, s[92:93]
	s_nop 0
	v_cndmask_b32_e32 v55, v48, v50, vcc
	v_lshrrev_b32_e32 v54, 1, v54
	v_add_u32_e32 v56, v69, v116
	v_mov_b32_dpp v55, v55 quad_perm:[1,0,3,2] row_mask:0xf bank_mask:0xf bound_ctrl:1
	v_cndmask_b32_e32 v48, v55, v48, vcc
	v_cndmask_b32_e32 v50, v50, v55, vcc
	s_waitcnt vmcnt(39)
	v_fmac_f32_e32 v48, 0x3f9837f0, v202
	v_fmac_f32_e32 v50, 0x3f9837f0, v203
	v_cvt_pk_bf16_f32 v48, v48, v50
	global_store_dword v54, v48, s[92:93]
	s_nop 0
	v_cndmask_b32_e32 v48, v49, v51, vcc
	s_nop 1
	v_mov_b32_dpp v48, v48 quad_perm:[1,0,3,2] row_mask:0xf bank_mask:0xf bound_ctrl:1
	v_cndmask_b32_e32 v49, v48, v49, vcc
	v_cndmask_b32_e32 v48, v51, v48, vcc
	s_waitcnt vmcnt(39)
	v_fmac_f32_e32 v49, 0x3f9837f0, v204
	v_fmac_f32_e32 v48, 0x3f9837f0, v205
	v_cvt_pk_bf16_f32 v48, v49, v48
	v_lshrrev_b32_e32 v49, 1, v56
	global_store_dword v49, v48, s[92:93]
	v_add_u32_e32 v135, 0x160000, v128
	v_add_u32_e32 v136, v135, v129
	global_load_dwordx2 v[190:191], v136, s[76:77]
	v_add_u32_e32 v137, 0x162000, v128
	v_add_u32_e32 v138, v137, v129
	global_load_dwordx2 v[192:193], v138, s[76:77]
	v_add_u32_e32 v139, v135, v124
	global_load_dwordx2 v[194:195], v139, s[76:77]
	v_add_u32_e32 v170, v137, v124
	global_load_dwordx2 v[196:197], v170, s[76:77]
	v_add_u32_e32 v171, v135, v120
	global_load_dwordx2 v[198:199], v171, s[76:77]
	v_add_u32_e32 v172, v137, v120
	global_load_dwordx2 v[200:201], v172, s[76:77]
	v_add_u32_e32 v173, v135, v116
	global_load_dwordx2 v[202:203], v173, s[76:77]
	v_add_u32_e32 v174, v137, v116
	global_load_dwordx2 v[204:205], v174, s[76:77]
	v_add_u32_e32 v50, 0x120000, v128
	v_add_u32_e32 v51, v50, v129
	s_nop 0
	v_cndmask_b32_e32 v52, v44, v46, vcc
	v_add_u32_e32 v53, 0x122000, v128
	v_lshrrev_b32_e32 v51, 1, v51
	v_mov_b32_dpp v52, v52 quad_perm:[1,0,3,2] row_mask:0xf bank_mask:0xf bound_ctrl:1
	v_cndmask_b32_e32 v44, v52, v44, vcc
	v_cndmask_b32_e32 v46, v46, v52, vcc
	v_add_u32_e32 v54, v53, v129
	s_waitcnt vmcnt(39)
	v_fmac_f32_e32 v44, 0x3f9837f0, v214
	v_fmac_f32_e32 v46, 0x3f9837f0, v215
	v_cvt_pk_bf16_f32 v44, v44, v46
	global_store_dword v51, v44, s[92:93]
	s_nop 0
	v_cndmask_b32_e32 v44, v45, v47, vcc
	v_add_u32_e32 v46, v50, v124
	s_nop 0
	v_mov_b32_dpp v44, v44 quad_perm:[1,0,3,2] row_mask:0xf bank_mask:0xf bound_ctrl:1
	v_cndmask_b32_e32 v45, v44, v45, vcc
	v_cndmask_b32_e32 v44, v47, v44, vcc
	v_lshrrev_b32_e32 v47, 1, v54
	s_waitcnt vmcnt(39)
	v_fmac_f32_e32 v45, 0x3f9837f0, v216
	v_fmac_f32_e32 v44, 0x3f9837f0, v217
	v_cvt_pk_bf16_f32 v44, v45, v44
	global_store_dword v47, v44, s[92:93]
	s_nop 0
	v_cndmask_b32_e32 v47, v40, v42, vcc
	v_lshrrev_b32_e32 v46, 1, v46
	v_add_u32_e32 v48, v53, v124
	v_mov_b32_dpp v47, v47 quad_perm:[1,0,3,2] row_mask:0xf bank_mask:0xf bound_ctrl:1
	v_cndmask_b32_e32 v40, v47, v40, vcc
	v_cndmask_b32_e32 v42, v42, v47, vcc
	s_waitcnt vmcnt(39)
	v_fmac_f32_e32 v40, 0x3f9837f0, v218
	v_fmac_f32_e32 v42, 0x3f9837f0, v219
	v_cvt_pk_bf16_f32 v40, v40, v42
	global_store_dword v46, v40, s[92:93]
	s_nop 0
	v_cndmask_b32_e32 v40, v41, v43, vcc
	v_add_u32_e32 v42, v50, v120
	s_nop 0
	v_mov_b32_dpp v40, v40 quad_perm:[1,0,3,2] row_mask:0xf bank_mask:0xf bound_ctrl:1
	v_cndmask_b32_e32 v41, v40, v41, vcc
	v_cndmask_b32_e32 v40, v43, v40, vcc
	v_lshrrev_b32_e32 v43, 1, v48
	s_waitcnt vmcnt(39)
; DEVINL void xchg_pairs(f32x4 v, bool odd, float (&lo)[2], float (&hi)[2]) {
;   const float s0 = odd ? v[0] : v[2], s1 = odd ? v[1] : v[3];
;   const float r0 = dppf<0xB1>(s0), r1 = dppf<0xB1>(s1);
;   lo[0] = odd ? r0 : v[0]; hi[0] = odd ? v[2] : r0;
;   lo[1] = odd ? r1 : v[1]; hi[1] = odd ? v[3] : r1;
; }
; template <int EPI, bool GATHER>
; DEVINL void gemm_tile(const Params& p, const u16* __restrict__ A, int lda, const int* __restrict__ rowidx,
;                       const u16* __restrict__ Bt, int ldb, int K, int brow, int bcol, int orow, int ocol) {
;     ...
;             } else if (EPI == EPI_R1) {
;               const unsigned o4 = (row * 2048u + (unsigned)(colp + cc)) * 4u;
;               const float2 xv = *(const float2*)((const char*)p.x + o4);
;               *(unsigned*)(ws + O_R1 + (o4 >> 1)) = pk2(ALPHA * xv.x + lo[k], ALPHA * xv.y + hi[k]);
;             }
	v_fmac_f32_e32 v41, 0x3f9837f0, v220
	v_fmac_f32_e32 v40, 0x3f9837f0, v221
	v_cvt_pk_bf16_f32 v40, v41, v40
	global_store_dword v43, v40, s[92:93]
	s_nop 0
	v_cndmask_b32_e32 v43, v36, v38, vcc
	v_lshrrev_b32_e32 v42, 1, v42
	v_add_u32_e32 v44, v53, v120
	v_mov_b32_dpp v43, v43 quad_perm:[1,0,3,2] row_mask:0xf bank_mask:0xf bound_ctrl:1
	v_cndmask_b32_e32 v36, v43, v36, vcc
	v_cndmask_b32_e32 v38, v38, v43, vcc
	s_waitcnt vmcnt(39)
	v_fmac_f32_e32 v36, 0x3f9837f0, v222
	v_fmac_f32_e32 v38, 0x3f9837f0, v223
	v_cvt_pk_bf16_f32 v36, v36, v38
	global_store_dword v42, v36, s[92:93]
	s_nop 0
	v_cndmask_b32_e32 v36, v37, v39, vcc
	v_add_u32_e32 v38, v50, v116
	s_nop 0
	v_mov_b32_dpp v36, v36 quad_perm:[1,0,3,2] row_mask:0xf bank_mask:0xf bound_ctrl:1
	v_cndmask_b32_e32 v37, v36, v37, vcc
	v_cndmask_b32_e32 v36, v39, v36, vcc
	v_lshrrev_b32_e32 v39, 1, v44
	s_waitcnt vmcnt(39)
	v_fmac_f32_e32 v37, 0x3f9837f0, v224
	v_fmac_f32_e32 v36, 0x3f9837f0, v225
	v_cvt_pk_bf16_f32 v36, v37, v36
	global_store_dword v39, v36, s[92:93]
	s_nop 0
	v_cndmask_b32_e32 v39, v32, v34, vcc
	v_lshrrev_b32_e32 v38, 1, v38
	v_add_u32_e32 v40, v53, v116
	v_mov_b32_dpp v39, v39 quad_perm:[1,0,3,2] row_mask:0xf bank_mask:0xf bound_ctrl:1
	v_cndmask_b32_e32 v32, v39, v32, vcc
	v_cndmask_b32_e32 v34, v34, v39, vcc
	s_waitcnt vmcnt(39)
	v_fmac_f32_e32 v32, 0x3f9837f0, v226
	v_fmac_f32_e32 v34, 0x3f9837f0, v227
	v_cvt_pk_bf16_f32 v32, v32, v34
	global_store_dword v38, v32, s[92:93]
	s_nop 0
	v_cndmask_b32_e32 v32, v33, v35, vcc
	s_nop 1
	v_mov_b32_dpp v32, v32 quad_perm:[1,0,3,2] row_mask:0xf bank_mask:0xf bound_ctrl:1
	v_cndmask_b32_e32 v33, v32, v33, vcc
	v_cndmask_b32_e32 v32, v35, v32, vcc
	s_waitcnt vmcnt(39)
	v_fmac_f32_e32 v33, 0x3f9837f0, v228
	v_fmac_f32_e32 v32, 0x3f9837f0, v229
	v_cvt_pk_bf16_f32 v32, v33, v32
	v_lshrrev_b32_e32 v33, 1, v40
	global_store_dword v33, v32, s[92:93]
	v_add_u32_e32 v34, 0x140000, v128
	v_add_u32_e32 v35, v34, v129
	s_nop 0
	v_cndmask_b32_e32 v36, v28, v30, vcc
	v_add_u32_e32 v37, 0x142000, v128
	v_lshrrev_b32_e32 v35, 1, v35
	v_mov_b32_dpp v36, v36 quad_perm:[1,0,3,2] row_mask:0xf bank_mask:0xf bound_ctrl:1
	v_cndmask_b32_e32 v28, v36, v28, vcc
	v_cndmask_b32_e32 v30, v30, v36, vcc
	v_add_u32_e32 v38, v37, v129
	s_waitcnt vmcnt(31)
	v_fmac_f32_e32 v28, 0x3f9837f0, v146
	v_fmac_f32_e32 v30, 0x3f9837f0, v147
	v_cvt_pk_bf16_f32 v28, v28, v30
	global_store_dword v35, v28, s[92:93]
	s_nop 0
	v_cndmask_b32_e32 v28, v29, v31, vcc
	v_add_u32_e32 v30, v34, v124
	s_nop 0
	v_mov_b32_dpp v28, v28 quad_perm:[1,0,3,2] row_mask:0xf bank_mask:0xf bound_ctrl:1
	v_cndmask_b32_e32 v29, v28, v29, vcc
	v_cndmask_b32_e32 v28, v31, v28, vcc
	v_lshrrev_b32_e32 v31, 1, v38
	s_waitcnt vmcnt(31)
	v_fmac_f32_e32 v29, 0x3f9837f0, v148
	v_fmac_f32_e32 v28, 0x3f9837f0, v149
	v_cvt_pk_bf16_f32 v28, v29, v28
	global_store_dword v31, v28, s[92:93]
	s_nop 0
	v_cndmask_b32_e32 v31, v24, v26, vcc
	v_lshrrev_b32_e32 v30, 1, v30
	v_add_u32_e32 v32, v37, v124
	v_mov_b32_dpp v31, v31 quad_perm:[1,0,3,2] row_mask:0xf bank_mask:0xf bound_ctrl:1
	v_cndmask_b32_e32 v24, v31, v24, vcc
	v_cndmask_b32_e32 v26, v26, v31, vcc
	s_waitcnt vmcnt(31)
	v_fmac_f32_e32 v24, 0x3f9837f0, v150
	v_fmac_f32_e32 v26, 0x3f9837f0, v151
	v_cvt_pk_bf16_f32 v24, v24, v26
	global_store_dword v30, v24, s[92:93]
	s_nop 0
	v_cndmask_b32_e32 v24, v25, v27, vcc
	v_add_u32_e32 v26, v34, v120
	s_nop 0
	v_mov_b32_dpp v24, v24 quad_perm:[1,0,3,2] row_mask:0xf bank_mask:0xf bound_ctrl:1
	v_cndmask_b32_e32 v25, v24, v25, vcc
	v_cndmask_b32_e32 v24, v27, v24, vcc
	v_lshrrev_b32_e32 v27, 1, v32
	s_waitcnt vmcnt(31)
	v_fmac_f32_e32 v25, 0x3f9837f0, v152
	v_fmac_f32_e32 v24, 0x3f9837f0, v153
	v_cvt_pk_bf16_f32 v24, v25, v24
	global_store_dword v27, v24, s[92:93]
	s_nop 0
	v_cndmask_b32_e32 v27, v20, v22, vcc
	v_lshrrev_b32_e32 v26, 1, v26
	v_add_u32_e32 v28, v37, v120
	v_mov_b32_dpp v27, v27 quad_perm:[1,0,3,2] row_mask:0xf bank_mask:0xf bound_ctrl:1
	v_cndmask_b32_e32 v20, v27, v20, vcc
	v_cndmask_b32_e32 v22, v22, v27, vcc
	s_waitcnt vmcnt(31)
	v_fmac_f32_e32 v20, 0x3f9837f0, v154
	v_fmac_f32_e32 v22, 0x3f9837f0, v155
	v_cvt_pk_bf16_f32 v20, v20, v22
	global_store_dword v26, v20, s[92:93]
	s_nop 0
	v_cndmask_b32_e32 v20, v21, v23, vcc
	v_add_u32_e32 v22, v34, v116
	s_nop 0
	v_mov_b32_dpp v20, v20 quad_perm:[1,0,3,2] row_mask:0xf bank_mask:0xf bound_ctrl:1
	v_cndmask_b32_e32 v21, v20, v21, vcc
	v_cndmask_b32_e32 v20, v23, v20, vcc
	v_lshrrev_b32_e32 v23, 1, v28
	s_waitcnt vmcnt(31)
; DEVINL void xchg_pairs(f32x4 v, bool odd, float (&lo)[2], float (&hi)[2]) {
;   const float s0 = odd ? v[0] : v[2], s1 = odd ? v[1] : v[3];
;   const float r0 = dppf<0xB1>(s0), r1 = dppf<0xB1>(s1);
;   lo[0] = odd ? r0 : v[0]; hi[0] = odd ? v[2] : r0;
;   lo[1] = odd ? r1 : v[1]; hi[1] = odd ? v[3] : r1;
; }
; template <int EPI, bool GATHER>
; DEVINL void gemm_tile(const Params& p, const u16* __restrict__ A, int lda, const int* __restrict__ rowidx,
;                       const u16* __restrict__ Bt, int ldb, int K, int brow, int bcol, int orow, int ocol) {
;     ...
;             } else if (EPI == EPI_R1) {
;               const unsigned o4 = (row * 2048u + (unsigned)(colp + cc)) * 4u;
;               const float2 xv = *(const float2*)((const char*)p.x + o4);
;               *(unsigned*)(ws + O_R1 + (o4 >> 1)) = pk2(ALPHA * xv.x + lo[k], ALPHA * xv.y + hi[k]);
;             }
;     ...
;       __builtin_amdgcn_sched_barrier(0);
;     }
;   __syncthreads();
	v_fmac_f32_e32 v21, 0x3f9837f0, v156
	v_fmac_f32_e32 v20, 0x3f9837f0, v157
	v_cvt_pk_bf16_f32 v20, v21, v20
	global_store_dword v23, v20, s[92:93]
	s_nop 0
	v_cndmask_b32_e32 v23, v16, v18, vcc
	v_lshrrev_b32_e32 v22, 1, v22
	v_add_u32_e32 v24, v37, v116
	v_mov_b32_dpp v23, v23 quad_perm:[1,0,3,2] row_mask:0xf bank_mask:0xf bound_ctrl:1
	v_cndmask_b32_e32 v16, v23, v16, vcc
	v_cndmask_b32_e32 v18, v18, v23, vcc
	s_waitcnt vmcnt(31)
	v_fmac_f32_e32 v16, 0x3f9837f0, v158
	v_fmac_f32_e32 v18, 0x3f9837f0, v159
	v_cvt_pk_bf16_f32 v16, v16, v18
	global_store_dword v22, v16, s[92:93]
	s_nop 0
	v_cndmask_b32_e32 v16, v17, v19, vcc
	s_nop 1
	v_mov_b32_dpp v16, v16 quad_perm:[1,0,3,2] row_mask:0xf bank_mask:0xf bound_ctrl:1
	v_cndmask_b32_e32 v17, v16, v17, vcc
	v_cndmask_b32_e32 v16, v19, v16, vcc
	s_waitcnt vmcnt(31)
	v_fmac_f32_e32 v17, 0x3f9837f0, v160
	v_fmac_f32_e32 v16, 0x3f9837f0, v161
	v_cvt_pk_bf16_f32 v16, v17, v16
	v_lshrrev_b32_e32 v17, 1, v24
	global_store_dword v17, v16, s[92:93]
	v_add_u32_e32 v18, 0x160000, v128
	v_add_u32_e32 v19, v18, v129
	s_nop 0
	v_cndmask_b32_e32 v20, v12, v14, vcc
	v_add_u32_e32 v21, 0x162000, v128
	v_lshrrev_b32_e32 v19, 1, v19
	v_mov_b32_dpp v20, v20 quad_perm:[1,0,3,2] row_mask:0xf bank_mask:0xf bound_ctrl:1
	v_cndmask_b32_e32 v12, v20, v12, vcc
	v_cndmask_b32_e32 v14, v14, v20, vcc
	v_add_u32_e32 v22, v21, v129
	s_waitcnt vmcnt(23)
	v_fmac_f32_e32 v12, 0x3f9837f0, v190
	v_fmac_f32_e32 v14, 0x3f9837f0, v191
	v_cvt_pk_bf16_f32 v12, v12, v14
	global_store_dword v19, v12, s[92:93]
	s_nop 0
	v_cndmask_b32_e32 v12, v13, v15, vcc
	v_add_u32_e32 v14, v18, v124
	s_nop 0
	v_mov_b32_dpp v12, v12 quad_perm:[1,0,3,2] row_mask:0xf bank_mask:0xf bound_ctrl:1
	v_cndmask_b32_e32 v13, v12, v13, vcc
	v_cndmask_b32_e32 v12, v15, v12, vcc
	v_lshrrev_b32_e32 v15, 1, v22
	s_waitcnt vmcnt(23)
	v_fmac_f32_e32 v13, 0x3f9837f0, v192
	v_fmac_f32_e32 v12, 0x3f9837f0, v193
	v_cvt_pk_bf16_f32 v12, v13, v12
	global_store_dword v15, v12, s[92:93]
	s_nop 0
	v_cndmask_b32_e32 v15, v8, v10, vcc
	v_lshrrev_b32_e32 v14, 1, v14
	v_add_u32_e32 v16, v21, v124
	v_mov_b32_dpp v15, v15 quad_perm:[1,0,3,2] row_mask:0xf bank_mask:0xf bound_ctrl:1
	v_cndmask_b32_e32 v8, v15, v8, vcc
	v_cndmask_b32_e32 v10, v10, v15, vcc
	s_waitcnt vmcnt(23)
	v_fmac_f32_e32 v8, 0x3f9837f0, v194
	v_fmac_f32_e32 v10, 0x3f9837f0, v195
	v_cvt_pk_bf16_f32 v8, v8, v10
	global_store_dword v14, v8, s[92:93]
	s_nop 0
	v_cndmask_b32_e32 v8, v9, v11, vcc
	v_add_u32_e32 v10, v18, v120
	s_nop 0
	v_mov_b32_dpp v8, v8 quad_perm:[1,0,3,2] row_mask:0xf bank_mask:0xf bound_ctrl:1
	v_cndmask_b32_e32 v9, v8, v9, vcc
	v_cndmask_b32_e32 v8, v11, v8, vcc
	v_lshrrev_b32_e32 v11, 1, v16
	s_waitcnt vmcnt(23)
	v_fmac_f32_e32 v9, 0x3f9837f0, v196
	v_fmac_f32_e32 v8, 0x3f9837f0, v197
	v_cvt_pk_bf16_f32 v8, v9, v8
	global_store_dword v11, v8, s[92:93]
	s_nop 0
	v_cndmask_b32_e32 v11, v4, v6, vcc
	v_lshrrev_b32_e32 v10, 1, v10
	v_add_u32_e32 v12, v21, v120
	v_mov_b32_dpp v11, v11 quad_perm:[1,0,3,2] row_mask:0xf bank_mask:0xf bound_ctrl:1
	v_cndmask_b32_e32 v4, v11, v4, vcc
	v_cndmask_b32_e32 v6, v6, v11, vcc
	s_waitcnt vmcnt(23)
	v_fmac_f32_e32 v4, 0x3f9837f0, v198
	v_fmac_f32_e32 v6, 0x3f9837f0, v199
	v_cvt_pk_bf16_f32 v4, v4, v6
	global_store_dword v10, v4, s[92:93]
	s_nop 0
	v_cndmask_b32_e32 v4, v5, v7, vcc
	v_add_u32_e32 v6, v18, v116
	s_nop 0
	v_mov_b32_dpp v4, v4 quad_perm:[1,0,3,2] row_mask:0xf bank_mask:0xf bound_ctrl:1
	v_cndmask_b32_e32 v5, v4, v5, vcc
	v_cndmask_b32_e32 v4, v7, v4, vcc
	v_lshrrev_b32_e32 v7, 1, v12
	s_waitcnt vmcnt(23)
	v_fmac_f32_e32 v5, 0x3f9837f0, v200
	v_fmac_f32_e32 v4, 0x3f9837f0, v201
	v_cvt_pk_bf16_f32 v4, v5, v4
	global_store_dword v7, v4, s[92:93]
	s_nop 0
	v_cndmask_b32_e32 v7, v0, v2, vcc
	v_lshrrev_b32_e32 v6, 1, v6
	v_add_u32_e32 v8, v21, v116
	v_mov_b32_dpp v7, v7 quad_perm:[1,0,3,2] row_mask:0xf bank_mask:0xf bound_ctrl:1
	v_cndmask_b32_e32 v0, v7, v0, vcc
	v_cndmask_b32_e32 v2, v2, v7, vcc
	s_waitcnt vmcnt(23)
	v_fmac_f32_e32 v0, 0x3f9837f0, v202
	v_fmac_f32_e32 v2, 0x3f9837f0, v203
	v_cvt_pk_bf16_f32 v0, v0, v2
	global_store_dword v6, v0, s[92:93]
	s_nop 0
	v_cndmask_b32_e32 v0, v1, v3, vcc
	s_nop 1
	v_mov_b32_dpp v0, v0 quad_perm:[1,0,3,2] row_mask:0xf bank_mask:0xf bound_ctrl:1
	v_cndmask_b32_e32 v1, v0, v1, vcc
	v_cndmask_b32_e32 v0, v3, v0, vcc
	s_waitcnt vmcnt(23)
	v_fmac_f32_e32 v1, 0x3f9837f0, v204
	v_fmac_f32_e32 v0, 0x3f9837f0, v205
	v_cvt_pk_bf16_f32 v0, v1, v0
	v_lshrrev_b32_e32 v1, 1, v8
	global_store_dword v1, v0, s[92:93]
	s_add_i32 s42, s42, s94
	s_add_i32 s31, s31, s34
	s_add_i32 s41, s41, s60
	s_cmpk_lt_i32 s42, 0x100
	s_barrier
	s_cbranch_scc0 .LBB0_685
